# A-phase (in-proj) GEMM gets the same treatment as E: K-loop unrolled x8, C=0 start, SGPR-base LDS-DMA addressing, half of each tile's stores deferred into next tile's K-loop
# speedup vs baseline: 1.0249x; 1.0101x over previous
; template <class Epi>
; __device__ __forceinline__ void gemm_phase(LAS unsigned char* lds, const Gemm g, const StaticOrder& S, const Epi& E) {
;     ...
;         const bool has_next = S.next(ui + 1, nxt);
;         const char* nA = has_next ? (const char*)g.A + (size_t)nxt.pm * tstep : cA; const char* nB = has_next ? (const char*)g.Bt + (size_t)nxt.pn * tstep : cB;
;         for (int t = 0; t < nt; t += 2) {
;             if constexpr (Epi::MIDSCALE) {
;                 if (t == 4 || t == 8) {
;                     float f[2][4];
; #pragma unroll
;                     for (int ai = 0; ai < 2; ++ai)
; #pragma unroll
;                         for (int m = 0; m < 4; ++m) f[ai][m] = E.rstab[ui * 256 + wr * 64 + fr + ai * HALF + m * 16];
;                     asm volatile("s_waitcnt lgkmcnt(0)" ::: "memory");
; #pragma unroll
;                     for (int ai = 0; ai < 2; ++ai)
; #pragma unroll
;                         for (int m = 0; m < 4; ++m) { const float ff = (t == 4) ? __builtin_amdgcn_rcpf(f[ai][m]) : f[ai][m];
; #pragma unroll
;                             for (int bj = 0; bj < 2; ++bj)
; #pragma unroll
;                                 for (int n = 0; n < 2; ++n) acc[ai][bj][m][n] = acc[ai][bj][m][n] * ff; }
;                 }
;             }
;             const bool last = (t == nt - 2);
;             const char* a1 = cA + (size_t)(t + 1) * kstep;
;             const char* a2 = last ? nA : cA + (size_t)(t + 2) * kstep; const char* b2 = last ? nB : cB + (size_t)(t + 2) * kstep;
;             const char* a3 = a2 + kstep; const char* b3 = b2 + kstep;
;             PG8_LDB(B0, 0, 0); PG8_SCHED; PG8_LDA(At, 0, 0); PG8_STAGE(PG8_SA(1, 1), a1 + hstep, voffA);
;             PG8_WAIT_L(8); PG8_BAR; PG8_WAIT_L(0); PG8_MMA(0, 0, At, B0); PG8_BAR; PG8_SCHED;
;             PG8_LDB(B1, 0, 1); PG8_STAGE(PG8_SB(0, 0), b2, voffB);
;             PG8_BAR; PG8_WAIT_L(0); PG8_MMA(0, 1, At, B1); PG8_BAR;
;             PG8_LDA(At, 0, 1); PG8_STAGE(PG8_SA(0, 0), a2, voffA);
;             PG8_BAR; PG8_WAIT_L(0); PG8_MMA(1, 0, At, B0); PG8_BAR; PG8_SCHED;
;             PG8_STAGE(PG8_SB(0, 1), b2 + hstep, voffB);
;             PG8_WAIT_V(6); PG8_BAR; PG8_MMA(1, 1, At, B1); PG8_BAR;
;             PG8_LDB(B0, 1, 0); PG8_SCHED; PG8_LDA(At, 1, 0); PG8_STAGE(PG8_SA(0, 1), a2 + hstep, voffA);
;             PG8_WAIT_L(8); PG8_BAR; PG8_WAIT_L(0); PG8_MMA(0, 0, At, B0); PG8_BAR; PG8_SCHED;
.LBB0_462:
	v_mov_b64_e32 v[2:3], 0x380
	s_ashr_i32 s11, s10, 31
	v_cmp_lt_i64_e32 vcc, s[12:13], v[2:3]
	s_lshl_b64 s[12:13], s[10:11], 19
	s_add_u32 s12, s45, s12
	s_addc_u32 s13, s46, s13
	s_and_b64 s[22:23], vcc, exec
	s_cselect_b32 s11, s13, s25
	s_cselect_b32 s71, s12, s24
	s_ashr_i32 s9, s8, 31
	s_lshl_b64 s[22:23], s[8:9], 19
	s_add_u32 s22, s42, s22
	s_addc_u32 s23, s43, s23
	s_and_b64 s[36:37], vcc, exec
	s_cselect_b32 s9, s23, s7
	s_cselect_b32 s88, s22, s6
	s_add_u32 s24, s24, 0x40080
	s_addc_u32 s25, s25, 0
	s_add_u32 s89, s6, 0x100
	s_addc_u32 s90, s7, 0
	s_mov_b32 s91, -2
.LBB0_463:
	s_add_u32 s6, s24, 0xfffc0080
	s_addc_u32 s7, s25, -1
	s_add_i32 s58, 0, 0x10000
	v_add_u32_e32 v153, s58, v149
	ds_read_b128 v[140:143], v153
	ds_read_b128 v[144:147], v153 offset:1024
	ds_read_b128 v[154:157], v153 offset:2048
	ds_read_b128 v[158:161], v153 offset:3072
	s_cmp_eq_u32 s91, 12
	s_cselect_b32 s37, s11, s7
	s_cselect_b32 s36, s71, s6
	s_cselect_b32 s7, s9, s90
	s_cselect_b32 s6, s88, s89
	s_add_i32 m0, s47, 0xc000
	ds_read_b128 v[168:171], v152
	ds_read_b128 v[172:175], v152 offset:1024
	ds_read_b128 v[176:179], v152 offset:2048
	ds_read_b128 v[180:183], v152 offset:3072
	ds_read_b128 v[184:187], v152 offset:4096
	ds_read_b128 v[204:207], v152 offset:5120
	ds_read_b128 v[208:211], v152 offset:6144
	ds_read_b128 v[212:215], v152 offset:7168
	global_load_lds_dwordx4 v136, s[24:25]
	s_add_i32 m0, s47, 0xe000
	s_nop 0
	global_load_lds_dwordx4 v138, s[24:25]
	s_waitcnt lgkmcnt(8)
	s_barrier
	s_waitcnt lgkmcnt(0)
	s_setprio 1
	s_waitcnt lgkmcnt(0)
	v_mfma_f32_16x16x32_bf16 v[126:129], v[140:143], v[168:171], 0
	v_mfma_f32_16x16x32_bf16 v[122:125], v[154:157], v[168:171], 0
	v_mfma_f32_16x16x32_bf16 v[114:117], v[140:143], v[176:179], 0
	v_mfma_f32_16x16x32_bf16 v[106:109], v[154:157], v[176:179], 0
	v_mfma_f32_16x16x32_bf16 v[98:101], v[140:143], v[184:187], 0
	v_mfma_f32_16x16x32_bf16 v[90:93], v[154:157], v[184:187], 0
	v_mfma_f32_16x16x32_bf16 v[82:85], v[140:143], v[208:211], 0
	v_mfma_f32_16x16x32_bf16 v[74:77], v[154:157], v[208:211], 0
	v_mfma_f32_16x16x32_bf16 v[126:129], v[144:147], v[172:175], v[126:129]
	v_mfma_f32_16x16x32_bf16 v[122:125], v[158:161], v[172:175], v[122:125]
	v_mfma_f32_16x16x32_bf16 v[114:117], v[144:147], v[180:183], v[114:117]
	v_mfma_f32_16x16x32_bf16 v[106:109], v[158:161], v[180:183], v[106:109]
	v_mfma_f32_16x16x32_bf16 v[98:101], v[144:147], v[204:207], v[98:101]
	v_mfma_f32_16x16x32_bf16 v[90:93], v[158:161], v[204:207], v[90:93]
	v_mfma_f32_16x16x32_bf16 v[82:85], v[144:147], v[212:215], v[82:85]
	v_mfma_f32_16x16x32_bf16 v[74:77], v[158:161], v[212:215], v[74:77]
	s_setprio 0
	s_barrier
	s_add_i32 s70, 0, 0x14000
	s_add_i32 s58, s58, s44
	v_add_u32_e32 v153, s70, v149
	s_mov_b32 m0, s58
	ds_read_b128 v[216:219], v153
	ds_read_b128 v[226:229], v153 offset:1024
	ds_read_b128 v[230:233], v153 offset:2048
	ds_read_b128 v[234:237], v153 offset:3072
	global_load_lds_dwordx4 v0, s[6:7]
	s_add_i32 m0, s58, 0x2000
	s_nop 0
	global_load_lds_dwordx4 v130, s[6:7]
	s_barrier
	s_waitcnt lgkmcnt(0)
	s_setprio 1
	s_waitcnt lgkmcnt(0)
	v_mfma_f32_16x16x32_bf16 v[118:121], v[216:219], v[168:171], 0
	v_mfma_f32_16x16x32_bf16 v[110:113], v[230:233], v[168:171], 0
	v_mfma_f32_16x16x32_bf16 v[102:105], v[216:219], v[176:179], 0
	v_mfma_f32_16x16x32_bf16 v[94:97], v[230:233], v[176:179], 0
	v_mfma_f32_16x16x32_bf16 v[86:89], v[216:219], v[184:187], 0
	v_mfma_f32_16x16x32_bf16 v[78:81], v[230:233], v[184:187], 0
	v_mfma_f32_16x16x32_bf16 v[70:73], v[216:219], v[208:211], 0
	v_mfma_f32_16x16x32_bf16 v[66:69], v[230:233], v[208:211], 0
	v_mfma_f32_16x16x32_bf16 v[118:121], v[226:229], v[172:175], v[118:121]
	v_mfma_f32_16x16x32_bf16 v[110:113], v[234:237], v[172:175], v[110:113]
	v_mfma_f32_16x16x32_bf16 v[102:105], v[226:229], v[180:183], v[102:105]
	v_mfma_f32_16x16x32_bf16 v[94:97], v[234:237], v[180:183], v[94:97]
	v_mfma_f32_16x16x32_bf16 v[86:89], v[226:229], v[204:207], v[86:89]
	v_mfma_f32_16x16x32_bf16 v[78:81], v[234:237], v[204:207], v[78:81]
	v_mfma_f32_16x16x32_bf16 v[70:73], v[226:229], v[212:215], v[70:73]
	v_mfma_f32_16x16x32_bf16 v[66:69], v[234:237], v[212:215], v[66:69]
	s_setprio 0
	s_mov_b32 m0, s47
	s_add_u32 vcc_lo, s36, 0x80
	s_addc_u32 vcc_hi, s37, 0
	s_barrier
	ds_read_b128 v[168:171], v152 offset:16384
	ds_read_b128 v[172:175], v152 offset:17408
	ds_read_b128 v[176:179], v152 offset:18432
	ds_read_b128 v[180:183], v152 offset:19456
	ds_read_b128 v[184:187], v152 offset:20480
	ds_read_b128 v[204:207], v152 offset:21504
	ds_read_b128 v[208:211], v152 offset:22528
	ds_read_b128 v[212:215], v152 offset:23552
	global_load_lds_dwordx4 v134, s[36:37]
	s_mov_b32 m0, s48
	s_nop 0
	global_load_lds_dwordx4 v132, s[36:37]
	s_barrier
	s_waitcnt lgkmcnt(0)
	s_setprio 1
	s_waitcnt lgkmcnt(0)
	v_mfma_f32_16x16x32_bf16 v[62:65], v[140:143], v[168:171], 0
	v_mfma_f32_16x16x32_bf16 v[58:61], v[154:157], v[168:171], 0
	v_mfma_f32_16x16x32_bf16 v[50:53], v[140:143], v[176:179], 0
	v_mfma_f32_16x16x32_bf16 v[42:45], v[154:157], v[176:179], 0
	v_mfma_f32_16x16x32_bf16 v[34:37], v[140:143], v[184:187], 0
	v_mfma_f32_16x16x32_bf16 v[26:29], v[154:157], v[184:187], 0
	v_mfma_f32_16x16x32_bf16 v[18:21], v[140:143], v[208:211], 0
	v_mfma_f32_16x16x32_bf16 v[10:13], v[154:157], v[208:211], 0
	v_mfma_f32_16x16x32_bf16 v[62:65], v[144:147], v[172:175], v[62:65]
	v_mfma_f32_16x16x32_bf16 v[58:61], v[158:161], v[172:175], v[58:61]
	v_mfma_f32_16x16x32_bf16 v[50:53], v[144:147], v[180:183], v[50:53]
	v_mfma_f32_16x16x32_bf16 v[42:45], v[158:161], v[180:183], v[42:45]
	v_mfma_f32_16x16x32_bf16 v[34:37], v[144:147], v[204:207], v[34:37]
	v_mfma_f32_16x16x32_bf16 v[26:29], v[158:161], v[204:207], v[26:29]
	v_mfma_f32_16x16x32_bf16 v[18:21], v[144:147], v[212:215], v[18:21]
	v_mfma_f32_16x16x32_bf16 v[10:13], v[158:161], v[212:215], v[10:13]
	s_setprio 0
	s_barrier
	s_add_u32 s60, s6, 0x40000
	s_addc_u32 s61, s7, 0
	s_add_i32 s58, s70, s44
	s_mov_b32 m0, s58
	s_nop 0
	global_load_lds_dwordx4 v0, s[60:61]
	s_add_i32 m0, s58, 0x2000
	s_nop 0
	global_load_lds_dwordx4 v130, s[60:61]
	s_waitcnt vmcnt(6)
	s_barrier
	s_setprio 1
	v_mfma_f32_16x16x32_bf16 v[54:57], v[216:219], v[168:171], 0
	v_mfma_f32_16x16x32_bf16 v[46:49], v[230:233], v[168:171], 0
	s_cmp_eq_u32 s87, 0
	s_cbranch_scc1 .LdsA_skip_0
	global_store_dwordx4 v166, v[162:165], s[4:5]
; #define PG8_STAGE(bufoff, gbase, voff) do { _Pragma("unroll") for (int _i = 0; _i < 2; ++_i) \
;         __builtin_amdgcn_global_load_lds((const unsigned*)((const char*)(gbase) + (voff)[_i]), (LAS unsigned*)(lds + (bufoff) + ldsw + _i * 8192), 16, 0, 0); } while (0)
; #define PG8_LDA(dst, b, h) do { _Pragma("unroll") for (int m = 0; m < 4; ++m) _Pragma("unroll") for (int k = 0; k < 2; ++k) dst[m][k] = *(const LAS bf16x8*)(lds + PG8_SA(b, h) + aoff + m * 2048 + k * 1024); } while (0)
; #define PG8_LDB(dst, b, h) do { _Pragma("unroll") for (int n = 0; n < 2; ++n) _Pragma("unroll") for (int k = 0; k < 2; ++k) dst[n][k] = *(const LAS bf16x8*)(lds + PG8_SB(b, h) + boff + n * 2048 + k * 1024); } while (0)
; #define PG8_WAIT_V(n) asm volatile("s_waitcnt vmcnt(" #n ")" ::: "memory")
; #define PG8_WAIT_L(n) asm volatile("s_waitcnt lgkmcnt(" #n ")" ::: "memory")
; #define PG8_BAR __builtin_amdgcn_s_barrier()
; #define PG8_SCHED __builtin_amdgcn_sched_barrier(0)
; template <class Epi>
; __device__ __forceinline__ void gemm_phase(LAS unsigned char* lds, const Gemm g, const StaticOrder& S, const Epi& E) {
;     ...
;             PG8_LDB(B0, 0, 0); PG8_SCHED; PG8_LDA(At, 0, 0); PG8_STAGE(PG8_SA(1, 1), a1 + hstep, voffA);
;             PG8_WAIT_L(8); PG8_BAR; PG8_WAIT_L(0); PG8_MMA(0, 0, At, B0); PG8_BAR; PG8_SCHED;
;             PG8_LDB(B1, 0, 1); PG8_STAGE(PG8_SB(0, 0), b2, voffB);
;             PG8_BAR; PG8_WAIT_L(0); PG8_MMA(0, 1, At, B1); PG8_BAR;
;             PG8_LDA(At, 0, 1); PG8_STAGE(PG8_SA(0, 0), a2, voffA);
;             PG8_BAR; PG8_WAIT_L(0); PG8_MMA(1, 0, At, B0); PG8_BAR; PG8_SCHED;
;             PG8_STAGE(PG8_SB(0, 1), b2 + hstep, voffB);
;             PG8_WAIT_V(6); PG8_BAR; PG8_MMA(1, 1, At, B1); PG8_BAR;
;             PG8_LDB(B0, 1, 0); PG8_SCHED; PG8_LDA(At, 1, 0); PG8_STAGE(PG8_SA(0, 1), a2 + hstep, voffA);
;             PG8_WAIT_L(8); PG8_BAR; PG8_WAIT_L(0); PG8_MMA(0, 0, At, B0); PG8_BAR; PG8_SCHED;
;             PG8_LDB(B1, 1, 1); PG8_STAGE(PG8_SB(1, 0), b3, voffB);
;             PG8_BAR; PG8_WAIT_L(0); PG8_MMA(0, 1, At, B1); PG8_BAR;
;             PG8_LDA(At, 1, 1); PG8_STAGE(PG8_SA(1, 0), a3, voffA);
;             PG8_BAR; PG8_WAIT_L(0); PG8_MMA(1, 0, At, B0); PG8_BAR; PG8_SCHED;
;             PG8_STAGE(PG8_SB(1, 1), b3 + hstep, voffB);
;             PG8_WAIT_V(6); PG8_BAR; PG8_MMA(1, 1, At, B1); PG8_BAR;
.LdsA_skip_0:
	v_mfma_f32_16x16x32_bf16 v[38:41], v[216:219], v[176:179], 0
	v_mfma_f32_16x16x32_bf16 v[30:33], v[230:233], v[176:179], 0
	v_mfma_f32_16x16x32_bf16 v[22:25], v[216:219], v[184:187], 0
	v_mfma_f32_16x16x32_bf16 v[14:17], v[230:233], v[184:187], 0
	v_mfma_f32_16x16x32_bf16 v[6:9], v[216:219], v[208:211], 0
	v_mfma_f32_16x16x32_bf16 v[2:5], v[230:233], v[208:211], 0
	v_mfma_f32_16x16x32_bf16 v[54:57], v[226:229], v[172:175], v[54:57]
	v_mfma_f32_16x16x32_bf16 v[46:49], v[234:237], v[172:175], v[46:49]
	v_mfma_f32_16x16x32_bf16 v[38:41], v[226:229], v[180:183], v[38:41]
	v_mfma_f32_16x16x32_bf16 v[30:33], v[234:237], v[180:183], v[30:33]
	v_mfma_f32_16x16x32_bf16 v[22:25], v[226:229], v[204:207], v[22:25]
	v_mfma_f32_16x16x32_bf16 v[14:17], v[234:237], v[204:207], v[14:17]
	v_mfma_f32_16x16x32_bf16 v[6:9], v[226:229], v[212:215], v[6:9]
	v_mfma_f32_16x16x32_bf16 v[2:5], v[234:237], v[212:215], v[2:5]
	s_setprio 0
	s_add_i32 s58, 0, 0x18000
	v_add_u32_e32 v153, s58, v149
	s_barrier
	ds_read_b128 v[140:143], v153
	ds_read_b128 v[144:147], v153 offset:1024
	ds_read_b128 v[154:157], v153 offset:2048
	ds_read_b128 v[158:161], v153 offset:3072
	s_add_u32 s36, s36, 0x40000
	s_addc_u32 s37, s37, 0
	s_mov_b32 m0, s49
	ds_read_b128 v[168:171], v152 offset:32768
	ds_read_b128 v[172:175], v152 offset:33792
	ds_read_b128 v[176:179], v152 offset:34816
	ds_read_b128 v[180:183], v152 offset:35840
	ds_read_b128 v[184:187], v152 offset:36864
	ds_read_b128 v[204:207], v152 offset:37888
	ds_read_b128 v[208:211], v152 offset:38912
	ds_read_b128 v[212:215], v152 offset:39936
	global_load_lds_dwordx4 v134, s[36:37]
	s_mov_b32 m0, s54
	s_nop 0
	global_load_lds_dwordx4 v132, s[36:37]
	s_waitcnt lgkmcnt(8)
	s_barrier
	s_waitcnt lgkmcnt(0)
	s_setprio 1
	s_waitcnt lgkmcnt(0)
	v_mfma_f32_16x16x32_bf16 v[126:129], v[140:143], v[168:171], v[126:129]
	v_mfma_f32_16x16x32_bf16 v[122:125], v[154:157], v[168:171], v[122:125]
	v_mfma_f32_16x16x32_bf16 v[114:117], v[140:143], v[176:179], v[114:117]
	v_mfma_f32_16x16x32_bf16 v[106:109], v[154:157], v[176:179], v[106:109]
	v_mfma_f32_16x16x32_bf16 v[98:101], v[140:143], v[184:187], v[98:101]
	v_mfma_f32_16x16x32_bf16 v[90:93], v[154:157], v[184:187], v[90:93]
	v_mfma_f32_16x16x32_bf16 v[82:85], v[140:143], v[208:211], v[82:85]
	v_mfma_f32_16x16x32_bf16 v[74:77], v[154:157], v[208:211], v[74:77]
	v_mfma_f32_16x16x32_bf16 v[126:129], v[144:147], v[172:175], v[126:129]
	v_mfma_f32_16x16x32_bf16 v[122:125], v[158:161], v[172:175], v[122:125]
	v_mfma_f32_16x16x32_bf16 v[114:117], v[144:147], v[180:183], v[114:117]
	v_mfma_f32_16x16x32_bf16 v[106:109], v[158:161], v[180:183], v[106:109]
	v_mfma_f32_16x16x32_bf16 v[98:101], v[144:147], v[204:207], v[98:101]
	v_mfma_f32_16x16x32_bf16 v[90:93], v[158:161], v[204:207], v[90:93]
	v_mfma_f32_16x16x32_bf16 v[82:85], v[144:147], v[212:215], v[82:85]
	v_mfma_f32_16x16x32_bf16 v[74:77], v[158:161], v[212:215], v[74:77]
	s_setprio 0
	s_barrier
	s_add_i32 s36, 0, 0x1c000
	s_add_i32 s37, s58, s44
	v_add_u32_e32 v153, s36, v149
	s_add_u32 s60, s6, 0x80
	s_addc_u32 s61, s7, 0
	s_mov_b32 m0, s37
	ds_read_b128 v[216:219], v153
	ds_read_b128 v[226:229], v153 offset:1024
	ds_read_b128 v[230:233], v153 offset:2048
	ds_read_b128 v[234:237], v153 offset:3072
	global_load_lds_dwordx4 v0, s[60:61]
	s_add_i32 m0, s37, 0x2000
	s_nop 0
	global_load_lds_dwordx4 v130, s[60:61]
	s_barrier
	s_waitcnt lgkmcnt(0)
	s_setprio 1
	s_waitcnt lgkmcnt(0)
	v_mfma_f32_16x16x32_bf16 v[118:121], v[216:219], v[168:171], v[118:121]
	v_mfma_f32_16x16x32_bf16 v[110:113], v[230:233], v[168:171], v[110:113]
	v_mfma_f32_16x16x32_bf16 v[102:105], v[216:219], v[176:179], v[102:105]
	v_mfma_f32_16x16x32_bf16 v[94:97], v[230:233], v[176:179], v[94:97]
	v_mfma_f32_16x16x32_bf16 v[86:89], v[216:219], v[184:187], v[86:89]
	v_mfma_f32_16x16x32_bf16 v[78:81], v[230:233], v[184:187], v[78:81]
	v_mfma_f32_16x16x32_bf16 v[70:73], v[216:219], v[208:211], v[70:73]
	v_mfma_f32_16x16x32_bf16 v[66:69], v[230:233], v[208:211], v[66:69]
	v_mfma_f32_16x16x32_bf16 v[118:121], v[226:229], v[172:175], v[118:121]
	v_mfma_f32_16x16x32_bf16 v[110:113], v[234:237], v[172:175], v[110:113]
	v_mfma_f32_16x16x32_bf16 v[102:105], v[226:229], v[180:183], v[102:105]
	v_mfma_f32_16x16x32_bf16 v[94:97], v[234:237], v[180:183], v[94:97]
	v_mfma_f32_16x16x32_bf16 v[86:89], v[226:229], v[204:207], v[86:89]
	v_mfma_f32_16x16x32_bf16 v[78:81], v[234:237], v[204:207], v[78:81]
	v_mfma_f32_16x16x32_bf16 v[70:73], v[226:229], v[212:215], v[70:73]
	v_mfma_f32_16x16x32_bf16 v[66:69], v[234:237], v[212:215], v[66:69]
	s_setprio 0
	s_mov_b32 m0, s55
	s_barrier
	ds_read_b128 v[168:171], v152 offset:49152
	ds_read_b128 v[172:175], v152 offset:50176
	ds_read_b128 v[176:179], v152 offset:51200
	ds_read_b128 v[180:183], v152 offset:52224
	ds_read_b128 v[184:187], v152 offset:53248
	ds_read_b128 v[204:207], v152 offset:54272
	ds_read_b128 v[208:211], v152 offset:55296
	ds_read_b128 v[212:215], v152 offset:56320
	global_load_lds_dwordx4 v134, vcc
	s_mov_b32 m0, s83
	s_nop 0
	global_load_lds_dwordx4 v132, vcc
	s_barrier
; #define PG8_STAGE(bufoff, gbase, voff) do { _Pragma("unroll") for (int _i = 0; _i < 2; ++_i) \
;         __builtin_amdgcn_global_load_lds((const unsigned*)((const char*)(gbase) + (voff)[_i]), (LAS unsigned*)(lds + (bufoff) + ldsw + _i * 8192), 16, 0, 0); } while (0)
; #define PG8_LDA(dst, b, h) do { _Pragma("unroll") for (int m = 0; m < 4; ++m) _Pragma("unroll") for (int k = 0; k < 2; ++k) dst[m][k] = *(const LAS bf16x8*)(lds + PG8_SA(b, h) + aoff + m * 2048 + k * 1024); } while (0)
; #define PG8_LDB(dst, b, h) do { _Pragma("unroll") for (int n = 0; n < 2; ++n) _Pragma("unroll") for (int k = 0; k < 2; ++k) dst[n][k] = *(const LAS bf16x8*)(lds + PG8_SB(b, h) + boff + n * 2048 + k * 1024); } while (0)
; template <class Epi>
; __device__ __forceinline__ void gemm_phase(LAS unsigned char* lds, const Gemm g, const StaticOrder& S, const Epi& E) {
;     ...
;             const char* a1 = cA + (size_t)(t + 1) * kstep;
;             const char* a2 = last ? nA : cA + (size_t)(t + 2) * kstep; const char* b2 = last ? nB : cB + (size_t)(t + 2) * kstep;
;             const char* a3 = a2 + kstep; const char* b3 = b2 + kstep;
;             PG8_LDB(B0, 0, 0); PG8_SCHED; PG8_LDA(At, 0, 0); PG8_STAGE(PG8_SA(1, 1), a1 + hstep, voffA);
;             PG8_WAIT_L(8); PG8_BAR; PG8_WAIT_L(0); PG8_MMA(0, 0, At, B0); PG8_BAR; PG8_SCHED;
;             PG8_LDB(B1, 0, 1); PG8_STAGE(PG8_SB(0, 0), b2, voffB);
;             PG8_BAR; PG8_WAIT_L(0); PG8_MMA(0, 1, At, B1); PG8_BAR;
;             PG8_LDA(At, 0, 1); PG8_STAGE(PG8_SA(0, 0), a2, voffA);
;             PG8_BAR; PG8_WAIT_L(0); PG8_MMA(1, 0, At, B0); PG8_BAR; PG8_SCHED;
;             PG8_STAGE(PG8_SB(0, 1), b2 + hstep, voffB);
;             PG8_WAIT_V(6); PG8_BAR; PG8_MMA(1, 1, At, B1); PG8_BAR;
;             PG8_LDB(B0, 1, 0); PG8_SCHED; PG8_LDA(At, 1, 0); PG8_STAGE(PG8_SA(0, 1), a2 + hstep, voffA);
;             PG8_WAIT_L(8); PG8_BAR; PG8_WAIT_L(0); PG8_MMA(0, 0, At, B0); PG8_BAR; PG8_SCHED;
;             PG8_LDB(B1, 1, 1); PG8_STAGE(PG8_SB(1, 0), b3, voffB);
;             PG8_BAR; PG8_WAIT_L(0); PG8_MMA(0, 1, At, B1); PG8_BAR;
;             PG8_LDA(At, 1, 1); PG8_STAGE(PG8_SA(1, 0), a3, voffA);
;             PG8_BAR; PG8_WAIT_L(0); PG8_MMA(1, 0, At, B0); PG8_BAR; PG8_SCHED;
;             PG8_STAGE(PG8_SB(1, 1), b3 + hstep, voffB);
;             PG8_WAIT_V(6); PG8_BAR; PG8_MMA(1, 1, At, B1); PG8_BAR;
	s_waitcnt lgkmcnt(0)
	s_setprio 1
	s_waitcnt lgkmcnt(0)
	v_mfma_f32_16x16x32_bf16 v[62:65], v[140:143], v[168:171], v[62:65]
	v_mfma_f32_16x16x32_bf16 v[58:61], v[154:157], v[168:171], v[58:61]
	v_mfma_f32_16x16x32_bf16 v[50:53], v[140:143], v[176:179], v[50:53]
	v_mfma_f32_16x16x32_bf16 v[42:45], v[154:157], v[176:179], v[42:45]
	v_mfma_f32_16x16x32_bf16 v[34:37], v[140:143], v[184:187], v[34:37]
	v_mfma_f32_16x16x32_bf16 v[26:29], v[154:157], v[184:187], v[26:29]
	v_mfma_f32_16x16x32_bf16 v[18:21], v[140:143], v[208:211], v[18:21]
	v_mfma_f32_16x16x32_bf16 v[10:13], v[154:157], v[208:211], v[10:13]
	v_mfma_f32_16x16x32_bf16 v[62:65], v[144:147], v[172:175], v[62:65]
	v_mfma_f32_16x16x32_bf16 v[58:61], v[158:161], v[172:175], v[58:61]
	v_mfma_f32_16x16x32_bf16 v[50:53], v[144:147], v[180:183], v[50:53]
	v_mfma_f32_16x16x32_bf16 v[42:45], v[158:161], v[180:183], v[42:45]
	v_mfma_f32_16x16x32_bf16 v[34:37], v[144:147], v[204:207], v[34:37]
	v_mfma_f32_16x16x32_bf16 v[26:29], v[158:161], v[204:207], v[26:29]
	v_mfma_f32_16x16x32_bf16 v[18:21], v[144:147], v[212:215], v[18:21]
	v_mfma_f32_16x16x32_bf16 v[10:13], v[158:161], v[212:215], v[10:13]
	s_setprio 0
	s_barrier
	s_add_u32 s6, s6, 0x40080
	s_addc_u32 s7, s7, 0
	s_add_i32 s36, s36, s44
	s_mov_b32 m0, s36
	s_nop 0
	global_load_lds_dwordx4 v0, s[6:7]
	s_add_i32 m0, s36, 0x2000
	s_nop 0
	global_load_lds_dwordx4 v130, s[6:7]
	s_waitcnt vmcnt(6)
	s_barrier
	s_setprio 1
	v_mfma_f32_16x16x32_bf16 v[54:57], v[216:219], v[168:171], v[54:57]
	v_mfma_f32_16x16x32_bf16 v[46:49], v[230:233], v[168:171], v[46:49]
	v_mfma_f32_16x16x32_bf16 v[38:41], v[216:219], v[176:179], v[38:41]
	v_mfma_f32_16x16x32_bf16 v[30:33], v[230:233], v[176:179], v[30:33]
	v_mfma_f32_16x16x32_bf16 v[22:25], v[216:219], v[184:187], v[22:25]
	v_mfma_f32_16x16x32_bf16 v[14:17], v[230:233], v[184:187], v[14:17]
	v_mfma_f32_16x16x32_bf16 v[6:9], v[216:219], v[208:211], v[6:9]
	v_mfma_f32_16x16x32_bf16 v[2:5], v[230:233], v[208:211], v[2:5]
	v_mfma_f32_16x16x32_bf16 v[54:57], v[226:229], v[172:175], v[54:57]
	v_mfma_f32_16x16x32_bf16 v[46:49], v[234:237], v[172:175], v[46:49]
	v_mfma_f32_16x16x32_bf16 v[38:41], v[226:229], v[180:183], v[38:41]
	v_mfma_f32_16x16x32_bf16 v[30:33], v[234:237], v[180:183], v[30:33]
	v_mfma_f32_16x16x32_bf16 v[22:25], v[226:229], v[204:207], v[22:25]
	v_mfma_f32_16x16x32_bf16 v[14:17], v[234:237], v[204:207], v[14:17]
	v_mfma_f32_16x16x32_bf16 v[6:9], v[226:229], v[212:215], v[6:9]
	v_mfma_f32_16x16x32_bf16 v[2:5], v[234:237], v[212:215], v[2:5]
	s_setprio 0
	s_add_i32 s91, s91, 2
	s_add_u32 s24, s24, 0x100
	s_addc_u32 s25, s25, 0
	s_add_u32 s89, s89, 0x100
	s_addc_u32 s90, s90, 0
	s_cmp_gt_u32 s91, 13
	s_barrier
	s_add_u32 s6, s24, 0xfffc0080
	s_addc_u32 s7, s25, -1
	s_add_i32 s58, 0, 0x10000
	v_add_u32_e32 v153, s58, v149
	ds_read_b128 v[140:143], v153
	ds_read_b128 v[144:147], v153 offset:1024
	ds_read_b128 v[154:157], v153 offset:2048
	ds_read_b128 v[158:161], v153 offset:3072
	s_cmp_eq_u32 s91, 12
	s_cselect_b32 s37, s11, s7
	s_cselect_b32 s36, s71, s6
	s_cselect_b32 s7, s9, s90
	s_cselect_b32 s6, s88, s89
	s_add_i32 m0, s47, 0xc000
	ds_read_b128 v[168:171], v152
	ds_read_b128 v[172:175], v152 offset:1024
	ds_read_b128 v[176:179], v152 offset:2048
	ds_read_b128 v[180:183], v152 offset:3072
	ds_read_b128 v[184:187], v152 offset:4096
	ds_read_b128 v[204:207], v152 offset:5120
	ds_read_b128 v[208:211], v152 offset:6144
	ds_read_b128 v[212:215], v152 offset:7168
	global_load_lds_dwordx4 v136, s[24:25]
	s_add_i32 m0, s47, 0xe000
	s_nop 0
	global_load_lds_dwordx4 v138, s[24:25]
	s_waitcnt lgkmcnt(8)
	s_barrier
	s_waitcnt lgkmcnt(0)
	s_setprio 1
	s_waitcnt lgkmcnt(0)
	v_mfma_f32_16x16x32_bf16 v[126:129], v[140:143], v[168:171], v[126:129]
	v_mfma_f32_16x16x32_bf16 v[122:125], v[154:157], v[168:171], v[122:125]
	v_mfma_f32_16x16x32_bf16 v[114:117], v[140:143], v[176:179], v[114:117]
	v_mfma_f32_16x16x32_bf16 v[106:109], v[154:157], v[176:179], v[106:109]
	v_mfma_f32_16x16x32_bf16 v[98:101], v[140:143], v[184:187], v[98:101]
	v_mfma_f32_16x16x32_bf16 v[90:93], v[154:157], v[184:187], v[90:93]
	v_mfma_f32_16x16x32_bf16 v[82:85], v[140:143], v[208:211], v[82:85]
	v_mfma_f32_16x16x32_bf16 v[74:77], v[154:157], v[208:211], v[74:77]
	v_mfma_f32_16x16x32_bf16 v[126:129], v[144:147], v[172:175], v[126:129]
	v_mfma_f32_16x16x32_bf16 v[122:125], v[158:161], v[172:175], v[122:125]
	v_mfma_f32_16x16x32_bf16 v[114:117], v[144:147], v[180:183], v[114:117]
	v_mfma_f32_16x16x32_bf16 v[106:109], v[158:161], v[180:183], v[106:109]
	v_mfma_f32_16x16x32_bf16 v[98:101], v[144:147], v[204:207], v[98:101]
	v_mfma_f32_16x16x32_bf16 v[90:93], v[158:161], v[204:207], v[90:93]
	v_mfma_f32_16x16x32_bf16 v[82:85], v[144:147], v[212:215], v[82:85]
	v_mfma_f32_16x16x32_bf16 v[74:77], v[158:161], v[212:215], v[74:77]
	s_setprio 0
	s_barrier
	s_add_i32 s70, 0, 0x14000
	s_add_i32 s58, s58, s44
	v_add_u32_e32 v153, s70, v149
	s_mov_b32 m0, s58
	ds_read_b128 v[216:219], v153
	ds_read_b128 v[226:229], v153 offset:1024
	ds_read_b128 v[230:233], v153 offset:2048
	ds_read_b128 v[234:237], v153 offset:3072
	global_load_lds_dwordx4 v0, s[6:7]
	s_add_i32 m0, s58, 0x2000
	s_nop 0
	global_load_lds_dwordx4 v130, s[6:7]
	s_barrier
; #define PG8_STAGE(bufoff, gbase, voff) do { _Pragma("unroll") for (int _i = 0; _i < 2; ++_i) \
;         __builtin_amdgcn_global_load_lds((const unsigned*)((const char*)(gbase) + (voff)[_i]), (LAS unsigned*)(lds + (bufoff) + ldsw + _i * 8192), 16, 0, 0); } while (0)
; #define PG8_LDA(dst, b, h) do { _Pragma("unroll") for (int m = 0; m < 4; ++m) _Pragma("unroll") for (int k = 0; k < 2; ++k) dst[m][k] = *(const LAS bf16x8*)(lds + PG8_SA(b, h) + aoff + m * 2048 + k * 1024); } while (0)
; #define PG8_LDB(dst, b, h) do { _Pragma("unroll") for (int n = 0; n < 2; ++n) _Pragma("unroll") for (int k = 0; k < 2; ++k) dst[n][k] = *(const LAS bf16x8*)(lds + PG8_SB(b, h) + boff + n * 2048 + k * 1024); } while (0)
; #define PG8_WAIT_V(n) asm volatile("s_waitcnt vmcnt(" #n ")" ::: "memory")
; #define PG8_WAIT_L(n) asm volatile("s_waitcnt lgkmcnt(" #n ")" ::: "memory")
; #define PG8_BAR __builtin_amdgcn_s_barrier()
; #define PG8_SCHED __builtin_amdgcn_sched_barrier(0)
; template <class Epi>
; __device__ __forceinline__ void gemm_phase(LAS unsigned char* lds, const Gemm g, const StaticOrder& S, const Epi& E) {
;     ...
;             PG8_LDB(B0, 0, 0); PG8_SCHED; PG8_LDA(At, 0, 0); PG8_STAGE(PG8_SA(1, 1), a1 + hstep, voffA);
;             PG8_WAIT_L(8); PG8_BAR; PG8_WAIT_L(0); PG8_MMA(0, 0, At, B0); PG8_BAR; PG8_SCHED;
;             PG8_LDB(B1, 0, 1); PG8_STAGE(PG8_SB(0, 0), b2, voffB);
;             PG8_BAR; PG8_WAIT_L(0); PG8_MMA(0, 1, At, B1); PG8_BAR;
;             PG8_LDA(At, 0, 1); PG8_STAGE(PG8_SA(0, 0), a2, voffA);
;             PG8_BAR; PG8_WAIT_L(0); PG8_MMA(1, 0, At, B0); PG8_BAR; PG8_SCHED;
;             PG8_STAGE(PG8_SB(0, 1), b2 + hstep, voffB);
;             PG8_WAIT_V(6); PG8_BAR; PG8_MMA(1, 1, At, B1); PG8_BAR;
;             PG8_LDB(B0, 1, 0); PG8_SCHED; PG8_LDA(At, 1, 0); PG8_STAGE(PG8_SA(0, 1), a2 + hstep, voffA);
;             PG8_WAIT_L(8); PG8_BAR; PG8_WAIT_L(0); PG8_MMA(0, 0, At, B0); PG8_BAR; PG8_SCHED;
;             PG8_LDB(B1, 1, 1); PG8_STAGE(PG8_SB(1, 0), b3, voffB);
;             PG8_BAR; PG8_WAIT_L(0); PG8_MMA(0, 1, At, B1); PG8_BAR;
;             PG8_LDA(At, 1, 1); PG8_STAGE(PG8_SA(1, 0), a3, voffA);
;             PG8_BAR; PG8_WAIT_L(0); PG8_MMA(1, 0, At, B0); PG8_BAR; PG8_SCHED;
;             PG8_STAGE(PG8_SB(1, 1), b3 + hstep, voffB);
;             PG8_WAIT_V(6); PG8_BAR; PG8_MMA(1, 1, At, B1); PG8_BAR;
	s_waitcnt lgkmcnt(0)
	s_setprio 1
	s_waitcnt lgkmcnt(0)
	v_mfma_f32_16x16x32_bf16 v[118:121], v[216:219], v[168:171], v[118:121]
	v_mfma_f32_16x16x32_bf16 v[110:113], v[230:233], v[168:171], v[110:113]
	v_mfma_f32_16x16x32_bf16 v[102:105], v[216:219], v[176:179], v[102:105]
	v_mfma_f32_16x16x32_bf16 v[94:97], v[230:233], v[176:179], v[94:97]
	v_mfma_f32_16x16x32_bf16 v[86:89], v[216:219], v[184:187], v[86:89]
	v_mfma_f32_16x16x32_bf16 v[78:81], v[230:233], v[184:187], v[78:81]
	v_mfma_f32_16x16x32_bf16 v[70:73], v[216:219], v[208:211], v[70:73]
	v_mfma_f32_16x16x32_bf16 v[66:69], v[230:233], v[208:211], v[66:69]
	v_mfma_f32_16x16x32_bf16 v[118:121], v[226:229], v[172:175], v[118:121]
	v_mfma_f32_16x16x32_bf16 v[110:113], v[234:237], v[172:175], v[110:113]
	v_mfma_f32_16x16x32_bf16 v[102:105], v[226:229], v[180:183], v[102:105]
	v_mfma_f32_16x16x32_bf16 v[94:97], v[234:237], v[180:183], v[94:97]
	v_mfma_f32_16x16x32_bf16 v[86:89], v[226:229], v[204:207], v[86:89]
	v_mfma_f32_16x16x32_bf16 v[78:81], v[234:237], v[204:207], v[78:81]
	v_mfma_f32_16x16x32_bf16 v[70:73], v[226:229], v[212:215], v[70:73]
	v_mfma_f32_16x16x32_bf16 v[66:69], v[234:237], v[212:215], v[66:69]
	s_setprio 0
	s_mov_b32 m0, s47
	s_add_u32 vcc_lo, s36, 0x80
	s_addc_u32 vcc_hi, s37, 0
	s_barrier
	ds_read_b128 v[168:171], v152 offset:16384
	ds_read_b128 v[172:175], v152 offset:17408
	ds_read_b128 v[176:179], v152 offset:18432
	ds_read_b128 v[180:183], v152 offset:19456
	ds_read_b128 v[184:187], v152 offset:20480
	ds_read_b128 v[204:207], v152 offset:21504
	ds_read_b128 v[208:211], v152 offset:22528
	ds_read_b128 v[212:215], v152 offset:23552
	global_load_lds_dwordx4 v134, s[36:37]
	s_mov_b32 m0, s48
	s_nop 0
	global_load_lds_dwordx4 v132, s[36:37]
	s_barrier
	s_waitcnt lgkmcnt(0)
	s_setprio 1
	s_waitcnt lgkmcnt(0)
	v_mfma_f32_16x16x32_bf16 v[62:65], v[140:143], v[168:171], v[62:65]
	v_mfma_f32_16x16x32_bf16 v[58:61], v[154:157], v[168:171], v[58:61]
	v_mfma_f32_16x16x32_bf16 v[50:53], v[140:143], v[176:179], v[50:53]
	v_mfma_f32_16x16x32_bf16 v[42:45], v[154:157], v[176:179], v[42:45]
	v_mfma_f32_16x16x32_bf16 v[34:37], v[140:143], v[184:187], v[34:37]
	v_mfma_f32_16x16x32_bf16 v[26:29], v[154:157], v[184:187], v[26:29]
	v_mfma_f32_16x16x32_bf16 v[18:21], v[140:143], v[208:211], v[18:21]
	v_mfma_f32_16x16x32_bf16 v[10:13], v[154:157], v[208:211], v[10:13]
	v_mfma_f32_16x16x32_bf16 v[62:65], v[144:147], v[172:175], v[62:65]
	v_mfma_f32_16x16x32_bf16 v[58:61], v[158:161], v[172:175], v[58:61]
	v_mfma_f32_16x16x32_bf16 v[50:53], v[144:147], v[180:183], v[50:53]
	v_mfma_f32_16x16x32_bf16 v[42:45], v[158:161], v[180:183], v[42:45]
	v_mfma_f32_16x16x32_bf16 v[34:37], v[144:147], v[204:207], v[34:37]
	v_mfma_f32_16x16x32_bf16 v[26:29], v[158:161], v[204:207], v[26:29]
	v_mfma_f32_16x16x32_bf16 v[18:21], v[144:147], v[212:215], v[18:21]
	v_mfma_f32_16x16x32_bf16 v[10:13], v[158:161], v[212:215], v[10:13]
	s_setprio 0
	s_barrier
	s_add_u32 s60, s6, 0x40000
	s_addc_u32 s61, s7, 0
	s_add_i32 s58, s70, s44
	s_mov_b32 m0, s58
	s_nop 0
	global_load_lds_dwordx4 v0, s[60:61]
	s_add_i32 m0, s58, 0x2000
	s_nop 0
	global_load_lds_dwordx4 v130, s[60:61]
	s_waitcnt vmcnt(6)
	s_barrier
	s_setprio 1
	v_mfma_f32_16x16x32_bf16 v[54:57], v[216:219], v[168:171], v[54:57]
	v_mfma_f32_16x16x32_bf16 v[46:49], v[230:233], v[168:171], v[46:49]
	s_cmp_eq_u32 s87, 0
	s_cbranch_scc1 .LdsA_skip_1
	global_store_dwordx4 v166, v[188:191], s[4:5] offset:256
	v_add_u32_e32 v166, 0xe000, v166
.LdsA_skip_1:
	v_mfma_f32_16x16x32_bf16 v[38:41], v[216:219], v[176:179], v[38:41]
	v_mfma_f32_16x16x32_bf16 v[30:33], v[230:233], v[176:179], v[30:33]
	v_mfma_f32_16x16x32_bf16 v[22:25], v[216:219], v[184:187], v[22:25]
	v_mfma_f32_16x16x32_bf16 v[14:17], v[230:233], v[184:187], v[14:17]
	v_mfma_f32_16x16x32_bf16 v[6:9], v[216:219], v[208:211], v[6:9]
	v_mfma_f32_16x16x32_bf16 v[2:5], v[230:233], v[208:211], v[2:5]
	v_mfma_f32_16x16x32_bf16 v[54:57], v[226:229], v[172:175], v[54:57]
	v_mfma_f32_16x16x32_bf16 v[46:49], v[234:237], v[172:175], v[46:49]
	v_mfma_f32_16x16x32_bf16 v[38:41], v[226:229], v[180:183], v[38:41]
	v_mfma_f32_16x16x32_bf16 v[30:33], v[234:237], v[180:183], v[30:33]
	v_mfma_f32_16x16x32_bf16 v[22:25], v[226:229], v[204:207], v[22:25]
	v_mfma_f32_16x16x32_bf16 v[14:17], v[234:237], v[204:207], v[14:17]
	v_mfma_f32_16x16x32_bf16 v[6:9], v[226:229], v[212:215], v[6:9]
	v_mfma_f32_16x16x32_bf16 v[2:5], v[234:237], v[212:215], v[2:5]
	s_setprio 0
	s_add_i32 s58, 0, 0x18000
	v_add_u32_e32 v153, s58, v149
	s_barrier
	ds_read_b128 v[140:143], v153
	ds_read_b128 v[144:147], v153 offset:1024
	ds_read_b128 v[154:157], v153 offset:2048
	ds_read_b128 v[158:161], v153 offset:3072
	s_add_u32 s36, s36, 0x40000
	s_addc_u32 s37, s37, 0
	s_mov_b32 m0, s49
	ds_read_b128 v[168:171], v152 offset:32768
	ds_read_b128 v[172:175], v152 offset:33792
	ds_read_b128 v[176:179], v152 offset:34816
	ds_read_b128 v[180:183], v152 offset:35840
	ds_read_b128 v[184:187], v152 offset:36864
	ds_read_b128 v[204:207], v152 offset:37888
	ds_read_b128 v[208:211], v152 offset:38912
	ds_read_b128 v[212:215], v152 offset:39936
	global_load_lds_dwordx4 v134, s[36:37]
	s_mov_b32 m0, s54
	s_nop 0
	global_load_lds_dwordx4 v132, s[36:37]
	s_waitcnt lgkmcnt(8)
	s_barrier
; #define PG8_STAGE(bufoff, gbase, voff) do { _Pragma("unroll") for (int _i = 0; _i < 2; ++_i) \
;         __builtin_amdgcn_global_load_lds((const unsigned*)((const char*)(gbase) + (voff)[_i]), (LAS unsigned*)(lds + (bufoff) + ldsw + _i * 8192), 16, 0, 0); } while (0)
; #define PG8_LDA(dst, b, h) do { _Pragma("unroll") for (int m = 0; m < 4; ++m) _Pragma("unroll") for (int k = 0; k < 2; ++k) dst[m][k] = *(const LAS bf16x8*)(lds + PG8_SA(b, h) + aoff + m * 2048 + k * 1024); } while (0)
; #define PG8_LDB(dst, b, h) do { _Pragma("unroll") for (int n = 0; n < 2; ++n) _Pragma("unroll") for (int k = 0; k < 2; ++k) dst[n][k] = *(const LAS bf16x8*)(lds + PG8_SB(b, h) + boff + n * 2048 + k * 1024); } while (0)
; #define PG8_WAIT_V(n) asm volatile("s_waitcnt vmcnt(" #n ")" ::: "memory")
; #define PG8_WAIT_L(n) asm volatile("s_waitcnt lgkmcnt(" #n ")" ::: "memory")
; #define PG8_BAR __builtin_amdgcn_s_barrier()
; #define PG8_SCHED __builtin_amdgcn_sched_barrier(0)
; template <class Epi>
; __device__ __forceinline__ void gemm_phase(LAS unsigned char* lds, const Gemm g, const StaticOrder& S, const Epi& E) {
;     ...
;             PG8_LDB(B0, 0, 0); PG8_SCHED; PG8_LDA(At, 0, 0); PG8_STAGE(PG8_SA(1, 1), a1 + hstep, voffA);
;             PG8_WAIT_L(8); PG8_BAR; PG8_WAIT_L(0); PG8_MMA(0, 0, At, B0); PG8_BAR; PG8_SCHED;
;             PG8_LDB(B1, 0, 1); PG8_STAGE(PG8_SB(0, 0), b2, voffB);
;             PG8_BAR; PG8_WAIT_L(0); PG8_MMA(0, 1, At, B1); PG8_BAR;
;             PG8_LDA(At, 0, 1); PG8_STAGE(PG8_SA(0, 0), a2, voffA);
;             PG8_BAR; PG8_WAIT_L(0); PG8_MMA(1, 0, At, B0); PG8_BAR; PG8_SCHED;
;             PG8_STAGE(PG8_SB(0, 1), b2 + hstep, voffB);
;             PG8_WAIT_V(6); PG8_BAR; PG8_MMA(1, 1, At, B1); PG8_BAR;
;             PG8_LDB(B0, 1, 0); PG8_SCHED; PG8_LDA(At, 1, 0); PG8_STAGE(PG8_SA(0, 1), a2 + hstep, voffA);
;             PG8_WAIT_L(8); PG8_BAR; PG8_WAIT_L(0); PG8_MMA(0, 0, At, B0); PG8_BAR; PG8_SCHED;
;             PG8_LDB(B1, 1, 1); PG8_STAGE(PG8_SB(1, 0), b3, voffB);
;             PG8_BAR; PG8_WAIT_L(0); PG8_MMA(0, 1, At, B1); PG8_BAR;
;             PG8_LDA(At, 1, 1); PG8_STAGE(PG8_SA(1, 0), a3, voffA);
;             PG8_BAR; PG8_WAIT_L(0); PG8_MMA(1, 0, At, B0); PG8_BAR; PG8_SCHED;
;             PG8_STAGE(PG8_SB(1, 1), b3 + hstep, voffB);
;             PG8_WAIT_V(6); PG8_BAR; PG8_MMA(1, 1, At, B1); PG8_BAR;
	s_waitcnt lgkmcnt(0)
	s_setprio 1
	s_waitcnt lgkmcnt(0)
	v_mfma_f32_16x16x32_bf16 v[126:129], v[140:143], v[168:171], v[126:129]
	v_mfma_f32_16x16x32_bf16 v[122:125], v[154:157], v[168:171], v[122:125]
	v_mfma_f32_16x16x32_bf16 v[114:117], v[140:143], v[176:179], v[114:117]
	v_mfma_f32_16x16x32_bf16 v[106:109], v[154:157], v[176:179], v[106:109]
	v_mfma_f32_16x16x32_bf16 v[98:101], v[140:143], v[184:187], v[98:101]
	v_mfma_f32_16x16x32_bf16 v[90:93], v[154:157], v[184:187], v[90:93]
	v_mfma_f32_16x16x32_bf16 v[82:85], v[140:143], v[208:211], v[82:85]
	v_mfma_f32_16x16x32_bf16 v[74:77], v[154:157], v[208:211], v[74:77]
	v_mfma_f32_16x16x32_bf16 v[126:129], v[144:147], v[172:175], v[126:129]
	v_mfma_f32_16x16x32_bf16 v[122:125], v[158:161], v[172:175], v[122:125]
	v_mfma_f32_16x16x32_bf16 v[114:117], v[144:147], v[180:183], v[114:117]
	v_mfma_f32_16x16x32_bf16 v[106:109], v[158:161], v[180:183], v[106:109]
	v_mfma_f32_16x16x32_bf16 v[98:101], v[144:147], v[204:207], v[98:101]
	v_mfma_f32_16x16x32_bf16 v[90:93], v[158:161], v[204:207], v[90:93]
	v_mfma_f32_16x16x32_bf16 v[82:85], v[144:147], v[212:215], v[82:85]
	v_mfma_f32_16x16x32_bf16 v[74:77], v[158:161], v[212:215], v[74:77]
	s_setprio 0
	s_barrier
	s_add_i32 s36, 0, 0x1c000
	s_add_i32 s37, s58, s44
	v_add_u32_e32 v153, s36, v149
	s_add_u32 s60, s6, 0x80
	s_addc_u32 s61, s7, 0
	s_mov_b32 m0, s37
	ds_read_b128 v[216:219], v153
	ds_read_b128 v[226:229], v153 offset:1024
	ds_read_b128 v[230:233], v153 offset:2048
	ds_read_b128 v[234:237], v153 offset:3072
	global_load_lds_dwordx4 v0, s[60:61]
	s_add_i32 m0, s37, 0x2000
	s_nop 0
	global_load_lds_dwordx4 v130, s[60:61]
	s_barrier
	s_waitcnt lgkmcnt(0)
	s_setprio 1
	s_waitcnt lgkmcnt(0)
	v_mfma_f32_16x16x32_bf16 v[118:121], v[216:219], v[168:171], v[118:121]
	v_mfma_f32_16x16x32_bf16 v[110:113], v[230:233], v[168:171], v[110:113]
	v_mfma_f32_16x16x32_bf16 v[102:105], v[216:219], v[176:179], v[102:105]
	v_mfma_f32_16x16x32_bf16 v[94:97], v[230:233], v[176:179], v[94:97]
	v_mfma_f32_16x16x32_bf16 v[86:89], v[216:219], v[184:187], v[86:89]
	v_mfma_f32_16x16x32_bf16 v[78:81], v[230:233], v[184:187], v[78:81]
	v_mfma_f32_16x16x32_bf16 v[70:73], v[216:219], v[208:211], v[70:73]
	v_mfma_f32_16x16x32_bf16 v[66:69], v[230:233], v[208:211], v[66:69]
	v_mfma_f32_16x16x32_bf16 v[118:121], v[226:229], v[172:175], v[118:121]
	v_mfma_f32_16x16x32_bf16 v[110:113], v[234:237], v[172:175], v[110:113]
	v_mfma_f32_16x16x32_bf16 v[102:105], v[226:229], v[180:183], v[102:105]
	v_mfma_f32_16x16x32_bf16 v[94:97], v[234:237], v[180:183], v[94:97]
	v_mfma_f32_16x16x32_bf16 v[86:89], v[226:229], v[204:207], v[86:89]
	v_mfma_f32_16x16x32_bf16 v[78:81], v[234:237], v[204:207], v[78:81]
	v_mfma_f32_16x16x32_bf16 v[70:73], v[226:229], v[212:215], v[70:73]
	v_mfma_f32_16x16x32_bf16 v[66:69], v[234:237], v[212:215], v[66:69]
	s_setprio 0
	s_mov_b32 m0, s55
	s_barrier
	ds_read_b128 v[168:171], v152 offset:49152
	ds_read_b128 v[172:175], v152 offset:50176
	ds_read_b128 v[176:179], v152 offset:51200
	ds_read_b128 v[180:183], v152 offset:52224
	ds_read_b128 v[184:187], v152 offset:53248
	ds_read_b128 v[204:207], v152 offset:54272
	ds_read_b128 v[208:211], v152 offset:55296
	ds_read_b128 v[212:215], v152 offset:56320
	global_load_lds_dwordx4 v134, vcc
	s_mov_b32 m0, s83
	s_nop 0
	global_load_lds_dwordx4 v132, vcc
	s_barrier
	s_waitcnt lgkmcnt(0)
	s_setprio 1
	s_waitcnt lgkmcnt(0)
	v_mfma_f32_16x16x32_bf16 v[62:65], v[140:143], v[168:171], v[62:65]
	v_mfma_f32_16x16x32_bf16 v[58:61], v[154:157], v[168:171], v[58:61]
	v_mfma_f32_16x16x32_bf16 v[50:53], v[140:143], v[176:179], v[50:53]
	v_mfma_f32_16x16x32_bf16 v[42:45], v[154:157], v[176:179], v[42:45]
	v_mfma_f32_16x16x32_bf16 v[34:37], v[140:143], v[184:187], v[34:37]
	v_mfma_f32_16x16x32_bf16 v[26:29], v[154:157], v[184:187], v[26:29]
	v_mfma_f32_16x16x32_bf16 v[18:21], v[140:143], v[208:211], v[18:21]
	v_mfma_f32_16x16x32_bf16 v[10:13], v[154:157], v[208:211], v[10:13]
	v_mfma_f32_16x16x32_bf16 v[62:65], v[144:147], v[172:175], v[62:65]
	v_mfma_f32_16x16x32_bf16 v[58:61], v[158:161], v[172:175], v[58:61]
	v_mfma_f32_16x16x32_bf16 v[50:53], v[144:147], v[180:183], v[50:53]
	v_mfma_f32_16x16x32_bf16 v[42:45], v[158:161], v[180:183], v[42:45]
	v_mfma_f32_16x16x32_bf16 v[34:37], v[144:147], v[204:207], v[34:37]
	v_mfma_f32_16x16x32_bf16 v[26:29], v[158:161], v[204:207], v[26:29]
	v_mfma_f32_16x16x32_bf16 v[18:21], v[144:147], v[212:215], v[18:21]
	v_mfma_f32_16x16x32_bf16 v[10:13], v[158:161], v[212:215], v[10:13]
	s_setprio 0
	s_barrier
	s_add_u32 s6, s6, 0x40080
	s_addc_u32 s7, s7, 0
	s_add_i32 s36, s36, s44
	s_mov_b32 m0, s36
	s_nop 0
	global_load_lds_dwordx4 v0, s[6:7]
	s_add_i32 m0, s36, 0x2000
	s_nop 0
	global_load_lds_dwordx4 v130, s[6:7]
	s_waitcnt vmcnt(6)
	s_barrier
	s_setprio 1
	v_mfma_f32_16x16x32_bf16 v[54:57], v[216:219], v[168:171], v[54:57]
	v_mfma_f32_16x16x32_bf16 v[46:49], v[230:233], v[168:171], v[46:49]
	v_mfma_f32_16x16x32_bf16 v[38:41], v[216:219], v[176:179], v[38:41]
	v_mfma_f32_16x16x32_bf16 v[30:33], v[230:233], v[176:179], v[30:33]
	v_mfma_f32_16x16x32_bf16 v[22:25], v[216:219], v[184:187], v[22:25]
	v_mfma_f32_16x16x32_bf16 v[14:17], v[230:233], v[184:187], v[14:17]
	v_mfma_f32_16x16x32_bf16 v[6:9], v[216:219], v[208:211], v[6:9]
	v_mfma_f32_16x16x32_bf16 v[2:5], v[230:233], v[208:211], v[2:5]
	v_mfma_f32_16x16x32_bf16 v[54:57], v[226:229], v[172:175], v[54:57]
	v_mfma_f32_16x16x32_bf16 v[46:49], v[234:237], v[172:175], v[46:49]
	v_mfma_f32_16x16x32_bf16 v[38:41], v[226:229], v[180:183], v[38:41]
	v_mfma_f32_16x16x32_bf16 v[30:33], v[234:237], v[180:183], v[30:33]
	v_mfma_f32_16x16x32_bf16 v[22:25], v[226:229], v[204:207], v[22:25]
	v_mfma_f32_16x16x32_bf16 v[14:17], v[234:237], v[204:207], v[14:17]
	v_mfma_f32_16x16x32_bf16 v[6:9], v[226:229], v[212:215], v[6:9]
	v_mfma_f32_16x16x32_bf16 v[2:5], v[234:237], v[212:215], v[2:5]
	s_setprio 0
	s_add_i32 s91, s91, 2
	s_add_u32 s24, s24, 0x100
	s_addc_u32 s25, s25, 0
	s_add_u32 s89, s89, 0x100
	s_addc_u32 s90, s90, 0
	s_cmp_gt_u32 s91, 13
	s_barrier
; #define PG8_STAGE(bufoff, gbase, voff) do { _Pragma("unroll") for (int _i = 0; _i < 2; ++_i) \
;         __builtin_amdgcn_global_load_lds((const unsigned*)((const char*)(gbase) + (voff)[_i]), (LAS unsigned*)(lds + (bufoff) + ldsw + _i * 8192), 16, 0, 0); } while (0)
; #define PG8_LDA(dst, b, h) do { _Pragma("unroll") for (int m = 0; m < 4; ++m) _Pragma("unroll") for (int k = 0; k < 2; ++k) dst[m][k] = *(const LAS bf16x8*)(lds + PG8_SA(b, h) + aoff + m * 2048 + k * 1024); } while (0)
; #define PG8_LDB(dst, b, h) do { _Pragma("unroll") for (int n = 0; n < 2; ++n) _Pragma("unroll") for (int k = 0; k < 2; ++k) dst[n][k] = *(const LAS bf16x8*)(lds + PG8_SB(b, h) + boff + n * 2048 + k * 1024); } while (0)
; #define PG8_WAIT_V(n) asm volatile("s_waitcnt vmcnt(" #n ")" ::: "memory")
; #define PG8_WAIT_L(n) asm volatile("s_waitcnt lgkmcnt(" #n ")" ::: "memory")
; #define PG8_BAR __builtin_amdgcn_s_barrier()
; #define PG8_SCHED __builtin_amdgcn_sched_barrier(0)
; template <class Epi>
; __device__ __forceinline__ void gemm_phase(LAS unsigned char* lds, const Gemm g, const StaticOrder& S, const Epi& E) {
;     ...
;             PG8_LDB(B0, 0, 0); PG8_SCHED; PG8_LDA(At, 0, 0); PG8_STAGE(PG8_SA(1, 1), a1 + hstep, voffA);
;             PG8_WAIT_L(8); PG8_BAR; PG8_WAIT_L(0); PG8_MMA(0, 0, At, B0); PG8_BAR; PG8_SCHED;
;             PG8_LDB(B1, 0, 1); PG8_STAGE(PG8_SB(0, 0), b2, voffB);
;             PG8_BAR; PG8_WAIT_L(0); PG8_MMA(0, 1, At, B1); PG8_BAR;
;             PG8_LDA(At, 0, 1); PG8_STAGE(PG8_SA(0, 0), a2, voffA);
;             PG8_BAR; PG8_WAIT_L(0); PG8_MMA(1, 0, At, B0); PG8_BAR; PG8_SCHED;
;             PG8_STAGE(PG8_SB(0, 1), b2 + hstep, voffB);
;             PG8_WAIT_V(6); PG8_BAR; PG8_MMA(1, 1, At, B1); PG8_BAR;
;             PG8_LDB(B0, 1, 0); PG8_SCHED; PG8_LDA(At, 1, 0); PG8_STAGE(PG8_SA(0, 1), a2 + hstep, voffA);
;             PG8_WAIT_L(8); PG8_BAR; PG8_WAIT_L(0); PG8_MMA(0, 0, At, B0); PG8_BAR; PG8_SCHED;
;             PG8_LDB(B1, 1, 1); PG8_STAGE(PG8_SB(1, 0), b3, voffB);
;             PG8_BAR; PG8_WAIT_L(0); PG8_MMA(0, 1, At, B1); PG8_BAR;
;             PG8_LDA(At, 1, 1); PG8_STAGE(PG8_SA(1, 0), a3, voffA);
;             PG8_BAR; PG8_WAIT_L(0); PG8_MMA(1, 0, At, B0); PG8_BAR; PG8_SCHED;
;             PG8_STAGE(PG8_SB(1, 1), b3 + hstep, voffB);
;             PG8_WAIT_V(6); PG8_BAR; PG8_MMA(1, 1, At, B1); PG8_BAR;
	s_add_u32 s6, s24, 0xfffc0080
	s_addc_u32 s7, s25, -1
	s_add_i32 s58, 0, 0x10000
	v_add_u32_e32 v153, s58, v149
	ds_read_b128 v[140:143], v153
	ds_read_b128 v[144:147], v153 offset:1024
	ds_read_b128 v[154:157], v153 offset:2048
	ds_read_b128 v[158:161], v153 offset:3072
	s_cmp_eq_u32 s91, 12
	s_cselect_b32 s37, s11, s7
	s_cselect_b32 s36, s71, s6
	s_cselect_b32 s7, s9, s90
	s_cselect_b32 s6, s88, s89
	s_add_i32 m0, s47, 0xc000
	ds_read_b128 v[168:171], v152
	ds_read_b128 v[172:175], v152 offset:1024
	ds_read_b128 v[176:179], v152 offset:2048
	ds_read_b128 v[180:183], v152 offset:3072
	ds_read_b128 v[184:187], v152 offset:4096
	ds_read_b128 v[204:207], v152 offset:5120
	ds_read_b128 v[208:211], v152 offset:6144
	ds_read_b128 v[212:215], v152 offset:7168
	global_load_lds_dwordx4 v136, s[24:25]
	s_add_i32 m0, s47, 0xe000
	s_nop 0
	global_load_lds_dwordx4 v138, s[24:25]
	s_waitcnt lgkmcnt(8)
	s_barrier
	s_waitcnt lgkmcnt(0)
	s_setprio 1
	s_waitcnt lgkmcnt(0)
	v_mfma_f32_16x16x32_bf16 v[126:129], v[140:143], v[168:171], v[126:129]
	v_mfma_f32_16x16x32_bf16 v[122:125], v[154:157], v[168:171], v[122:125]
	v_mfma_f32_16x16x32_bf16 v[114:117], v[140:143], v[176:179], v[114:117]
	v_mfma_f32_16x16x32_bf16 v[106:109], v[154:157], v[176:179], v[106:109]
	v_mfma_f32_16x16x32_bf16 v[98:101], v[140:143], v[184:187], v[98:101]
	v_mfma_f32_16x16x32_bf16 v[90:93], v[154:157], v[184:187], v[90:93]
	v_mfma_f32_16x16x32_bf16 v[82:85], v[140:143], v[208:211], v[82:85]
	v_mfma_f32_16x16x32_bf16 v[74:77], v[154:157], v[208:211], v[74:77]
	v_mfma_f32_16x16x32_bf16 v[126:129], v[144:147], v[172:175], v[126:129]
	v_mfma_f32_16x16x32_bf16 v[122:125], v[158:161], v[172:175], v[122:125]
	v_mfma_f32_16x16x32_bf16 v[114:117], v[144:147], v[180:183], v[114:117]
	v_mfma_f32_16x16x32_bf16 v[106:109], v[158:161], v[180:183], v[106:109]
	v_mfma_f32_16x16x32_bf16 v[98:101], v[144:147], v[204:207], v[98:101]
	v_mfma_f32_16x16x32_bf16 v[90:93], v[158:161], v[204:207], v[90:93]
	v_mfma_f32_16x16x32_bf16 v[82:85], v[144:147], v[212:215], v[82:85]
	v_mfma_f32_16x16x32_bf16 v[74:77], v[158:161], v[212:215], v[74:77]
	s_setprio 0
	s_barrier
	s_add_i32 s70, 0, 0x14000
	s_add_i32 s58, s58, s44
	v_add_u32_e32 v153, s70, v149
	s_mov_b32 m0, s58
	ds_read_b128 v[216:219], v153
	ds_read_b128 v[226:229], v153 offset:1024
	ds_read_b128 v[230:233], v153 offset:2048
	ds_read_b128 v[234:237], v153 offset:3072
	global_load_lds_dwordx4 v0, s[6:7]
	s_add_i32 m0, s58, 0x2000
	s_nop 0
	global_load_lds_dwordx4 v130, s[6:7]
	s_barrier
	s_waitcnt lgkmcnt(0)
	s_setprio 1
	s_waitcnt lgkmcnt(0)
	v_mfma_f32_16x16x32_bf16 v[118:121], v[216:219], v[168:171], v[118:121]
	v_mfma_f32_16x16x32_bf16 v[110:113], v[230:233], v[168:171], v[110:113]
	v_mfma_f32_16x16x32_bf16 v[102:105], v[216:219], v[176:179], v[102:105]
	v_mfma_f32_16x16x32_bf16 v[94:97], v[230:233], v[176:179], v[94:97]
	v_mfma_f32_16x16x32_bf16 v[86:89], v[216:219], v[184:187], v[86:89]
	v_mfma_f32_16x16x32_bf16 v[78:81], v[230:233], v[184:187], v[78:81]
	v_mfma_f32_16x16x32_bf16 v[70:73], v[216:219], v[208:211], v[70:73]
	v_mfma_f32_16x16x32_bf16 v[66:69], v[230:233], v[208:211], v[66:69]
	v_mfma_f32_16x16x32_bf16 v[118:121], v[226:229], v[172:175], v[118:121]
	v_mfma_f32_16x16x32_bf16 v[110:113], v[234:237], v[172:175], v[110:113]
	v_mfma_f32_16x16x32_bf16 v[102:105], v[226:229], v[180:183], v[102:105]
	v_mfma_f32_16x16x32_bf16 v[94:97], v[234:237], v[180:183], v[94:97]
	v_mfma_f32_16x16x32_bf16 v[86:89], v[226:229], v[204:207], v[86:89]
	v_mfma_f32_16x16x32_bf16 v[78:81], v[234:237], v[204:207], v[78:81]
	v_mfma_f32_16x16x32_bf16 v[70:73], v[226:229], v[212:215], v[70:73]
	v_mfma_f32_16x16x32_bf16 v[66:69], v[234:237], v[212:215], v[66:69]
	s_setprio 0
	s_mov_b32 m0, s47
	s_add_u32 vcc_lo, s36, 0x80
	s_addc_u32 vcc_hi, s37, 0
	s_barrier
	ds_read_b128 v[168:171], v152 offset:16384
	ds_read_b128 v[172:175], v152 offset:17408
	ds_read_b128 v[176:179], v152 offset:18432
	ds_read_b128 v[180:183], v152 offset:19456
	ds_read_b128 v[184:187], v152 offset:20480
	ds_read_b128 v[204:207], v152 offset:21504
	ds_read_b128 v[208:211], v152 offset:22528
	ds_read_b128 v[212:215], v152 offset:23552
	global_load_lds_dwordx4 v134, s[36:37]
	s_mov_b32 m0, s48
	s_nop 0
	global_load_lds_dwordx4 v132, s[36:37]
	s_barrier
	s_waitcnt lgkmcnt(0)
	s_setprio 1
	s_waitcnt lgkmcnt(0)
	v_mfma_f32_16x16x32_bf16 v[62:65], v[140:143], v[168:171], v[62:65]
	v_mfma_f32_16x16x32_bf16 v[58:61], v[154:157], v[168:171], v[58:61]
	v_mfma_f32_16x16x32_bf16 v[50:53], v[140:143], v[176:179], v[50:53]
	v_mfma_f32_16x16x32_bf16 v[42:45], v[154:157], v[176:179], v[42:45]
	v_mfma_f32_16x16x32_bf16 v[34:37], v[140:143], v[184:187], v[34:37]
	v_mfma_f32_16x16x32_bf16 v[26:29], v[154:157], v[184:187], v[26:29]
	v_mfma_f32_16x16x32_bf16 v[18:21], v[140:143], v[208:211], v[18:21]
	v_mfma_f32_16x16x32_bf16 v[10:13], v[154:157], v[208:211], v[10:13]
	v_mfma_f32_16x16x32_bf16 v[62:65], v[144:147], v[172:175], v[62:65]
	v_mfma_f32_16x16x32_bf16 v[58:61], v[158:161], v[172:175], v[58:61]
	v_mfma_f32_16x16x32_bf16 v[50:53], v[144:147], v[180:183], v[50:53]
	v_mfma_f32_16x16x32_bf16 v[42:45], v[158:161], v[180:183], v[42:45]
	v_mfma_f32_16x16x32_bf16 v[34:37], v[144:147], v[204:207], v[34:37]
	v_mfma_f32_16x16x32_bf16 v[26:29], v[158:161], v[204:207], v[26:29]
	v_mfma_f32_16x16x32_bf16 v[18:21], v[144:147], v[212:215], v[18:21]
	v_mfma_f32_16x16x32_bf16 v[10:13], v[158:161], v[212:215], v[10:13]
	s_setprio 0
	s_barrier
	s_add_u32 s60, s6, 0x40000
	s_addc_u32 s61, s7, 0
	s_add_i32 s58, s70, s44
	s_mov_b32 m0, s58
	s_nop 0
	global_load_lds_dwordx4 v0, s[60:61]
	s_add_i32 m0, s58, 0x2000
	s_nop 0
	global_load_lds_dwordx4 v130, s[60:61]
	s_waitcnt vmcnt(6)
	s_barrier
	s_setprio 1
	v_mfma_f32_16x16x32_bf16 v[54:57], v[216:219], v[168:171], v[54:57]
	v_mfma_f32_16x16x32_bf16 v[46:49], v[230:233], v[168:171], v[46:49]
	s_cmp_eq_u32 s87, 0
	s_cbranch_scc1 .LdsA_skip_2
	global_store_dwordx4 v166, v[192:195], s[4:5]
; #define PG8_STAGE(bufoff, gbase, voff) do { _Pragma("unroll") for (int _i = 0; _i < 2; ++_i) \
;         __builtin_amdgcn_global_load_lds((const unsigned*)((const char*)(gbase) + (voff)[_i]), (LAS unsigned*)(lds + (bufoff) + ldsw + _i * 8192), 16, 0, 0); } while (0)
; #define PG8_LDA(dst, b, h) do { _Pragma("unroll") for (int m = 0; m < 4; ++m) _Pragma("unroll") for (int k = 0; k < 2; ++k) dst[m][k] = *(const LAS bf16x8*)(lds + PG8_SA(b, h) + aoff + m * 2048 + k * 1024); } while (0)
; #define PG8_LDB(dst, b, h) do { _Pragma("unroll") for (int n = 0; n < 2; ++n) _Pragma("unroll") for (int k = 0; k < 2; ++k) dst[n][k] = *(const LAS bf16x8*)(lds + PG8_SB(b, h) + boff + n * 2048 + k * 1024); } while (0)
; #define PG8_WAIT_V(n) asm volatile("s_waitcnt vmcnt(" #n ")" ::: "memory")
; #define PG8_WAIT_L(n) asm volatile("s_waitcnt lgkmcnt(" #n ")" ::: "memory")
; #define PG8_BAR __builtin_amdgcn_s_barrier()
; #define PG8_SCHED __builtin_amdgcn_sched_barrier(0)
; template <class Epi>
; __device__ __forceinline__ void gemm_phase(LAS unsigned char* lds, const Gemm g, const StaticOrder& S, const Epi& E) {
;     ...
;             PG8_LDB(B0, 0, 0); PG8_SCHED; PG8_LDA(At, 0, 0); PG8_STAGE(PG8_SA(1, 1), a1 + hstep, voffA);
;             PG8_WAIT_L(8); PG8_BAR; PG8_WAIT_L(0); PG8_MMA(0, 0, At, B0); PG8_BAR; PG8_SCHED;
;             PG8_LDB(B1, 0, 1); PG8_STAGE(PG8_SB(0, 0), b2, voffB);
;             PG8_BAR; PG8_WAIT_L(0); PG8_MMA(0, 1, At, B1); PG8_BAR;
;             PG8_LDA(At, 0, 1); PG8_STAGE(PG8_SA(0, 0), a2, voffA);
;             PG8_BAR; PG8_WAIT_L(0); PG8_MMA(1, 0, At, B0); PG8_BAR; PG8_SCHED;
;             PG8_STAGE(PG8_SB(0, 1), b2 + hstep, voffB);
;             PG8_WAIT_V(6); PG8_BAR; PG8_MMA(1, 1, At, B1); PG8_BAR;
;             PG8_LDB(B0, 1, 0); PG8_SCHED; PG8_LDA(At, 1, 0); PG8_STAGE(PG8_SA(0, 1), a2 + hstep, voffA);
;             PG8_WAIT_L(8); PG8_BAR; PG8_WAIT_L(0); PG8_MMA(0, 0, At, B0); PG8_BAR; PG8_SCHED;
;             PG8_LDB(B1, 1, 1); PG8_STAGE(PG8_SB(1, 0), b3, voffB);
;             PG8_BAR; PG8_WAIT_L(0); PG8_MMA(0, 1, At, B1); PG8_BAR;
;             PG8_LDA(At, 1, 1); PG8_STAGE(PG8_SA(1, 0), a3, voffA);
;             PG8_BAR; PG8_WAIT_L(0); PG8_MMA(1, 0, At, B0); PG8_BAR; PG8_SCHED;
;             PG8_STAGE(PG8_SB(1, 1), b3 + hstep, voffB);
;             PG8_WAIT_V(6); PG8_BAR; PG8_MMA(1, 1, At, B1); PG8_BAR;
.LdsA_skip_2:
	v_mfma_f32_16x16x32_bf16 v[38:41], v[216:219], v[176:179], v[38:41]
	v_mfma_f32_16x16x32_bf16 v[30:33], v[230:233], v[176:179], v[30:33]
	v_mfma_f32_16x16x32_bf16 v[22:25], v[216:219], v[184:187], v[22:25]
	v_mfma_f32_16x16x32_bf16 v[14:17], v[230:233], v[184:187], v[14:17]
	v_mfma_f32_16x16x32_bf16 v[6:9], v[216:219], v[208:211], v[6:9]
	v_mfma_f32_16x16x32_bf16 v[2:5], v[230:233], v[208:211], v[2:5]
	v_mfma_f32_16x16x32_bf16 v[54:57], v[226:229], v[172:175], v[54:57]
	v_mfma_f32_16x16x32_bf16 v[46:49], v[234:237], v[172:175], v[46:49]
	v_mfma_f32_16x16x32_bf16 v[38:41], v[226:229], v[180:183], v[38:41]
	v_mfma_f32_16x16x32_bf16 v[30:33], v[234:237], v[180:183], v[30:33]
	v_mfma_f32_16x16x32_bf16 v[22:25], v[226:229], v[204:207], v[22:25]
	v_mfma_f32_16x16x32_bf16 v[14:17], v[234:237], v[204:207], v[14:17]
	v_mfma_f32_16x16x32_bf16 v[6:9], v[226:229], v[212:215], v[6:9]
	v_mfma_f32_16x16x32_bf16 v[2:5], v[234:237], v[212:215], v[2:5]
	s_setprio 0
	s_add_i32 s58, 0, 0x18000
	v_add_u32_e32 v153, s58, v149
	s_barrier
	ds_read_b128 v[140:143], v153
	ds_read_b128 v[144:147], v153 offset:1024
	ds_read_b128 v[154:157], v153 offset:2048
	ds_read_b128 v[158:161], v153 offset:3072
	s_add_u32 s36, s36, 0x40000
	s_addc_u32 s37, s37, 0
	s_mov_b32 m0, s49
	ds_read_b128 v[168:171], v152 offset:32768
	ds_read_b128 v[172:175], v152 offset:33792
	ds_read_b128 v[176:179], v152 offset:34816
	ds_read_b128 v[180:183], v152 offset:35840
	ds_read_b128 v[184:187], v152 offset:36864
	ds_read_b128 v[204:207], v152 offset:37888
	ds_read_b128 v[208:211], v152 offset:38912
	ds_read_b128 v[212:215], v152 offset:39936
	global_load_lds_dwordx4 v134, s[36:37]
	s_mov_b32 m0, s54
	s_nop 0
	global_load_lds_dwordx4 v132, s[36:37]
	s_waitcnt lgkmcnt(8)
	s_barrier
	s_waitcnt lgkmcnt(0)
	s_setprio 1
	s_waitcnt lgkmcnt(0)
	v_mfma_f32_16x16x32_bf16 v[126:129], v[140:143], v[168:171], v[126:129]
	v_mfma_f32_16x16x32_bf16 v[122:125], v[154:157], v[168:171], v[122:125]
	v_mfma_f32_16x16x32_bf16 v[114:117], v[140:143], v[176:179], v[114:117]
	v_mfma_f32_16x16x32_bf16 v[106:109], v[154:157], v[176:179], v[106:109]
	v_mfma_f32_16x16x32_bf16 v[98:101], v[140:143], v[184:187], v[98:101]
	v_mfma_f32_16x16x32_bf16 v[90:93], v[154:157], v[184:187], v[90:93]
	v_mfma_f32_16x16x32_bf16 v[82:85], v[140:143], v[208:211], v[82:85]
	v_mfma_f32_16x16x32_bf16 v[74:77], v[154:157], v[208:211], v[74:77]
	v_mfma_f32_16x16x32_bf16 v[126:129], v[144:147], v[172:175], v[126:129]
	v_mfma_f32_16x16x32_bf16 v[122:125], v[158:161], v[172:175], v[122:125]
	v_mfma_f32_16x16x32_bf16 v[114:117], v[144:147], v[180:183], v[114:117]
	v_mfma_f32_16x16x32_bf16 v[106:109], v[158:161], v[180:183], v[106:109]
	v_mfma_f32_16x16x32_bf16 v[98:101], v[144:147], v[204:207], v[98:101]
	v_mfma_f32_16x16x32_bf16 v[90:93], v[158:161], v[204:207], v[90:93]
	v_mfma_f32_16x16x32_bf16 v[82:85], v[144:147], v[212:215], v[82:85]
	v_mfma_f32_16x16x32_bf16 v[74:77], v[158:161], v[212:215], v[74:77]
	s_setprio 0
	s_barrier
	s_add_i32 s36, 0, 0x1c000
	s_add_i32 s37, s58, s44
	v_add_u32_e32 v153, s36, v149
	s_add_u32 s60, s6, 0x80
	s_addc_u32 s61, s7, 0
	s_mov_b32 m0, s37
	ds_read_b128 v[216:219], v153
	ds_read_b128 v[226:229], v153 offset:1024
	ds_read_b128 v[230:233], v153 offset:2048
	ds_read_b128 v[234:237], v153 offset:3072
	global_load_lds_dwordx4 v0, s[60:61]
	s_add_i32 m0, s37, 0x2000
	s_nop 0
	global_load_lds_dwordx4 v130, s[60:61]
	s_barrier
	s_waitcnt lgkmcnt(0)
	s_setprio 1
	s_waitcnt lgkmcnt(0)
	v_mfma_f32_16x16x32_bf16 v[118:121], v[216:219], v[168:171], v[118:121]
	v_mfma_f32_16x16x32_bf16 v[110:113], v[230:233], v[168:171], v[110:113]
	v_mfma_f32_16x16x32_bf16 v[102:105], v[216:219], v[176:179], v[102:105]
	v_mfma_f32_16x16x32_bf16 v[94:97], v[230:233], v[176:179], v[94:97]
	v_mfma_f32_16x16x32_bf16 v[86:89], v[216:219], v[184:187], v[86:89]
	v_mfma_f32_16x16x32_bf16 v[78:81], v[230:233], v[184:187], v[78:81]
	v_mfma_f32_16x16x32_bf16 v[70:73], v[216:219], v[208:211], v[70:73]
	v_mfma_f32_16x16x32_bf16 v[66:69], v[230:233], v[208:211], v[66:69]
	v_mfma_f32_16x16x32_bf16 v[118:121], v[226:229], v[172:175], v[118:121]
	v_mfma_f32_16x16x32_bf16 v[110:113], v[234:237], v[172:175], v[110:113]
	v_mfma_f32_16x16x32_bf16 v[102:105], v[226:229], v[180:183], v[102:105]
	v_mfma_f32_16x16x32_bf16 v[94:97], v[234:237], v[180:183], v[94:97]
	v_mfma_f32_16x16x32_bf16 v[86:89], v[226:229], v[204:207], v[86:89]
	v_mfma_f32_16x16x32_bf16 v[78:81], v[234:237], v[204:207], v[78:81]
	v_mfma_f32_16x16x32_bf16 v[70:73], v[226:229], v[212:215], v[70:73]
	v_mfma_f32_16x16x32_bf16 v[66:69], v[234:237], v[212:215], v[66:69]
	s_setprio 0
	s_mov_b32 m0, s55
	s_barrier
	ds_read_b128 v[168:171], v152 offset:49152
	ds_read_b128 v[172:175], v152 offset:50176
	ds_read_b128 v[176:179], v152 offset:51200
	ds_read_b128 v[180:183], v152 offset:52224
	ds_read_b128 v[184:187], v152 offset:53248
	ds_read_b128 v[204:207], v152 offset:54272
	ds_read_b128 v[208:211], v152 offset:55296
	ds_read_b128 v[212:215], v152 offset:56320
	global_load_lds_dwordx4 v134, vcc
	s_mov_b32 m0, s83
	s_nop 0
	global_load_lds_dwordx4 v132, vcc
	s_barrier
; #define PG8_STAGE(bufoff, gbase, voff) do { _Pragma("unroll") for (int _i = 0; _i < 2; ++_i) \
;         __builtin_amdgcn_global_load_lds((const unsigned*)((const char*)(gbase) + (voff)[_i]), (LAS unsigned*)(lds + (bufoff) + ldsw + _i * 8192), 16, 0, 0); } while (0)
; #define PG8_LDA(dst, b, h) do { _Pragma("unroll") for (int m = 0; m < 4; ++m) _Pragma("unroll") for (int k = 0; k < 2; ++k) dst[m][k] = *(const LAS bf16x8*)(lds + PG8_SA(b, h) + aoff + m * 2048 + k * 1024); } while (0)
; #define PG8_LDB(dst, b, h) do { _Pragma("unroll") for (int n = 0; n < 2; ++n) _Pragma("unroll") for (int k = 0; k < 2; ++k) dst[n][k] = *(const LAS bf16x8*)(lds + PG8_SB(b, h) + boff + n * 2048 + k * 1024); } while (0)
; #define PG8_WAIT_V(n) asm volatile("s_waitcnt vmcnt(" #n ")" ::: "memory")
; #define PG8_WAIT_L(n) asm volatile("s_waitcnt lgkmcnt(" #n ")" ::: "memory")
; #define PG8_BAR __builtin_amdgcn_s_barrier()
; #define PG8_SCHED __builtin_amdgcn_sched_barrier(0)
; template <class Epi>
; __device__ __forceinline__ void gemm_phase(LAS unsigned char* lds, const Gemm g, const StaticOrder& S, const Epi& E) {
;     ...
;             PG8_LDB(B0, 0, 0); PG8_SCHED; PG8_LDA(At, 0, 0); PG8_STAGE(PG8_SA(1, 1), a1 + hstep, voffA);
;             PG8_WAIT_L(8); PG8_BAR; PG8_WAIT_L(0); PG8_MMA(0, 0, At, B0); PG8_BAR; PG8_SCHED;
;             PG8_LDB(B1, 0, 1); PG8_STAGE(PG8_SB(0, 0), b2, voffB);
;             PG8_BAR; PG8_WAIT_L(0); PG8_MMA(0, 1, At, B1); PG8_BAR;
;             PG8_LDA(At, 0, 1); PG8_STAGE(PG8_SA(0, 0), a2, voffA);
;             PG8_BAR; PG8_WAIT_L(0); PG8_MMA(1, 0, At, B0); PG8_BAR; PG8_SCHED;
;             PG8_STAGE(PG8_SB(0, 1), b2 + hstep, voffB);
;             PG8_WAIT_V(6); PG8_BAR; PG8_MMA(1, 1, At, B1); PG8_BAR;
;             PG8_LDB(B0, 1, 0); PG8_SCHED; PG8_LDA(At, 1, 0); PG8_STAGE(PG8_SA(0, 1), a2 + hstep, voffA);
;             PG8_WAIT_L(8); PG8_BAR; PG8_WAIT_L(0); PG8_MMA(0, 0, At, B0); PG8_BAR; PG8_SCHED;
;             PG8_LDB(B1, 1, 1); PG8_STAGE(PG8_SB(1, 0), b3, voffB);
;             PG8_BAR; PG8_WAIT_L(0); PG8_MMA(0, 1, At, B1); PG8_BAR;
;             PG8_LDA(At, 1, 1); PG8_STAGE(PG8_SA(1, 0), a3, voffA);
;             PG8_BAR; PG8_WAIT_L(0); PG8_MMA(1, 0, At, B0); PG8_BAR; PG8_SCHED;
;             PG8_STAGE(PG8_SB(1, 1), b3 + hstep, voffB);
;             PG8_WAIT_V(6); PG8_BAR; PG8_MMA(1, 1, At, B1); PG8_BAR;
	s_waitcnt lgkmcnt(0)
	s_setprio 1
	s_waitcnt lgkmcnt(0)
	v_mfma_f32_16x16x32_bf16 v[62:65], v[140:143], v[168:171], v[62:65]
	v_mfma_f32_16x16x32_bf16 v[58:61], v[154:157], v[168:171], v[58:61]
	v_mfma_f32_16x16x32_bf16 v[50:53], v[140:143], v[176:179], v[50:53]
	v_mfma_f32_16x16x32_bf16 v[42:45], v[154:157], v[176:179], v[42:45]
	v_mfma_f32_16x16x32_bf16 v[34:37], v[140:143], v[184:187], v[34:37]
	v_mfma_f32_16x16x32_bf16 v[26:29], v[154:157], v[184:187], v[26:29]
	v_mfma_f32_16x16x32_bf16 v[18:21], v[140:143], v[208:211], v[18:21]
	v_mfma_f32_16x16x32_bf16 v[10:13], v[154:157], v[208:211], v[10:13]
	v_mfma_f32_16x16x32_bf16 v[62:65], v[144:147], v[172:175], v[62:65]
	v_mfma_f32_16x16x32_bf16 v[58:61], v[158:161], v[172:175], v[58:61]
	v_mfma_f32_16x16x32_bf16 v[50:53], v[144:147], v[180:183], v[50:53]
	v_mfma_f32_16x16x32_bf16 v[42:45], v[158:161], v[180:183], v[42:45]
	v_mfma_f32_16x16x32_bf16 v[34:37], v[144:147], v[204:207], v[34:37]
	v_mfma_f32_16x16x32_bf16 v[26:29], v[158:161], v[204:207], v[26:29]
	v_mfma_f32_16x16x32_bf16 v[18:21], v[144:147], v[212:215], v[18:21]
	v_mfma_f32_16x16x32_bf16 v[10:13], v[158:161], v[212:215], v[10:13]
	s_setprio 0
	s_barrier
	s_add_u32 s6, s6, 0x40080
	s_addc_u32 s7, s7, 0
	s_add_i32 s36, s36, s44
	s_mov_b32 m0, s36
	s_nop 0
	global_load_lds_dwordx4 v0, s[6:7]
	s_add_i32 m0, s36, 0x2000
	s_nop 0
	global_load_lds_dwordx4 v130, s[6:7]
	s_waitcnt vmcnt(6)
	s_barrier
	s_setprio 1
	v_mfma_f32_16x16x32_bf16 v[54:57], v[216:219], v[168:171], v[54:57]
	v_mfma_f32_16x16x32_bf16 v[46:49], v[230:233], v[168:171], v[46:49]
	v_mfma_f32_16x16x32_bf16 v[38:41], v[216:219], v[176:179], v[38:41]
	v_mfma_f32_16x16x32_bf16 v[30:33], v[230:233], v[176:179], v[30:33]
	v_mfma_f32_16x16x32_bf16 v[22:25], v[216:219], v[184:187], v[22:25]
	v_mfma_f32_16x16x32_bf16 v[14:17], v[230:233], v[184:187], v[14:17]
	v_mfma_f32_16x16x32_bf16 v[6:9], v[216:219], v[208:211], v[6:9]
	v_mfma_f32_16x16x32_bf16 v[2:5], v[230:233], v[208:211], v[2:5]
	v_mfma_f32_16x16x32_bf16 v[54:57], v[226:229], v[172:175], v[54:57]
	v_mfma_f32_16x16x32_bf16 v[46:49], v[234:237], v[172:175], v[46:49]
	v_mfma_f32_16x16x32_bf16 v[38:41], v[226:229], v[180:183], v[38:41]
	v_mfma_f32_16x16x32_bf16 v[30:33], v[234:237], v[180:183], v[30:33]
	v_mfma_f32_16x16x32_bf16 v[22:25], v[226:229], v[204:207], v[22:25]
	v_mfma_f32_16x16x32_bf16 v[14:17], v[234:237], v[204:207], v[14:17]
	v_mfma_f32_16x16x32_bf16 v[6:9], v[226:229], v[212:215], v[6:9]
	v_mfma_f32_16x16x32_bf16 v[2:5], v[234:237], v[212:215], v[2:5]
	s_setprio 0
	s_add_i32 s91, s91, 2
	s_add_u32 s24, s24, 0x100
	s_addc_u32 s25, s25, 0
	s_add_u32 s89, s89, 0x100
	s_addc_u32 s90, s90, 0
	s_cmp_gt_u32 s91, 13
	s_barrier
	s_add_u32 s6, s24, 0xfffc0080
	s_addc_u32 s7, s25, -1
	s_add_i32 s58, 0, 0x10000
	v_add_u32_e32 v153, s58, v149
	ds_read_b128 v[140:143], v153
	ds_read_b128 v[144:147], v153 offset:1024
	ds_read_b128 v[154:157], v153 offset:2048
	ds_read_b128 v[158:161], v153 offset:3072
	s_cmp_eq_u32 s91, 12
	s_cselect_b32 s37, s11, s7
	s_cselect_b32 s36, s71, s6
	s_cselect_b32 s7, s9, s90
	s_cselect_b32 s6, s88, s89
	s_add_i32 m0, s47, 0xc000
	ds_read_b128 v[168:171], v152
	ds_read_b128 v[172:175], v152 offset:1024
	ds_read_b128 v[176:179], v152 offset:2048
	ds_read_b128 v[180:183], v152 offset:3072
	ds_read_b128 v[184:187], v152 offset:4096
	ds_read_b128 v[204:207], v152 offset:5120
	ds_read_b128 v[208:211], v152 offset:6144
	ds_read_b128 v[212:215], v152 offset:7168
	global_load_lds_dwordx4 v136, s[24:25]
	s_add_i32 m0, s47, 0xe000
	s_nop 0
	global_load_lds_dwordx4 v138, s[24:25]
	s_waitcnt lgkmcnt(8)
	s_barrier
	s_waitcnt lgkmcnt(0)
	s_setprio 1
	s_waitcnt lgkmcnt(0)
	v_mfma_f32_16x16x32_bf16 v[126:129], v[140:143], v[168:171], v[126:129]
	v_mfma_f32_16x16x32_bf16 v[122:125], v[154:157], v[168:171], v[122:125]
	v_mfma_f32_16x16x32_bf16 v[114:117], v[140:143], v[176:179], v[114:117]
	v_mfma_f32_16x16x32_bf16 v[106:109], v[154:157], v[176:179], v[106:109]
	v_mfma_f32_16x16x32_bf16 v[98:101], v[140:143], v[184:187], v[98:101]
	v_mfma_f32_16x16x32_bf16 v[90:93], v[154:157], v[184:187], v[90:93]
	v_mfma_f32_16x16x32_bf16 v[82:85], v[140:143], v[208:211], v[82:85]
	v_mfma_f32_16x16x32_bf16 v[74:77], v[154:157], v[208:211], v[74:77]
	v_mfma_f32_16x16x32_bf16 v[126:129], v[144:147], v[172:175], v[126:129]
	v_mfma_f32_16x16x32_bf16 v[122:125], v[158:161], v[172:175], v[122:125]
	v_mfma_f32_16x16x32_bf16 v[114:117], v[144:147], v[180:183], v[114:117]
	v_mfma_f32_16x16x32_bf16 v[106:109], v[158:161], v[180:183], v[106:109]
	v_mfma_f32_16x16x32_bf16 v[98:101], v[144:147], v[204:207], v[98:101]
	v_mfma_f32_16x16x32_bf16 v[90:93], v[158:161], v[204:207], v[90:93]
	v_mfma_f32_16x16x32_bf16 v[82:85], v[144:147], v[212:215], v[82:85]
	v_mfma_f32_16x16x32_bf16 v[74:77], v[158:161], v[212:215], v[74:77]
	s_setprio 0
	s_barrier
	s_add_i32 s70, 0, 0x14000
	s_add_i32 s58, s58, s44
	v_add_u32_e32 v153, s70, v149
	s_mov_b32 m0, s58
	ds_read_b128 v[216:219], v153
	ds_read_b128 v[226:229], v153 offset:1024
	ds_read_b128 v[230:233], v153 offset:2048
	ds_read_b128 v[234:237], v153 offset:3072
	global_load_lds_dwordx4 v0, s[6:7]
	s_add_i32 m0, s58, 0x2000
	s_nop 0
	global_load_lds_dwordx4 v130, s[6:7]
	s_barrier
; #define PG8_STAGE(bufoff, gbase, voff) do { _Pragma("unroll") for (int _i = 0; _i < 2; ++_i) \
;         __builtin_amdgcn_global_load_lds((const unsigned*)((const char*)(gbase) + (voff)[_i]), (LAS unsigned*)(lds + (bufoff) + ldsw + _i * 8192), 16, 0, 0); } while (0)
; #define PG8_LDA(dst, b, h) do { _Pragma("unroll") for (int m = 0; m < 4; ++m) _Pragma("unroll") for (int k = 0; k < 2; ++k) dst[m][k] = *(const LAS bf16x8*)(lds + PG8_SA(b, h) + aoff + m * 2048 + k * 1024); } while (0)
; #define PG8_LDB(dst, b, h) do { _Pragma("unroll") for (int n = 0; n < 2; ++n) _Pragma("unroll") for (int k = 0; k < 2; ++k) dst[n][k] = *(const LAS bf16x8*)(lds + PG8_SB(b, h) + boff + n * 2048 + k * 1024); } while (0)
; #define PG8_WAIT_V(n) asm volatile("s_waitcnt vmcnt(" #n ")" ::: "memory")
; #define PG8_WAIT_L(n) asm volatile("s_waitcnt lgkmcnt(" #n ")" ::: "memory")
; #define PG8_BAR __builtin_amdgcn_s_barrier()
; #define PG8_SCHED __builtin_amdgcn_sched_barrier(0)
; template <class Epi>
; __device__ __forceinline__ void gemm_phase(LAS unsigned char* lds, const Gemm g, const StaticOrder& S, const Epi& E) {
;     ...
;             PG8_LDB(B0, 0, 0); PG8_SCHED; PG8_LDA(At, 0, 0); PG8_STAGE(PG8_SA(1, 1), a1 + hstep, voffA);
;             PG8_WAIT_L(8); PG8_BAR; PG8_WAIT_L(0); PG8_MMA(0, 0, At, B0); PG8_BAR; PG8_SCHED;
;             PG8_LDB(B1, 0, 1); PG8_STAGE(PG8_SB(0, 0), b2, voffB);
;             PG8_BAR; PG8_WAIT_L(0); PG8_MMA(0, 1, At, B1); PG8_BAR;
;             PG8_LDA(At, 0, 1); PG8_STAGE(PG8_SA(0, 0), a2, voffA);
;             PG8_BAR; PG8_WAIT_L(0); PG8_MMA(1, 0, At, B0); PG8_BAR; PG8_SCHED;
;             PG8_STAGE(PG8_SB(0, 1), b2 + hstep, voffB);
;             PG8_WAIT_V(6); PG8_BAR; PG8_MMA(1, 1, At, B1); PG8_BAR;
;             PG8_LDB(B0, 1, 0); PG8_SCHED; PG8_LDA(At, 1, 0); PG8_STAGE(PG8_SA(0, 1), a2 + hstep, voffA);
;             PG8_WAIT_L(8); PG8_BAR; PG8_WAIT_L(0); PG8_MMA(0, 0, At, B0); PG8_BAR; PG8_SCHED;
;             PG8_LDB(B1, 1, 1); PG8_STAGE(PG8_SB(1, 0), b3, voffB);
;             PG8_BAR; PG8_WAIT_L(0); PG8_MMA(0, 1, At, B1); PG8_BAR;
;             PG8_LDA(At, 1, 1); PG8_STAGE(PG8_SA(1, 0), a3, voffA);
;             PG8_BAR; PG8_WAIT_L(0); PG8_MMA(1, 0, At, B0); PG8_BAR; PG8_SCHED;
;             PG8_STAGE(PG8_SB(1, 1), b3 + hstep, voffB);
;             PG8_WAIT_V(6); PG8_BAR; PG8_MMA(1, 1, At, B1); PG8_BAR;
	s_waitcnt lgkmcnt(0)
	s_setprio 1
	s_waitcnt lgkmcnt(0)
	v_mfma_f32_16x16x32_bf16 v[118:121], v[216:219], v[168:171], v[118:121]
	v_mfma_f32_16x16x32_bf16 v[110:113], v[230:233], v[168:171], v[110:113]
	v_mfma_f32_16x16x32_bf16 v[102:105], v[216:219], v[176:179], v[102:105]
	v_mfma_f32_16x16x32_bf16 v[94:97], v[230:233], v[176:179], v[94:97]
	v_mfma_f32_16x16x32_bf16 v[86:89], v[216:219], v[184:187], v[86:89]
	v_mfma_f32_16x16x32_bf16 v[78:81], v[230:233], v[184:187], v[78:81]
	v_mfma_f32_16x16x32_bf16 v[70:73], v[216:219], v[208:211], v[70:73]
	v_mfma_f32_16x16x32_bf16 v[66:69], v[230:233], v[208:211], v[66:69]
	v_mfma_f32_16x16x32_bf16 v[118:121], v[226:229], v[172:175], v[118:121]
	v_mfma_f32_16x16x32_bf16 v[110:113], v[234:237], v[172:175], v[110:113]
	v_mfma_f32_16x16x32_bf16 v[102:105], v[226:229], v[180:183], v[102:105]
	v_mfma_f32_16x16x32_bf16 v[94:97], v[234:237], v[180:183], v[94:97]
	v_mfma_f32_16x16x32_bf16 v[86:89], v[226:229], v[204:207], v[86:89]
	v_mfma_f32_16x16x32_bf16 v[78:81], v[234:237], v[204:207], v[78:81]
	v_mfma_f32_16x16x32_bf16 v[70:73], v[226:229], v[212:215], v[70:73]
	v_mfma_f32_16x16x32_bf16 v[66:69], v[234:237], v[212:215], v[66:69]
	s_setprio 0
	s_mov_b32 m0, s47
	s_add_u32 vcc_lo, s36, 0x80
	s_addc_u32 vcc_hi, s37, 0
	s_barrier
	ds_read_b128 v[168:171], v152 offset:16384
	ds_read_b128 v[172:175], v152 offset:17408
	ds_read_b128 v[176:179], v152 offset:18432
	ds_read_b128 v[180:183], v152 offset:19456
	ds_read_b128 v[184:187], v152 offset:20480
	ds_read_b128 v[204:207], v152 offset:21504
	ds_read_b128 v[208:211], v152 offset:22528
	ds_read_b128 v[212:215], v152 offset:23552
	global_load_lds_dwordx4 v134, s[36:37]
	s_mov_b32 m0, s48
	s_nop 0
	global_load_lds_dwordx4 v132, s[36:37]
	s_barrier
	s_waitcnt lgkmcnt(0)
	s_setprio 1
	s_waitcnt lgkmcnt(0)
	v_mfma_f32_16x16x32_bf16 v[62:65], v[140:143], v[168:171], v[62:65]
	v_mfma_f32_16x16x32_bf16 v[58:61], v[154:157], v[168:171], v[58:61]
	v_mfma_f32_16x16x32_bf16 v[50:53], v[140:143], v[176:179], v[50:53]
	v_mfma_f32_16x16x32_bf16 v[42:45], v[154:157], v[176:179], v[42:45]
	v_mfma_f32_16x16x32_bf16 v[34:37], v[140:143], v[184:187], v[34:37]
	v_mfma_f32_16x16x32_bf16 v[26:29], v[154:157], v[184:187], v[26:29]
	v_mfma_f32_16x16x32_bf16 v[18:21], v[140:143], v[208:211], v[18:21]
	v_mfma_f32_16x16x32_bf16 v[10:13], v[154:157], v[208:211], v[10:13]
	v_mfma_f32_16x16x32_bf16 v[62:65], v[144:147], v[172:175], v[62:65]
	v_mfma_f32_16x16x32_bf16 v[58:61], v[158:161], v[172:175], v[58:61]
	v_mfma_f32_16x16x32_bf16 v[50:53], v[144:147], v[180:183], v[50:53]
	v_mfma_f32_16x16x32_bf16 v[42:45], v[158:161], v[180:183], v[42:45]
	v_mfma_f32_16x16x32_bf16 v[34:37], v[144:147], v[204:207], v[34:37]
	v_mfma_f32_16x16x32_bf16 v[26:29], v[158:161], v[204:207], v[26:29]
	v_mfma_f32_16x16x32_bf16 v[18:21], v[144:147], v[212:215], v[18:21]
	v_mfma_f32_16x16x32_bf16 v[10:13], v[158:161], v[212:215], v[10:13]
	s_setprio 0
	s_barrier
	s_add_u32 s60, s6, 0x40000
	s_addc_u32 s61, s7, 0
	s_add_i32 s58, s70, s44
	s_mov_b32 m0, s58
	s_nop 0
	global_load_lds_dwordx4 v0, s[60:61]
	s_add_i32 m0, s58, 0x2000
	s_nop 0
	global_load_lds_dwordx4 v130, s[60:61]
	s_waitcnt vmcnt(6)
	s_barrier
	s_setprio 1
	v_mfma_f32_16x16x32_bf16 v[54:57], v[216:219], v[168:171], v[54:57]
	v_mfma_f32_16x16x32_bf16 v[46:49], v[230:233], v[168:171], v[46:49]
	s_cmp_eq_u32 s87, 0
	s_cbranch_scc1 .LdsA_skip_3
	global_store_dwordx4 v166, v[196:199], s[4:5] offset:256
	v_add_u32_e32 v166, 0xe000, v166
.LdsA_skip_3:
	v_mfma_f32_16x16x32_bf16 v[38:41], v[216:219], v[176:179], v[38:41]
	v_mfma_f32_16x16x32_bf16 v[30:33], v[230:233], v[176:179], v[30:33]
	v_mfma_f32_16x16x32_bf16 v[22:25], v[216:219], v[184:187], v[22:25]
	v_mfma_f32_16x16x32_bf16 v[14:17], v[230:233], v[184:187], v[14:17]
	v_mfma_f32_16x16x32_bf16 v[6:9], v[216:219], v[208:211], v[6:9]
	v_mfma_f32_16x16x32_bf16 v[2:5], v[230:233], v[208:211], v[2:5]
	v_mfma_f32_16x16x32_bf16 v[54:57], v[226:229], v[172:175], v[54:57]
	v_mfma_f32_16x16x32_bf16 v[46:49], v[234:237], v[172:175], v[46:49]
	v_mfma_f32_16x16x32_bf16 v[38:41], v[226:229], v[180:183], v[38:41]
	v_mfma_f32_16x16x32_bf16 v[30:33], v[234:237], v[180:183], v[30:33]
	v_mfma_f32_16x16x32_bf16 v[22:25], v[226:229], v[204:207], v[22:25]
	v_mfma_f32_16x16x32_bf16 v[14:17], v[234:237], v[204:207], v[14:17]
	v_mfma_f32_16x16x32_bf16 v[6:9], v[226:229], v[212:215], v[6:9]
	v_mfma_f32_16x16x32_bf16 v[2:5], v[234:237], v[212:215], v[2:5]
	s_setprio 0
	s_add_i32 s58, 0, 0x18000
	v_add_u32_e32 v153, s58, v149
	s_barrier
	ds_read_b128 v[140:143], v153
	ds_read_b128 v[144:147], v153 offset:1024
	ds_read_b128 v[154:157], v153 offset:2048
	ds_read_b128 v[158:161], v153 offset:3072
	s_add_u32 s36, s36, 0x40000
	s_addc_u32 s37, s37, 0
	s_mov_b32 m0, s49
	ds_read_b128 v[168:171], v152 offset:32768
	ds_read_b128 v[172:175], v152 offset:33792
	ds_read_b128 v[176:179], v152 offset:34816
	ds_read_b128 v[180:183], v152 offset:35840
	ds_read_b128 v[184:187], v152 offset:36864
	ds_read_b128 v[204:207], v152 offset:37888
	ds_read_b128 v[208:211], v152 offset:38912
	ds_read_b128 v[212:215], v152 offset:39936
	global_load_lds_dwordx4 v134, s[36:37]
	s_mov_b32 m0, s54
	s_nop 0
	global_load_lds_dwordx4 v132, s[36:37]
	s_waitcnt lgkmcnt(8)
	s_barrier
; #define PG8_STAGE(bufoff, gbase, voff) do { _Pragma("unroll") for (int _i = 0; _i < 2; ++_i) \
;         __builtin_amdgcn_global_load_lds((const unsigned*)((const char*)(gbase) + (voff)[_i]), (LAS unsigned*)(lds + (bufoff) + ldsw + _i * 8192), 16, 0, 0); } while (0)
; #define PG8_LDA(dst, b, h) do { _Pragma("unroll") for (int m = 0; m < 4; ++m) _Pragma("unroll") for (int k = 0; k < 2; ++k) dst[m][k] = *(const LAS bf16x8*)(lds + PG8_SA(b, h) + aoff + m * 2048 + k * 1024); } while (0)
; #define PG8_LDB(dst, b, h) do { _Pragma("unroll") for (int n = 0; n < 2; ++n) _Pragma("unroll") for (int k = 0; k < 2; ++k) dst[n][k] = *(const LAS bf16x8*)(lds + PG8_SB(b, h) + boff + n * 2048 + k * 1024); } while (0)
; #define PG8_WAIT_V(n) asm volatile("s_waitcnt vmcnt(" #n ")" ::: "memory")
; #define PG8_WAIT_L(n) asm volatile("s_waitcnt lgkmcnt(" #n ")" ::: "memory")
; #define PG8_BAR __builtin_amdgcn_s_barrier()
; #define PG8_SCHED __builtin_amdgcn_sched_barrier(0)
; template <class Epi>
; __device__ __forceinline__ void gemm_phase(LAS unsigned char* lds, const Gemm g, const StaticOrder& S, const Epi& E) {
;     ...
;             PG8_LDB(B0, 0, 0); PG8_SCHED; PG8_LDA(At, 0, 0); PG8_STAGE(PG8_SA(1, 1), a1 + hstep, voffA);
;             PG8_WAIT_L(8); PG8_BAR; PG8_WAIT_L(0); PG8_MMA(0, 0, At, B0); PG8_BAR; PG8_SCHED;
;             PG8_LDB(B1, 0, 1); PG8_STAGE(PG8_SB(0, 0), b2, voffB);
;             PG8_BAR; PG8_WAIT_L(0); PG8_MMA(0, 1, At, B1); PG8_BAR;
;             PG8_LDA(At, 0, 1); PG8_STAGE(PG8_SA(0, 0), a2, voffA);
;             PG8_BAR; PG8_WAIT_L(0); PG8_MMA(1, 0, At, B0); PG8_BAR; PG8_SCHED;
;             PG8_STAGE(PG8_SB(0, 1), b2 + hstep, voffB);
;             PG8_WAIT_V(6); PG8_BAR; PG8_MMA(1, 1, At, B1); PG8_BAR;
;             PG8_LDB(B0, 1, 0); PG8_SCHED; PG8_LDA(At, 1, 0); PG8_STAGE(PG8_SA(0, 1), a2 + hstep, voffA);
;             PG8_WAIT_L(8); PG8_BAR; PG8_WAIT_L(0); PG8_MMA(0, 0, At, B0); PG8_BAR; PG8_SCHED;
;             PG8_LDB(B1, 1, 1); PG8_STAGE(PG8_SB(1, 0), b3, voffB);
;             PG8_BAR; PG8_WAIT_L(0); PG8_MMA(0, 1, At, B1); PG8_BAR;
;             PG8_LDA(At, 1, 1); PG8_STAGE(PG8_SA(1, 0), a3, voffA);
;             PG8_BAR; PG8_WAIT_L(0); PG8_MMA(1, 0, At, B0); PG8_BAR; PG8_SCHED;
;             PG8_STAGE(PG8_SB(1, 1), b3 + hstep, voffB);
;             PG8_WAIT_V(6); PG8_BAR; PG8_MMA(1, 1, At, B1); PG8_BAR;
	s_waitcnt lgkmcnt(0)
	s_setprio 1
	s_waitcnt lgkmcnt(0)
	v_mfma_f32_16x16x32_bf16 v[126:129], v[140:143], v[168:171], v[126:129]
	v_mfma_f32_16x16x32_bf16 v[122:125], v[154:157], v[168:171], v[122:125]
	v_mfma_f32_16x16x32_bf16 v[114:117], v[140:143], v[176:179], v[114:117]
	v_mfma_f32_16x16x32_bf16 v[106:109], v[154:157], v[176:179], v[106:109]
	v_mfma_f32_16x16x32_bf16 v[98:101], v[140:143], v[184:187], v[98:101]
	v_mfma_f32_16x16x32_bf16 v[90:93], v[154:157], v[184:187], v[90:93]
	v_mfma_f32_16x16x32_bf16 v[82:85], v[140:143], v[208:211], v[82:85]
	v_mfma_f32_16x16x32_bf16 v[74:77], v[154:157], v[208:211], v[74:77]
	v_mfma_f32_16x16x32_bf16 v[126:129], v[144:147], v[172:175], v[126:129]
	v_mfma_f32_16x16x32_bf16 v[122:125], v[158:161], v[172:175], v[122:125]
	v_mfma_f32_16x16x32_bf16 v[114:117], v[144:147], v[180:183], v[114:117]
	v_mfma_f32_16x16x32_bf16 v[106:109], v[158:161], v[180:183], v[106:109]
	v_mfma_f32_16x16x32_bf16 v[98:101], v[144:147], v[204:207], v[98:101]
	v_mfma_f32_16x16x32_bf16 v[90:93], v[158:161], v[204:207], v[90:93]
	v_mfma_f32_16x16x32_bf16 v[82:85], v[144:147], v[212:215], v[82:85]
	v_mfma_f32_16x16x32_bf16 v[74:77], v[158:161], v[212:215], v[74:77]
	s_setprio 0
	s_barrier
	s_add_i32 s36, 0, 0x1c000
	s_add_i32 s37, s58, s44
	v_add_u32_e32 v153, s36, v149
	s_add_u32 s60, s6, 0x80
	s_addc_u32 s61, s7, 0
	s_mov_b32 m0, s37
	ds_read_b128 v[216:219], v153
	ds_read_b128 v[226:229], v153 offset:1024
	ds_read_b128 v[230:233], v153 offset:2048
	ds_read_b128 v[234:237], v153 offset:3072
	global_load_lds_dwordx4 v0, s[60:61]
	s_add_i32 m0, s37, 0x2000
	s_nop 0
	global_load_lds_dwordx4 v130, s[60:61]
	s_barrier
	s_waitcnt lgkmcnt(0)
	s_setprio 1
	s_waitcnt lgkmcnt(0)
	v_mfma_f32_16x16x32_bf16 v[118:121], v[216:219], v[168:171], v[118:121]
	v_mfma_f32_16x16x32_bf16 v[110:113], v[230:233], v[168:171], v[110:113]
	v_mfma_f32_16x16x32_bf16 v[102:105], v[216:219], v[176:179], v[102:105]
	v_mfma_f32_16x16x32_bf16 v[94:97], v[230:233], v[176:179], v[94:97]
	v_mfma_f32_16x16x32_bf16 v[86:89], v[216:219], v[184:187], v[86:89]
	v_mfma_f32_16x16x32_bf16 v[78:81], v[230:233], v[184:187], v[78:81]
	v_mfma_f32_16x16x32_bf16 v[70:73], v[216:219], v[208:211], v[70:73]
	v_mfma_f32_16x16x32_bf16 v[66:69], v[230:233], v[208:211], v[66:69]
	v_mfma_f32_16x16x32_bf16 v[118:121], v[226:229], v[172:175], v[118:121]
	v_mfma_f32_16x16x32_bf16 v[110:113], v[234:237], v[172:175], v[110:113]
	v_mfma_f32_16x16x32_bf16 v[102:105], v[226:229], v[180:183], v[102:105]
	v_mfma_f32_16x16x32_bf16 v[94:97], v[234:237], v[180:183], v[94:97]
	v_mfma_f32_16x16x32_bf16 v[86:89], v[226:229], v[204:207], v[86:89]
	v_mfma_f32_16x16x32_bf16 v[78:81], v[234:237], v[204:207], v[78:81]
	v_mfma_f32_16x16x32_bf16 v[70:73], v[226:229], v[212:215], v[70:73]
	v_mfma_f32_16x16x32_bf16 v[66:69], v[234:237], v[212:215], v[66:69]
	s_setprio 0
	s_mov_b32 m0, s55
	s_barrier
	ds_read_b128 v[168:171], v152 offset:49152
	ds_read_b128 v[172:175], v152 offset:50176
	ds_read_b128 v[176:179], v152 offset:51200
	ds_read_b128 v[180:183], v152 offset:52224
	ds_read_b128 v[184:187], v152 offset:53248
	ds_read_b128 v[204:207], v152 offset:54272
	ds_read_b128 v[208:211], v152 offset:55296
	ds_read_b128 v[212:215], v152 offset:56320
	global_load_lds_dwordx4 v134, vcc
	s_mov_b32 m0, s83
	s_nop 0
	global_load_lds_dwordx4 v132, vcc
	s_barrier
	s_waitcnt lgkmcnt(0)
	s_setprio 1
	s_waitcnt lgkmcnt(0)
	v_mfma_f32_16x16x32_bf16 v[62:65], v[140:143], v[168:171], v[62:65]
	v_mfma_f32_16x16x32_bf16 v[58:61], v[154:157], v[168:171], v[58:61]
	v_mfma_f32_16x16x32_bf16 v[50:53], v[140:143], v[176:179], v[50:53]
	v_mfma_f32_16x16x32_bf16 v[42:45], v[154:157], v[176:179], v[42:45]
	v_mfma_f32_16x16x32_bf16 v[34:37], v[140:143], v[184:187], v[34:37]
	v_mfma_f32_16x16x32_bf16 v[26:29], v[154:157], v[184:187], v[26:29]
	v_mfma_f32_16x16x32_bf16 v[18:21], v[140:143], v[208:211], v[18:21]
	v_mfma_f32_16x16x32_bf16 v[10:13], v[154:157], v[208:211], v[10:13]
	v_mfma_f32_16x16x32_bf16 v[62:65], v[144:147], v[172:175], v[62:65]
	v_mfma_f32_16x16x32_bf16 v[58:61], v[158:161], v[172:175], v[58:61]
	v_mfma_f32_16x16x32_bf16 v[50:53], v[144:147], v[180:183], v[50:53]
	v_mfma_f32_16x16x32_bf16 v[42:45], v[158:161], v[180:183], v[42:45]
	v_mfma_f32_16x16x32_bf16 v[34:37], v[144:147], v[204:207], v[34:37]
	v_mfma_f32_16x16x32_bf16 v[26:29], v[158:161], v[204:207], v[26:29]
	v_mfma_f32_16x16x32_bf16 v[18:21], v[144:147], v[212:215], v[18:21]
	v_mfma_f32_16x16x32_bf16 v[10:13], v[158:161], v[212:215], v[10:13]
	s_setprio 0
	s_barrier
	s_add_u32 s6, s6, 0x40080
	s_addc_u32 s7, s7, 0
	s_add_i32 s36, s36, s44
	s_mov_b32 m0, s36
	s_nop 0
	global_load_lds_dwordx4 v0, s[6:7]
	s_add_i32 m0, s36, 0x2000
	s_nop 0
	global_load_lds_dwordx4 v130, s[6:7]
	s_waitcnt vmcnt(6)
	s_barrier
	s_setprio 1
	v_mfma_f32_16x16x32_bf16 v[54:57], v[216:219], v[168:171], v[54:57]
	v_mfma_f32_16x16x32_bf16 v[46:49], v[230:233], v[168:171], v[46:49]
	v_mfma_f32_16x16x32_bf16 v[38:41], v[216:219], v[176:179], v[38:41]
	v_mfma_f32_16x16x32_bf16 v[30:33], v[230:233], v[176:179], v[30:33]
	v_mfma_f32_16x16x32_bf16 v[22:25], v[216:219], v[184:187], v[22:25]
	v_mfma_f32_16x16x32_bf16 v[14:17], v[230:233], v[184:187], v[14:17]
	v_mfma_f32_16x16x32_bf16 v[6:9], v[216:219], v[208:211], v[6:9]
	v_mfma_f32_16x16x32_bf16 v[2:5], v[230:233], v[208:211], v[2:5]
	v_mfma_f32_16x16x32_bf16 v[54:57], v[226:229], v[172:175], v[54:57]
	v_mfma_f32_16x16x32_bf16 v[46:49], v[234:237], v[172:175], v[46:49]
	v_mfma_f32_16x16x32_bf16 v[38:41], v[226:229], v[180:183], v[38:41]
	v_mfma_f32_16x16x32_bf16 v[30:33], v[234:237], v[180:183], v[30:33]
	v_mfma_f32_16x16x32_bf16 v[22:25], v[226:229], v[204:207], v[22:25]
	v_mfma_f32_16x16x32_bf16 v[14:17], v[234:237], v[204:207], v[14:17]
	v_mfma_f32_16x16x32_bf16 v[6:9], v[226:229], v[212:215], v[6:9]
	v_mfma_f32_16x16x32_bf16 v[2:5], v[234:237], v[212:215], v[2:5]
	s_setprio 0
	s_add_i32 s91, s91, 2
	s_add_u32 s24, s24, 0x100
	s_addc_u32 s25, s25, 0
	s_add_u32 s89, s89, 0x100
	s_addc_u32 s90, s90, 0
	s_cmp_gt_u32 s91, 13
	s_barrier
; #define PG8_STAGE(bufoff, gbase, voff) do { _Pragma("unroll") for (int _i = 0; _i < 2; ++_i) \
;         __builtin_amdgcn_global_load_lds((const unsigned*)((const char*)(gbase) + (voff)[_i]), (LAS unsigned*)(lds + (bufoff) + ldsw + _i * 8192), 16, 0, 0); } while (0)
; #define PG8_LDA(dst, b, h) do { _Pragma("unroll") for (int m = 0; m < 4; ++m) _Pragma("unroll") for (int k = 0; k < 2; ++k) dst[m][k] = *(const LAS bf16x8*)(lds + PG8_SA(b, h) + aoff + m * 2048 + k * 1024); } while (0)
; #define PG8_LDB(dst, b, h) do { _Pragma("unroll") for (int n = 0; n < 2; ++n) _Pragma("unroll") for (int k = 0; k < 2; ++k) dst[n][k] = *(const LAS bf16x8*)(lds + PG8_SB(b, h) + boff + n * 2048 + k * 1024); } while (0)
; #define PG8_WAIT_V(n) asm volatile("s_waitcnt vmcnt(" #n ")" ::: "memory")
; #define PG8_WAIT_L(n) asm volatile("s_waitcnt lgkmcnt(" #n ")" ::: "memory")
; #define PG8_BAR __builtin_amdgcn_s_barrier()
; #define PG8_SCHED __builtin_amdgcn_sched_barrier(0)
; template <class Epi>
; __device__ __forceinline__ void gemm_phase(LAS unsigned char* lds, const Gemm g, const StaticOrder& S, const Epi& E) {
;     ...
;             PG8_LDB(B0, 0, 0); PG8_SCHED; PG8_LDA(At, 0, 0); PG8_STAGE(PG8_SA(1, 1), a1 + hstep, voffA);
;             PG8_WAIT_L(8); PG8_BAR; PG8_WAIT_L(0); PG8_MMA(0, 0, At, B0); PG8_BAR; PG8_SCHED;
;             PG8_LDB(B1, 0, 1); PG8_STAGE(PG8_SB(0, 0), b2, voffB);
;             PG8_BAR; PG8_WAIT_L(0); PG8_MMA(0, 1, At, B1); PG8_BAR;
;             PG8_LDA(At, 0, 1); PG8_STAGE(PG8_SA(0, 0), a2, voffA);
;             PG8_BAR; PG8_WAIT_L(0); PG8_MMA(1, 0, At, B0); PG8_BAR; PG8_SCHED;
;             PG8_STAGE(PG8_SB(0, 1), b2 + hstep, voffB);
;             PG8_WAIT_V(6); PG8_BAR; PG8_MMA(1, 1, At, B1); PG8_BAR;
;             PG8_LDB(B0, 1, 0); PG8_SCHED; PG8_LDA(At, 1, 0); PG8_STAGE(PG8_SA(0, 1), a2 + hstep, voffA);
;             PG8_WAIT_L(8); PG8_BAR; PG8_WAIT_L(0); PG8_MMA(0, 0, At, B0); PG8_BAR; PG8_SCHED;
;             PG8_LDB(B1, 1, 1); PG8_STAGE(PG8_SB(1, 0), b3, voffB);
;             PG8_BAR; PG8_WAIT_L(0); PG8_MMA(0, 1, At, B1); PG8_BAR;
;             PG8_LDA(At, 1, 1); PG8_STAGE(PG8_SA(1, 0), a3, voffA);
;             PG8_BAR; PG8_WAIT_L(0); PG8_MMA(1, 0, At, B0); PG8_BAR; PG8_SCHED;
;             PG8_STAGE(PG8_SB(1, 1), b3 + hstep, voffB);
;             PG8_WAIT_V(6); PG8_BAR; PG8_MMA(1, 1, At, B1); PG8_BAR;
	s_add_u32 s6, s24, 0xfffc0080
	s_addc_u32 s7, s25, -1
	s_add_i32 s58, 0, 0x10000
	v_add_u32_e32 v153, s58, v149
	ds_read_b128 v[140:143], v153
	ds_read_b128 v[144:147], v153 offset:1024
	ds_read_b128 v[154:157], v153 offset:2048
	ds_read_b128 v[158:161], v153 offset:3072
	s_cmp_eq_u32 s91, 12
	s_cselect_b32 s37, s11, s7
	s_cselect_b32 s36, s71, s6
	s_cselect_b32 s7, s9, s90
	s_cselect_b32 s6, s88, s89
	s_add_i32 m0, s47, 0xc000
	ds_read_b128 v[168:171], v152
	ds_read_b128 v[172:175], v152 offset:1024
	ds_read_b128 v[176:179], v152 offset:2048
	ds_read_b128 v[180:183], v152 offset:3072
	ds_read_b128 v[184:187], v152 offset:4096
	ds_read_b128 v[204:207], v152 offset:5120
	ds_read_b128 v[208:211], v152 offset:6144
	ds_read_b128 v[212:215], v152 offset:7168
	global_load_lds_dwordx4 v136, s[24:25]
	s_add_i32 m0, s47, 0xe000
	s_nop 0
	global_load_lds_dwordx4 v138, s[24:25]
	s_waitcnt lgkmcnt(8)
	s_barrier
	s_waitcnt lgkmcnt(0)
	s_setprio 1
	s_waitcnt lgkmcnt(0)
	v_mfma_f32_16x16x32_bf16 v[126:129], v[140:143], v[168:171], v[126:129]
	v_mfma_f32_16x16x32_bf16 v[122:125], v[154:157], v[168:171], v[122:125]
	v_mfma_f32_16x16x32_bf16 v[114:117], v[140:143], v[176:179], v[114:117]
	v_mfma_f32_16x16x32_bf16 v[106:109], v[154:157], v[176:179], v[106:109]
	v_mfma_f32_16x16x32_bf16 v[98:101], v[140:143], v[184:187], v[98:101]
	v_mfma_f32_16x16x32_bf16 v[90:93], v[154:157], v[184:187], v[90:93]
	v_mfma_f32_16x16x32_bf16 v[82:85], v[140:143], v[208:211], v[82:85]
	v_mfma_f32_16x16x32_bf16 v[74:77], v[154:157], v[208:211], v[74:77]
	v_mfma_f32_16x16x32_bf16 v[126:129], v[144:147], v[172:175], v[126:129]
	v_mfma_f32_16x16x32_bf16 v[122:125], v[158:161], v[172:175], v[122:125]
	v_mfma_f32_16x16x32_bf16 v[114:117], v[144:147], v[180:183], v[114:117]
	v_mfma_f32_16x16x32_bf16 v[106:109], v[158:161], v[180:183], v[106:109]
	v_mfma_f32_16x16x32_bf16 v[98:101], v[144:147], v[204:207], v[98:101]
	v_mfma_f32_16x16x32_bf16 v[90:93], v[158:161], v[204:207], v[90:93]
	v_mfma_f32_16x16x32_bf16 v[82:85], v[144:147], v[212:215], v[82:85]
	v_mfma_f32_16x16x32_bf16 v[74:77], v[158:161], v[212:215], v[74:77]
	s_setprio 0
	s_barrier
	s_add_i32 s70, 0, 0x14000
	s_add_i32 s58, s58, s44
	v_add_u32_e32 v153, s70, v149
	s_mov_b32 m0, s58
	ds_read_b128 v[216:219], v153
	ds_read_b128 v[226:229], v153 offset:1024
	ds_read_b128 v[230:233], v153 offset:2048
	ds_read_b128 v[234:237], v153 offset:3072
	global_load_lds_dwordx4 v0, s[6:7]
	s_add_i32 m0, s58, 0x2000
	s_nop 0
	global_load_lds_dwordx4 v130, s[6:7]
	s_barrier
	s_waitcnt lgkmcnt(0)
	s_setprio 1
	s_waitcnt lgkmcnt(0)
	v_mfma_f32_16x16x32_bf16 v[118:121], v[216:219], v[168:171], v[118:121]
	v_mfma_f32_16x16x32_bf16 v[110:113], v[230:233], v[168:171], v[110:113]
	v_mfma_f32_16x16x32_bf16 v[102:105], v[216:219], v[176:179], v[102:105]
	v_mfma_f32_16x16x32_bf16 v[94:97], v[230:233], v[176:179], v[94:97]
	v_mfma_f32_16x16x32_bf16 v[86:89], v[216:219], v[184:187], v[86:89]
	v_mfma_f32_16x16x32_bf16 v[78:81], v[230:233], v[184:187], v[78:81]
	v_mfma_f32_16x16x32_bf16 v[70:73], v[216:219], v[208:211], v[70:73]
	v_mfma_f32_16x16x32_bf16 v[66:69], v[230:233], v[208:211], v[66:69]
	v_mfma_f32_16x16x32_bf16 v[118:121], v[226:229], v[172:175], v[118:121]
	v_mfma_f32_16x16x32_bf16 v[110:113], v[234:237], v[172:175], v[110:113]
	v_mfma_f32_16x16x32_bf16 v[102:105], v[226:229], v[180:183], v[102:105]
	v_mfma_f32_16x16x32_bf16 v[94:97], v[234:237], v[180:183], v[94:97]
	v_mfma_f32_16x16x32_bf16 v[86:89], v[226:229], v[204:207], v[86:89]
	v_mfma_f32_16x16x32_bf16 v[78:81], v[234:237], v[204:207], v[78:81]
	v_mfma_f32_16x16x32_bf16 v[70:73], v[226:229], v[212:215], v[70:73]
	v_mfma_f32_16x16x32_bf16 v[66:69], v[234:237], v[212:215], v[66:69]
	s_setprio 0
	s_mov_b32 m0, s47
	s_add_u32 vcc_lo, s36, 0x80
	s_addc_u32 vcc_hi, s37, 0
	s_barrier
	ds_read_b128 v[168:171], v152 offset:16384
	ds_read_b128 v[172:175], v152 offset:17408
	ds_read_b128 v[176:179], v152 offset:18432
	ds_read_b128 v[180:183], v152 offset:19456
	ds_read_b128 v[184:187], v152 offset:20480
	ds_read_b128 v[204:207], v152 offset:21504
	ds_read_b128 v[208:211], v152 offset:22528
	ds_read_b128 v[212:215], v152 offset:23552
	global_load_lds_dwordx4 v134, s[36:37]
	s_mov_b32 m0, s48
	s_nop 0
	global_load_lds_dwordx4 v132, s[36:37]
	s_barrier
	s_waitcnt lgkmcnt(0)
	s_setprio 1
	s_waitcnt lgkmcnt(0)
	v_mfma_f32_16x16x32_bf16 v[62:65], v[140:143], v[168:171], v[62:65]
	v_mfma_f32_16x16x32_bf16 v[58:61], v[154:157], v[168:171], v[58:61]
	v_mfma_f32_16x16x32_bf16 v[50:53], v[140:143], v[176:179], v[50:53]
	v_mfma_f32_16x16x32_bf16 v[42:45], v[154:157], v[176:179], v[42:45]
	v_mfma_f32_16x16x32_bf16 v[34:37], v[140:143], v[184:187], v[34:37]
	v_mfma_f32_16x16x32_bf16 v[26:29], v[154:157], v[184:187], v[26:29]
	v_mfma_f32_16x16x32_bf16 v[18:21], v[140:143], v[208:211], v[18:21]
	v_mfma_f32_16x16x32_bf16 v[10:13], v[154:157], v[208:211], v[10:13]
	v_mfma_f32_16x16x32_bf16 v[62:65], v[144:147], v[172:175], v[62:65]
	v_mfma_f32_16x16x32_bf16 v[58:61], v[158:161], v[172:175], v[58:61]
	v_mfma_f32_16x16x32_bf16 v[50:53], v[144:147], v[180:183], v[50:53]
	v_mfma_f32_16x16x32_bf16 v[42:45], v[158:161], v[180:183], v[42:45]
	v_mfma_f32_16x16x32_bf16 v[34:37], v[144:147], v[204:207], v[34:37]
	v_mfma_f32_16x16x32_bf16 v[26:29], v[158:161], v[204:207], v[26:29]
	v_mfma_f32_16x16x32_bf16 v[18:21], v[144:147], v[212:215], v[18:21]
	v_mfma_f32_16x16x32_bf16 v[10:13], v[158:161], v[212:215], v[10:13]
	s_setprio 0
	s_barrier
	s_add_u32 s60, s6, 0x40000
	s_addc_u32 s61, s7, 0
	s_add_i32 s58, s70, s44
	s_mov_b32 m0, s58
	s_nop 0
	global_load_lds_dwordx4 v0, s[60:61]
	s_add_i32 m0, s58, 0x2000
	s_nop 0
	global_load_lds_dwordx4 v130, s[60:61]
	s_waitcnt vmcnt(6)
	s_barrier
	s_setprio 1
	v_mfma_f32_16x16x32_bf16 v[54:57], v[216:219], v[168:171], v[54:57]
	v_mfma_f32_16x16x32_bf16 v[46:49], v[230:233], v[168:171], v[46:49]
	s_cmp_eq_u32 s87, 0
	s_cbranch_scc1 .LdsA_skip_4
	global_store_dwordx4 v166, v[200:203], s[4:5]
; #define PG8_STAGE(bufoff, gbase, voff) do { _Pragma("unroll") for (int _i = 0; _i < 2; ++_i) \
;         __builtin_amdgcn_global_load_lds((const unsigned*)((const char*)(gbase) + (voff)[_i]), (LAS unsigned*)(lds + (bufoff) + ldsw + _i * 8192), 16, 0, 0); } while (0)
; #define PG8_LDA(dst, b, h) do { _Pragma("unroll") for (int m = 0; m < 4; ++m) _Pragma("unroll") for (int k = 0; k < 2; ++k) dst[m][k] = *(const LAS bf16x8*)(lds + PG8_SA(b, h) + aoff + m * 2048 + k * 1024); } while (0)
; #define PG8_LDB(dst, b, h) do { _Pragma("unroll") for (int n = 0; n < 2; ++n) _Pragma("unroll") for (int k = 0; k < 2; ++k) dst[n][k] = *(const LAS bf16x8*)(lds + PG8_SB(b, h) + boff + n * 2048 + k * 1024); } while (0)
; #define PG8_WAIT_V(n) asm volatile("s_waitcnt vmcnt(" #n ")" ::: "memory")
; #define PG8_WAIT_L(n) asm volatile("s_waitcnt lgkmcnt(" #n ")" ::: "memory")
; #define PG8_BAR __builtin_amdgcn_s_barrier()
; #define PG8_SCHED __builtin_amdgcn_sched_barrier(0)
; template <class Epi>
; __device__ __forceinline__ void gemm_phase(LAS unsigned char* lds, const Gemm g, const StaticOrder& S, const Epi& E) {
;     ...
;             PG8_LDB(B0, 0, 0); PG8_SCHED; PG8_LDA(At, 0, 0); PG8_STAGE(PG8_SA(1, 1), a1 + hstep, voffA);
;             PG8_WAIT_L(8); PG8_BAR; PG8_WAIT_L(0); PG8_MMA(0, 0, At, B0); PG8_BAR; PG8_SCHED;
;             PG8_LDB(B1, 0, 1); PG8_STAGE(PG8_SB(0, 0), b2, voffB);
;             PG8_BAR; PG8_WAIT_L(0); PG8_MMA(0, 1, At, B1); PG8_BAR;
;             PG8_LDA(At, 0, 1); PG8_STAGE(PG8_SA(0, 0), a2, voffA);
;             PG8_BAR; PG8_WAIT_L(0); PG8_MMA(1, 0, At, B0); PG8_BAR; PG8_SCHED;
;             PG8_STAGE(PG8_SB(0, 1), b2 + hstep, voffB);
;             PG8_WAIT_V(6); PG8_BAR; PG8_MMA(1, 1, At, B1); PG8_BAR;
;             PG8_LDB(B0, 1, 0); PG8_SCHED; PG8_LDA(At, 1, 0); PG8_STAGE(PG8_SA(0, 1), a2 + hstep, voffA);
;             PG8_WAIT_L(8); PG8_BAR; PG8_WAIT_L(0); PG8_MMA(0, 0, At, B0); PG8_BAR; PG8_SCHED;
;             PG8_LDB(B1, 1, 1); PG8_STAGE(PG8_SB(1, 0), b3, voffB);
;             PG8_BAR; PG8_WAIT_L(0); PG8_MMA(0, 1, At, B1); PG8_BAR;
;             PG8_LDA(At, 1, 1); PG8_STAGE(PG8_SA(1, 0), a3, voffA);
;             PG8_BAR; PG8_WAIT_L(0); PG8_MMA(1, 0, At, B0); PG8_BAR; PG8_SCHED;
;             PG8_STAGE(PG8_SB(1, 1), b3 + hstep, voffB);
;             PG8_WAIT_V(6); PG8_BAR; PG8_MMA(1, 1, At, B1); PG8_BAR;
.LdsA_skip_4:
	v_mfma_f32_16x16x32_bf16 v[38:41], v[216:219], v[176:179], v[38:41]
	v_mfma_f32_16x16x32_bf16 v[30:33], v[230:233], v[176:179], v[30:33]
	v_mfma_f32_16x16x32_bf16 v[22:25], v[216:219], v[184:187], v[22:25]
	v_mfma_f32_16x16x32_bf16 v[14:17], v[230:233], v[184:187], v[14:17]
	v_mfma_f32_16x16x32_bf16 v[6:9], v[216:219], v[208:211], v[6:9]
	v_mfma_f32_16x16x32_bf16 v[2:5], v[230:233], v[208:211], v[2:5]
	v_mfma_f32_16x16x32_bf16 v[54:57], v[226:229], v[172:175], v[54:57]
	v_mfma_f32_16x16x32_bf16 v[46:49], v[234:237], v[172:175], v[46:49]
	v_mfma_f32_16x16x32_bf16 v[38:41], v[226:229], v[180:183], v[38:41]
	v_mfma_f32_16x16x32_bf16 v[30:33], v[234:237], v[180:183], v[30:33]
	v_mfma_f32_16x16x32_bf16 v[22:25], v[226:229], v[204:207], v[22:25]
	v_mfma_f32_16x16x32_bf16 v[14:17], v[234:237], v[204:207], v[14:17]
	v_mfma_f32_16x16x32_bf16 v[6:9], v[226:229], v[212:215], v[6:9]
	v_mfma_f32_16x16x32_bf16 v[2:5], v[234:237], v[212:215], v[2:5]
	s_setprio 0
	s_add_i32 s58, 0, 0x18000
	v_add_u32_e32 v153, s58, v149
	s_barrier
	ds_read_b128 v[140:143], v153
	ds_read_b128 v[144:147], v153 offset:1024
	ds_read_b128 v[154:157], v153 offset:2048
	ds_read_b128 v[158:161], v153 offset:3072
	s_add_u32 s36, s36, 0x40000
	s_addc_u32 s37, s37, 0
	s_mov_b32 m0, s49
	ds_read_b128 v[168:171], v152 offset:32768
	ds_read_b128 v[172:175], v152 offset:33792
	ds_read_b128 v[176:179], v152 offset:34816
	ds_read_b128 v[180:183], v152 offset:35840
	ds_read_b128 v[184:187], v152 offset:36864
	ds_read_b128 v[204:207], v152 offset:37888
	ds_read_b128 v[208:211], v152 offset:38912
	ds_read_b128 v[212:215], v152 offset:39936
	global_load_lds_dwordx4 v134, s[36:37]
	s_mov_b32 m0, s54
	s_nop 0
	global_load_lds_dwordx4 v132, s[36:37]
	s_waitcnt lgkmcnt(8)
	s_barrier
	s_waitcnt lgkmcnt(0)
	s_setprio 1
	s_waitcnt lgkmcnt(0)
	v_mfma_f32_16x16x32_bf16 v[126:129], v[140:143], v[168:171], v[126:129]
	v_mfma_f32_16x16x32_bf16 v[122:125], v[154:157], v[168:171], v[122:125]
	v_mfma_f32_16x16x32_bf16 v[114:117], v[140:143], v[176:179], v[114:117]
	v_mfma_f32_16x16x32_bf16 v[106:109], v[154:157], v[176:179], v[106:109]
	v_mfma_f32_16x16x32_bf16 v[98:101], v[140:143], v[184:187], v[98:101]
	v_mfma_f32_16x16x32_bf16 v[90:93], v[154:157], v[184:187], v[90:93]
	v_mfma_f32_16x16x32_bf16 v[82:85], v[140:143], v[208:211], v[82:85]
	v_mfma_f32_16x16x32_bf16 v[74:77], v[154:157], v[208:211], v[74:77]
	v_mfma_f32_16x16x32_bf16 v[126:129], v[144:147], v[172:175], v[126:129]
	v_mfma_f32_16x16x32_bf16 v[122:125], v[158:161], v[172:175], v[122:125]
	v_mfma_f32_16x16x32_bf16 v[114:117], v[144:147], v[180:183], v[114:117]
	v_mfma_f32_16x16x32_bf16 v[106:109], v[158:161], v[180:183], v[106:109]
	v_mfma_f32_16x16x32_bf16 v[98:101], v[144:147], v[204:207], v[98:101]
	v_mfma_f32_16x16x32_bf16 v[90:93], v[158:161], v[204:207], v[90:93]
	v_mfma_f32_16x16x32_bf16 v[82:85], v[144:147], v[212:215], v[82:85]
	v_mfma_f32_16x16x32_bf16 v[74:77], v[158:161], v[212:215], v[74:77]
	s_setprio 0
	s_barrier
	s_add_i32 s36, 0, 0x1c000
	s_add_i32 s37, s58, s44
	v_add_u32_e32 v153, s36, v149
	s_add_u32 s60, s6, 0x80
	s_addc_u32 s61, s7, 0
	s_mov_b32 m0, s37
	ds_read_b128 v[216:219], v153
	ds_read_b128 v[226:229], v153 offset:1024
	ds_read_b128 v[230:233], v153 offset:2048
	ds_read_b128 v[234:237], v153 offset:3072
	global_load_lds_dwordx4 v0, s[60:61]
	s_add_i32 m0, s37, 0x2000
	s_nop 0
	global_load_lds_dwordx4 v130, s[60:61]
	s_barrier
	s_waitcnt lgkmcnt(0)
	s_setprio 1
	s_waitcnt lgkmcnt(0)
	v_mfma_f32_16x16x32_bf16 v[118:121], v[216:219], v[168:171], v[118:121]
	v_mfma_f32_16x16x32_bf16 v[110:113], v[230:233], v[168:171], v[110:113]
	v_mfma_f32_16x16x32_bf16 v[102:105], v[216:219], v[176:179], v[102:105]
	v_mfma_f32_16x16x32_bf16 v[94:97], v[230:233], v[176:179], v[94:97]
	v_mfma_f32_16x16x32_bf16 v[86:89], v[216:219], v[184:187], v[86:89]
	v_mfma_f32_16x16x32_bf16 v[78:81], v[230:233], v[184:187], v[78:81]
	v_mfma_f32_16x16x32_bf16 v[70:73], v[216:219], v[208:211], v[70:73]
	v_mfma_f32_16x16x32_bf16 v[66:69], v[230:233], v[208:211], v[66:69]
	v_mfma_f32_16x16x32_bf16 v[118:121], v[226:229], v[172:175], v[118:121]
	v_mfma_f32_16x16x32_bf16 v[110:113], v[234:237], v[172:175], v[110:113]
	v_mfma_f32_16x16x32_bf16 v[102:105], v[226:229], v[180:183], v[102:105]
	v_mfma_f32_16x16x32_bf16 v[94:97], v[234:237], v[180:183], v[94:97]
	v_mfma_f32_16x16x32_bf16 v[86:89], v[226:229], v[204:207], v[86:89]
	v_mfma_f32_16x16x32_bf16 v[78:81], v[234:237], v[204:207], v[78:81]
	v_mfma_f32_16x16x32_bf16 v[70:73], v[226:229], v[212:215], v[70:73]
	v_mfma_f32_16x16x32_bf16 v[66:69], v[234:237], v[212:215], v[66:69]
	s_setprio 0
	s_mov_b32 m0, s55
	s_barrier
	ds_read_b128 v[168:171], v152 offset:49152
	ds_read_b128 v[172:175], v152 offset:50176
	ds_read_b128 v[176:179], v152 offset:51200
	ds_read_b128 v[180:183], v152 offset:52224
	ds_read_b128 v[184:187], v152 offset:53248
	ds_read_b128 v[204:207], v152 offset:54272
	ds_read_b128 v[208:211], v152 offset:55296
	ds_read_b128 v[212:215], v152 offset:56320
	global_load_lds_dwordx4 v134, vcc
	s_mov_b32 m0, s83
	s_nop 0
	global_load_lds_dwordx4 v132, vcc
	s_barrier
; #define PG8_STAGE(bufoff, gbase, voff) do { _Pragma("unroll") for (int _i = 0; _i < 2; ++_i) \
;         __builtin_amdgcn_global_load_lds((const unsigned*)((const char*)(gbase) + (voff)[_i]), (LAS unsigned*)(lds + (bufoff) + ldsw + _i * 8192), 16, 0, 0); } while (0)
; #define PG8_LDA(dst, b, h) do { _Pragma("unroll") for (int m = 0; m < 4; ++m) _Pragma("unroll") for (int k = 0; k < 2; ++k) dst[m][k] = *(const LAS bf16x8*)(lds + PG8_SA(b, h) + aoff + m * 2048 + k * 1024); } while (0)
; #define PG8_LDB(dst, b, h) do { _Pragma("unroll") for (int n = 0; n < 2; ++n) _Pragma("unroll") for (int k = 0; k < 2; ++k) dst[n][k] = *(const LAS bf16x8*)(lds + PG8_SB(b, h) + boff + n * 2048 + k * 1024); } while (0)
; #define PG8_WAIT_V(n) asm volatile("s_waitcnt vmcnt(" #n ")" ::: "memory")
; #define PG8_WAIT_L(n) asm volatile("s_waitcnt lgkmcnt(" #n ")" ::: "memory")
; #define PG8_BAR __builtin_amdgcn_s_barrier()
; #define PG8_SCHED __builtin_amdgcn_sched_barrier(0)
; template <class Epi>
; __device__ __forceinline__ void gemm_phase(LAS unsigned char* lds, const Gemm g, const StaticOrder& S, const Epi& E) {
;     ...
;             PG8_LDB(B0, 0, 0); PG8_SCHED; PG8_LDA(At, 0, 0); PG8_STAGE(PG8_SA(1, 1), a1 + hstep, voffA);
;             PG8_WAIT_L(8); PG8_BAR; PG8_WAIT_L(0); PG8_MMA(0, 0, At, B0); PG8_BAR; PG8_SCHED;
;             PG8_LDB(B1, 0, 1); PG8_STAGE(PG8_SB(0, 0), b2, voffB);
;             PG8_BAR; PG8_WAIT_L(0); PG8_MMA(0, 1, At, B1); PG8_BAR;
;             PG8_LDA(At, 0, 1); PG8_STAGE(PG8_SA(0, 0), a2, voffA);
;             PG8_BAR; PG8_WAIT_L(0); PG8_MMA(1, 0, At, B0); PG8_BAR; PG8_SCHED;
;             PG8_STAGE(PG8_SB(0, 1), b2 + hstep, voffB);
;             PG8_WAIT_V(6); PG8_BAR; PG8_MMA(1, 1, At, B1); PG8_BAR;
;             PG8_LDB(B0, 1, 0); PG8_SCHED; PG8_LDA(At, 1, 0); PG8_STAGE(PG8_SA(0, 1), a2 + hstep, voffA);
;             PG8_WAIT_L(8); PG8_BAR; PG8_WAIT_L(0); PG8_MMA(0, 0, At, B0); PG8_BAR; PG8_SCHED;
;             PG8_LDB(B1, 1, 1); PG8_STAGE(PG8_SB(1, 0), b3, voffB);
;             PG8_BAR; PG8_WAIT_L(0); PG8_MMA(0, 1, At, B1); PG8_BAR;
;             PG8_LDA(At, 1, 1); PG8_STAGE(PG8_SA(1, 0), a3, voffA);
;             PG8_BAR; PG8_WAIT_L(0); PG8_MMA(1, 0, At, B0); PG8_BAR; PG8_SCHED;
;             PG8_STAGE(PG8_SB(1, 1), b3 + hstep, voffB);
;             PG8_WAIT_V(6); PG8_BAR; PG8_MMA(1, 1, At, B1); PG8_BAR;
	s_waitcnt lgkmcnt(0)
	s_setprio 1
	s_waitcnt lgkmcnt(0)
	v_mfma_f32_16x16x32_bf16 v[62:65], v[140:143], v[168:171], v[62:65]
	v_mfma_f32_16x16x32_bf16 v[58:61], v[154:157], v[168:171], v[58:61]
	v_mfma_f32_16x16x32_bf16 v[50:53], v[140:143], v[176:179], v[50:53]
	v_mfma_f32_16x16x32_bf16 v[42:45], v[154:157], v[176:179], v[42:45]
	v_mfma_f32_16x16x32_bf16 v[34:37], v[140:143], v[184:187], v[34:37]
	v_mfma_f32_16x16x32_bf16 v[26:29], v[154:157], v[184:187], v[26:29]
	v_mfma_f32_16x16x32_bf16 v[18:21], v[140:143], v[208:211], v[18:21]
	v_mfma_f32_16x16x32_bf16 v[10:13], v[154:157], v[208:211], v[10:13]
	v_mfma_f32_16x16x32_bf16 v[62:65], v[144:147], v[172:175], v[62:65]
	v_mfma_f32_16x16x32_bf16 v[58:61], v[158:161], v[172:175], v[58:61]
	v_mfma_f32_16x16x32_bf16 v[50:53], v[144:147], v[180:183], v[50:53]
	v_mfma_f32_16x16x32_bf16 v[42:45], v[158:161], v[180:183], v[42:45]
	v_mfma_f32_16x16x32_bf16 v[34:37], v[144:147], v[204:207], v[34:37]
	v_mfma_f32_16x16x32_bf16 v[26:29], v[158:161], v[204:207], v[26:29]
	v_mfma_f32_16x16x32_bf16 v[18:21], v[144:147], v[212:215], v[18:21]
	v_mfma_f32_16x16x32_bf16 v[10:13], v[158:161], v[212:215], v[10:13]
	s_setprio 0
	s_barrier
	s_add_u32 s6, s6, 0x40080
	s_addc_u32 s7, s7, 0
	s_add_i32 s36, s36, s44
	s_mov_b32 m0, s36
	s_nop 0
	global_load_lds_dwordx4 v0, s[6:7]
	s_add_i32 m0, s36, 0x2000
	s_nop 0
	global_load_lds_dwordx4 v130, s[6:7]
	s_waitcnt vmcnt(6)
	s_barrier
	s_setprio 1
	v_mfma_f32_16x16x32_bf16 v[54:57], v[216:219], v[168:171], v[54:57]
	v_mfma_f32_16x16x32_bf16 v[46:49], v[230:233], v[168:171], v[46:49]
	v_mfma_f32_16x16x32_bf16 v[38:41], v[216:219], v[176:179], v[38:41]
	v_mfma_f32_16x16x32_bf16 v[30:33], v[230:233], v[176:179], v[30:33]
	v_mfma_f32_16x16x32_bf16 v[22:25], v[216:219], v[184:187], v[22:25]
	v_mfma_f32_16x16x32_bf16 v[14:17], v[230:233], v[184:187], v[14:17]
	v_mfma_f32_16x16x32_bf16 v[6:9], v[216:219], v[208:211], v[6:9]
	v_mfma_f32_16x16x32_bf16 v[2:5], v[230:233], v[208:211], v[2:5]
	v_mfma_f32_16x16x32_bf16 v[54:57], v[226:229], v[172:175], v[54:57]
	v_mfma_f32_16x16x32_bf16 v[46:49], v[234:237], v[172:175], v[46:49]
	v_mfma_f32_16x16x32_bf16 v[38:41], v[226:229], v[180:183], v[38:41]
	v_mfma_f32_16x16x32_bf16 v[30:33], v[234:237], v[180:183], v[30:33]
	v_mfma_f32_16x16x32_bf16 v[22:25], v[226:229], v[204:207], v[22:25]
	v_mfma_f32_16x16x32_bf16 v[14:17], v[234:237], v[204:207], v[14:17]
	v_mfma_f32_16x16x32_bf16 v[6:9], v[226:229], v[212:215], v[6:9]
	v_mfma_f32_16x16x32_bf16 v[2:5], v[234:237], v[212:215], v[2:5]
	s_setprio 0
	s_add_i32 s91, s91, 2
	s_add_u32 s24, s24, 0x100
	s_addc_u32 s25, s25, 0
	s_add_u32 s89, s89, 0x100
	s_addc_u32 s90, s90, 0
	s_cmp_gt_u32 s91, 13
	s_barrier
	s_add_u32 s6, s24, 0xfffc0080
	s_addc_u32 s7, s25, -1
	s_add_i32 s58, 0, 0x10000
	v_add_u32_e32 v153, s58, v149
	ds_read_b128 v[140:143], v153
	ds_read_b128 v[144:147], v153 offset:1024
	ds_read_b128 v[154:157], v153 offset:2048
	ds_read_b128 v[158:161], v153 offset:3072
	s_cmp_eq_u32 s91, 12
	s_cselect_b32 s37, s11, s7
	s_cselect_b32 s36, s71, s6
	s_cselect_b32 s7, s9, s90
	s_cselect_b32 s6, s88, s89
	s_add_i32 m0, s47, 0xc000
	ds_read_b128 v[168:171], v152
	ds_read_b128 v[172:175], v152 offset:1024
	ds_read_b128 v[176:179], v152 offset:2048
	ds_read_b128 v[180:183], v152 offset:3072
	ds_read_b128 v[184:187], v152 offset:4096
	ds_read_b128 v[204:207], v152 offset:5120
	ds_read_b128 v[208:211], v152 offset:6144
	ds_read_b128 v[212:215], v152 offset:7168
	global_load_lds_dwordx4 v136, s[24:25]
	s_add_i32 m0, s47, 0xe000
	s_nop 0
	global_load_lds_dwordx4 v138, s[24:25]
	s_waitcnt lgkmcnt(8)
	s_barrier
	s_waitcnt lgkmcnt(0)
	s_setprio 1
	s_waitcnt lgkmcnt(0)
	v_mfma_f32_16x16x32_bf16 v[126:129], v[140:143], v[168:171], v[126:129]
	v_mfma_f32_16x16x32_bf16 v[122:125], v[154:157], v[168:171], v[122:125]
	v_mfma_f32_16x16x32_bf16 v[114:117], v[140:143], v[176:179], v[114:117]
	v_mfma_f32_16x16x32_bf16 v[106:109], v[154:157], v[176:179], v[106:109]
	v_mfma_f32_16x16x32_bf16 v[98:101], v[140:143], v[184:187], v[98:101]
	v_mfma_f32_16x16x32_bf16 v[90:93], v[154:157], v[184:187], v[90:93]
	v_mfma_f32_16x16x32_bf16 v[82:85], v[140:143], v[208:211], v[82:85]
	v_mfma_f32_16x16x32_bf16 v[74:77], v[154:157], v[208:211], v[74:77]
	v_mfma_f32_16x16x32_bf16 v[126:129], v[144:147], v[172:175], v[126:129]
	v_mfma_f32_16x16x32_bf16 v[122:125], v[158:161], v[172:175], v[122:125]
	v_mfma_f32_16x16x32_bf16 v[114:117], v[144:147], v[180:183], v[114:117]
	v_mfma_f32_16x16x32_bf16 v[106:109], v[158:161], v[180:183], v[106:109]
	v_mfma_f32_16x16x32_bf16 v[98:101], v[144:147], v[204:207], v[98:101]
	v_mfma_f32_16x16x32_bf16 v[90:93], v[158:161], v[204:207], v[90:93]
	v_mfma_f32_16x16x32_bf16 v[82:85], v[144:147], v[212:215], v[82:85]
	v_mfma_f32_16x16x32_bf16 v[74:77], v[158:161], v[212:215], v[74:77]
	s_setprio 0
	s_barrier
	s_add_i32 s70, 0, 0x14000
	s_add_i32 s58, s58, s44
	v_add_u32_e32 v153, s70, v149
	s_mov_b32 m0, s58
	ds_read_b128 v[216:219], v153
	ds_read_b128 v[226:229], v153 offset:1024
	ds_read_b128 v[230:233], v153 offset:2048
	ds_read_b128 v[234:237], v153 offset:3072
	global_load_lds_dwordx4 v0, s[6:7]
	s_add_i32 m0, s58, 0x2000
	s_nop 0
	global_load_lds_dwordx4 v130, s[6:7]
	s_barrier
; __device__ __forceinline__ unsigned pk2(float lo, float hi) { unsigned r; asm("v_cvt_pk_bf16_f32 %0, %1, %2" : "=v"(r) : "v"(lo), "v"(hi)); return r; }
; #define PG8_STAGE(bufoff, gbase, voff) do { _Pragma("unroll") for (int _i = 0; _i < 2; ++_i) \
;         __builtin_amdgcn_global_load_lds((const unsigned*)((const char*)(gbase) + (voff)[_i]), (LAS unsigned*)(lds + (bufoff) + ldsw + _i * 8192), 16, 0, 0); } while (0)
; #define PG8_LDA(dst, b, h) do { _Pragma("unroll") for (int m = 0; m < 4; ++m) _Pragma("unroll") for (int k = 0; k < 2; ++k) dst[m][k] = *(const LAS bf16x8*)(lds + PG8_SA(b, h) + aoff + m * 2048 + k * 1024); } while (0)
;     __device__ __forceinline__ void operator()(const f32x4 (&acc)[2][2][4][2], const Unit& u, int ui, int wr, int wc, int fr, int fq) const {
;     ...
;                     u32x4 w; w.x = pk2(v0[0], v0[1]); w.y = pk2(v0[2], v0[3]); w.z = pk2(v1[0], v1[1]); w.w = pk2(v1[2], v1[3]);
;                     *(u32x4*)(rowp + bj * HALF) = w;
; template <class Epi>
; __device__ __forceinline__ void gemm_phase(LAS unsigned char* lds, const Gemm g, const StaticOrder& S, const Epi& E) {
;     ...
;             PG8_LDB(B0, 0, 0); PG8_SCHED; PG8_LDA(At, 0, 0); PG8_STAGE(PG8_SA(1, 1), a1 + hstep, voffA);
;             PG8_WAIT_L(8); PG8_BAR; PG8_WAIT_L(0); PG8_MMA(0, 0, At, B0); PG8_BAR; PG8_SCHED;
;             PG8_LDB(B1, 0, 1); PG8_STAGE(PG8_SB(0, 0), b2, voffB);
;             PG8_BAR; PG8_WAIT_L(0); PG8_MMA(0, 1, At, B1); PG8_BAR;
;             PG8_LDA(At, 0, 1); PG8_STAGE(PG8_SA(0, 0), a2, voffA);
;             PG8_BAR; PG8_WAIT_L(0); PG8_MMA(1, 0, At, B0); PG8_BAR; PG8_SCHED;
;             PG8_STAGE(PG8_SB(0, 1), b2 + hstep, voffB);
;             PG8_WAIT_V(6); PG8_BAR; PG8_MMA(1, 1, At, B1); PG8_BAR;
;             PG8_LDB(B0, 1, 0); PG8_SCHED; PG8_LDA(At, 1, 0); PG8_STAGE(PG8_SA(0, 1), a2 + hstep, voffA);
;             PG8_WAIT_L(8); PG8_BAR; PG8_WAIT_L(0); PG8_MMA(0, 0, At, B0); PG8_BAR; PG8_SCHED;
;             PG8_LDB(B1, 1, 1); PG8_STAGE(PG8_SB(1, 0), b3, voffB);
;             PG8_BAR; PG8_WAIT_L(0); PG8_MMA(0, 1, At, B1); PG8_BAR;
;             PG8_LDA(At, 1, 1); PG8_STAGE(PG8_SA(1, 0), a3, voffA);
;             PG8_BAR; PG8_WAIT_L(0); PG8_MMA(1, 0, At, B0); PG8_BAR; PG8_SCHED;
;             PG8_STAGE(PG8_SB(1, 1), b3 + hstep, voffB);
;             PG8_WAIT_V(6); PG8_BAR; PG8_MMA(1, 1, At, B1); PG8_BAR;
	s_waitcnt lgkmcnt(0)
	s_setprio 1
	s_waitcnt lgkmcnt(0)
	v_mfma_f32_16x16x32_bf16 v[118:121], v[216:219], v[168:171], v[118:121]
	v_mfma_f32_16x16x32_bf16 v[110:113], v[230:233], v[168:171], v[110:113]
	v_mfma_f32_16x16x32_bf16 v[102:105], v[216:219], v[176:179], v[102:105]
	v_mfma_f32_16x16x32_bf16 v[94:97], v[230:233], v[176:179], v[94:97]
	v_mfma_f32_16x16x32_bf16 v[86:89], v[216:219], v[184:187], v[86:89]
	v_mfma_f32_16x16x32_bf16 v[78:81], v[230:233], v[184:187], v[78:81]
	v_mfma_f32_16x16x32_bf16 v[70:73], v[216:219], v[208:211], v[70:73]
	v_mfma_f32_16x16x32_bf16 v[66:69], v[230:233], v[208:211], v[66:69]
	v_mfma_f32_16x16x32_bf16 v[118:121], v[226:229], v[172:175], v[118:121]
	v_mfma_f32_16x16x32_bf16 v[110:113], v[234:237], v[172:175], v[110:113]
	v_mfma_f32_16x16x32_bf16 v[102:105], v[226:229], v[180:183], v[102:105]
	v_mfma_f32_16x16x32_bf16 v[94:97], v[234:237], v[180:183], v[94:97]
	v_mfma_f32_16x16x32_bf16 v[86:89], v[226:229], v[204:207], v[86:89]
	v_mfma_f32_16x16x32_bf16 v[78:81], v[234:237], v[204:207], v[78:81]
	v_mfma_f32_16x16x32_bf16 v[70:73], v[226:229], v[212:215], v[70:73]
	v_mfma_f32_16x16x32_bf16 v[66:69], v[234:237], v[212:215], v[66:69]
	s_setprio 0
	s_mov_b32 m0, s47
	s_add_u32 vcc_lo, s36, 0x80
	s_addc_u32 vcc_hi, s37, 0
	s_barrier
	ds_read_b128 v[168:171], v152 offset:16384
	ds_read_b128 v[172:175], v152 offset:17408
	ds_read_b128 v[176:179], v152 offset:18432
	ds_read_b128 v[180:183], v152 offset:19456
	ds_read_b128 v[184:187], v152 offset:20480
	ds_read_b128 v[204:207], v152 offset:21504
	ds_read_b128 v[208:211], v152 offset:22528
	ds_read_b128 v[212:215], v152 offset:23552
	global_load_lds_dwordx4 v134, s[36:37]
	s_mov_b32 m0, s48
	s_nop 0
	global_load_lds_dwordx4 v132, s[36:37]
	s_barrier
	s_waitcnt lgkmcnt(0)
	s_setprio 1
	s_waitcnt lgkmcnt(0)
	v_mfma_f32_16x16x32_bf16 v[62:65], v[140:143], v[168:171], v[62:65]
	v_mfma_f32_16x16x32_bf16 v[58:61], v[154:157], v[168:171], v[58:61]
	v_mfma_f32_16x16x32_bf16 v[50:53], v[140:143], v[176:179], v[50:53]
	v_mfma_f32_16x16x32_bf16 v[42:45], v[154:157], v[176:179], v[42:45]
	v_mfma_f32_16x16x32_bf16 v[34:37], v[140:143], v[184:187], v[34:37]
	v_mfma_f32_16x16x32_bf16 v[26:29], v[154:157], v[184:187], v[26:29]
	v_mfma_f32_16x16x32_bf16 v[18:21], v[140:143], v[208:211], v[18:21]
	v_mfma_f32_16x16x32_bf16 v[10:13], v[154:157], v[208:211], v[10:13]
	v_mfma_f32_16x16x32_bf16 v[62:65], v[144:147], v[172:175], v[62:65]
	v_mfma_f32_16x16x32_bf16 v[58:61], v[158:161], v[172:175], v[58:61]
	v_mfma_f32_16x16x32_bf16 v[50:53], v[144:147], v[180:183], v[50:53]
	v_mfma_f32_16x16x32_bf16 v[42:45], v[158:161], v[180:183], v[42:45]
	v_mfma_f32_16x16x32_bf16 v[34:37], v[144:147], v[204:207], v[34:37]
	v_mfma_f32_16x16x32_bf16 v[26:29], v[158:161], v[204:207], v[26:29]
	v_mfma_f32_16x16x32_bf16 v[18:21], v[144:147], v[212:215], v[18:21]
	v_mfma_f32_16x16x32_bf16 v[10:13], v[158:161], v[212:215], v[10:13]
	s_setprio 0
	s_barrier
	s_add_u32 s60, s6, 0x40000
	s_addc_u32 s61, s7, 0
	s_add_i32 s58, s70, s44
	s_mov_b32 m0, s58
	s_nop 0
	global_load_lds_dwordx4 v0, s[60:61]
	s_add_i32 m0, s58, 0x2000
	s_nop 0
	global_load_lds_dwordx4 v130, s[60:61]
	s_waitcnt vmcnt(6)
	s_barrier
	s_setprio 1
	v_mfma_f32_16x16x32_bf16 v[54:57], v[216:219], v[168:171], v[54:57]
	v_mfma_f32_16x16x32_bf16 v[46:49], v[230:233], v[168:171], v[46:49]
	s_cmp_eq_u32 s87, 0
	s_cbranch_scc1 .LdsA_skip_5
	global_store_dwordx4 v166, v[222:225], s[4:5] offset:256
	v_add_u32_e32 v166, 0xe000, v166
.LdsA_skip_5:
	v_mfma_f32_16x16x32_bf16 v[38:41], v[216:219], v[176:179], v[38:41]
	v_mfma_f32_16x16x32_bf16 v[30:33], v[230:233], v[176:179], v[30:33]
	v_mfma_f32_16x16x32_bf16 v[22:25], v[216:219], v[184:187], v[22:25]
	v_mfma_f32_16x16x32_bf16 v[14:17], v[230:233], v[184:187], v[14:17]
	v_mfma_f32_16x16x32_bf16 v[6:9], v[216:219], v[208:211], v[6:9]
	v_mfma_f32_16x16x32_bf16 v[2:5], v[230:233], v[208:211], v[2:5]
	v_mfma_f32_16x16x32_bf16 v[54:57], v[226:229], v[172:175], v[54:57]
	v_mfma_f32_16x16x32_bf16 v[46:49], v[234:237], v[172:175], v[46:49]
	v_mfma_f32_16x16x32_bf16 v[38:41], v[226:229], v[180:183], v[38:41]
	v_mfma_f32_16x16x32_bf16 v[30:33], v[234:237], v[180:183], v[30:33]
	v_mfma_f32_16x16x32_bf16 v[22:25], v[226:229], v[204:207], v[22:25]
	v_mfma_f32_16x16x32_bf16 v[14:17], v[234:237], v[204:207], v[14:17]
	v_mfma_f32_16x16x32_bf16 v[6:9], v[226:229], v[212:215], v[6:9]
	v_mfma_f32_16x16x32_bf16 v[2:5], v[234:237], v[212:215], v[2:5]
	s_setprio 0
	s_add_i32 s58, 0, 0x18000
	v_add_u32_e32 v153, s58, v149
	s_barrier
	ds_read_b128 v[140:143], v153
	ds_read_b128 v[144:147], v153 offset:1024
	ds_read_b128 v[154:157], v153 offset:2048
	ds_read_b128 v[158:161], v153 offset:3072
	s_add_u32 s36, s36, 0x40000
	s_addc_u32 s37, s37, 0
	s_mov_b32 m0, s49
	ds_read_b128 v[168:171], v152 offset:32768
	ds_read_b128 v[172:175], v152 offset:33792
	ds_read_b128 v[176:179], v152 offset:34816
	ds_read_b128 v[180:183], v152 offset:35840
	ds_read_b128 v[184:187], v152 offset:36864
	ds_read_b128 v[204:207], v152 offset:37888
	ds_read_b128 v[208:211], v152 offset:38912
	ds_read_b128 v[212:215], v152 offset:39936
	global_load_lds_dwordx4 v134, s[36:37]
	s_mov_b32 m0, s54
	s_nop 0
	global_load_lds_dwordx4 v132, s[36:37]
	s_waitcnt lgkmcnt(8)
	s_barrier
; #define PG8_STAGE(bufoff, gbase, voff) do { _Pragma("unroll") for (int _i = 0; _i < 2; ++_i) \
;         __builtin_amdgcn_global_load_lds((const unsigned*)((const char*)(gbase) + (voff)[_i]), (LAS unsigned*)(lds + (bufoff) + ldsw + _i * 8192), 16, 0, 0); } while (0)
; #define PG8_LDA(dst, b, h) do { _Pragma("unroll") for (int m = 0; m < 4; ++m) _Pragma("unroll") for (int k = 0; k < 2; ++k) dst[m][k] = *(const LAS bf16x8*)(lds + PG8_SA(b, h) + aoff + m * 2048 + k * 1024); } while (0)
; #define PG8_LDB(dst, b, h) do { _Pragma("unroll") for (int n = 0; n < 2; ++n) _Pragma("unroll") for (int k = 0; k < 2; ++k) dst[n][k] = *(const LAS bf16x8*)(lds + PG8_SB(b, h) + boff + n * 2048 + k * 1024); } while (0)
; #define PG8_WAIT_V(n) asm volatile("s_waitcnt vmcnt(" #n ")" ::: "memory")
; #define PG8_WAIT_L(n) asm volatile("s_waitcnt lgkmcnt(" #n ")" ::: "memory")
; #define PG8_BAR __builtin_amdgcn_s_barrier()
; #define PG8_SCHED __builtin_amdgcn_sched_barrier(0)
; template <class Epi>
; __device__ __forceinline__ void gemm_phase(LAS unsigned char* lds, const Gemm g, const StaticOrder& S, const Epi& E) {
;     ...
;             PG8_LDB(B0, 0, 0); PG8_SCHED; PG8_LDA(At, 0, 0); PG8_STAGE(PG8_SA(1, 1), a1 + hstep, voffA);
;             PG8_WAIT_L(8); PG8_BAR; PG8_WAIT_L(0); PG8_MMA(0, 0, At, B0); PG8_BAR; PG8_SCHED;
;             PG8_LDB(B1, 0, 1); PG8_STAGE(PG8_SB(0, 0), b2, voffB);
;             PG8_BAR; PG8_WAIT_L(0); PG8_MMA(0, 1, At, B1); PG8_BAR;
;             PG8_LDA(At, 0, 1); PG8_STAGE(PG8_SA(0, 0), a2, voffA);
;             PG8_BAR; PG8_WAIT_L(0); PG8_MMA(1, 0, At, B0); PG8_BAR; PG8_SCHED;
;             PG8_STAGE(PG8_SB(0, 1), b2 + hstep, voffB);
;             PG8_WAIT_V(6); PG8_BAR; PG8_MMA(1, 1, At, B1); PG8_BAR;
;             PG8_LDB(B0, 1, 0); PG8_SCHED; PG8_LDA(At, 1, 0); PG8_STAGE(PG8_SA(0, 1), a2 + hstep, voffA);
;             PG8_WAIT_L(8); PG8_BAR; PG8_WAIT_L(0); PG8_MMA(0, 0, At, B0); PG8_BAR; PG8_SCHED;
;             PG8_LDB(B1, 1, 1); PG8_STAGE(PG8_SB(1, 0), b3, voffB);
;             PG8_BAR; PG8_WAIT_L(0); PG8_MMA(0, 1, At, B1); PG8_BAR;
;             PG8_LDA(At, 1, 1); PG8_STAGE(PG8_SA(1, 0), a3, voffA);
;             PG8_BAR; PG8_WAIT_L(0); PG8_MMA(1, 0, At, B0); PG8_BAR; PG8_SCHED;
;             PG8_STAGE(PG8_SB(1, 1), b3 + hstep, voffB);
;             PG8_WAIT_V(6); PG8_BAR; PG8_MMA(1, 1, At, B1); PG8_BAR;
	s_waitcnt lgkmcnt(0)
	s_setprio 1
	s_waitcnt lgkmcnt(0)
	v_mfma_f32_16x16x32_bf16 v[126:129], v[140:143], v[168:171], v[126:129]
	v_mfma_f32_16x16x32_bf16 v[122:125], v[154:157], v[168:171], v[122:125]
	v_mfma_f32_16x16x32_bf16 v[114:117], v[140:143], v[176:179], v[114:117]
	v_mfma_f32_16x16x32_bf16 v[106:109], v[154:157], v[176:179], v[106:109]
	v_mfma_f32_16x16x32_bf16 v[98:101], v[140:143], v[184:187], v[98:101]
	v_mfma_f32_16x16x32_bf16 v[90:93], v[154:157], v[184:187], v[90:93]
	v_mfma_f32_16x16x32_bf16 v[82:85], v[140:143], v[208:211], v[82:85]
	v_mfma_f32_16x16x32_bf16 v[74:77], v[154:157], v[208:211], v[74:77]
	v_mfma_f32_16x16x32_bf16 v[126:129], v[144:147], v[172:175], v[126:129]
	v_mfma_f32_16x16x32_bf16 v[122:125], v[158:161], v[172:175], v[122:125]
	v_mfma_f32_16x16x32_bf16 v[114:117], v[144:147], v[180:183], v[114:117]
	v_mfma_f32_16x16x32_bf16 v[106:109], v[158:161], v[180:183], v[106:109]
	v_mfma_f32_16x16x32_bf16 v[98:101], v[144:147], v[204:207], v[98:101]
	v_mfma_f32_16x16x32_bf16 v[90:93], v[158:161], v[204:207], v[90:93]
	v_mfma_f32_16x16x32_bf16 v[82:85], v[144:147], v[212:215], v[82:85]
	v_mfma_f32_16x16x32_bf16 v[74:77], v[158:161], v[212:215], v[74:77]
	s_setprio 0
	s_barrier
	s_add_i32 s36, 0, 0x1c000
	s_add_i32 s37, s58, s44
	v_add_u32_e32 v153, s36, v149
	s_add_u32 s60, s6, 0x80
	s_addc_u32 s61, s7, 0
	s_mov_b32 m0, s37
	ds_read_b128 v[216:219], v153
	ds_read_b128 v[226:229], v153 offset:1024
	ds_read_b128 v[230:233], v153 offset:2048
	ds_read_b128 v[234:237], v153 offset:3072
	global_load_lds_dwordx4 v0, s[60:61]
	s_add_i32 m0, s37, 0x2000
	s_nop 0
	global_load_lds_dwordx4 v130, s[60:61]
	s_barrier
	s_waitcnt lgkmcnt(0)
	s_setprio 1
	s_waitcnt lgkmcnt(0)
	v_mfma_f32_16x16x32_bf16 v[118:121], v[216:219], v[168:171], v[118:121]
	v_mfma_f32_16x16x32_bf16 v[110:113], v[230:233], v[168:171], v[110:113]
	v_mfma_f32_16x16x32_bf16 v[102:105], v[216:219], v[176:179], v[102:105]
	v_mfma_f32_16x16x32_bf16 v[94:97], v[230:233], v[176:179], v[94:97]
	v_mfma_f32_16x16x32_bf16 v[86:89], v[216:219], v[184:187], v[86:89]
	v_mfma_f32_16x16x32_bf16 v[78:81], v[230:233], v[184:187], v[78:81]
	v_mfma_f32_16x16x32_bf16 v[70:73], v[216:219], v[208:211], v[70:73]
	v_mfma_f32_16x16x32_bf16 v[66:69], v[230:233], v[208:211], v[66:69]
	v_mfma_f32_16x16x32_bf16 v[118:121], v[226:229], v[172:175], v[118:121]
	v_mfma_f32_16x16x32_bf16 v[110:113], v[234:237], v[172:175], v[110:113]
	v_mfma_f32_16x16x32_bf16 v[102:105], v[226:229], v[180:183], v[102:105]
	v_mfma_f32_16x16x32_bf16 v[94:97], v[234:237], v[180:183], v[94:97]
	v_mfma_f32_16x16x32_bf16 v[86:89], v[226:229], v[204:207], v[86:89]
	v_mfma_f32_16x16x32_bf16 v[78:81], v[234:237], v[204:207], v[78:81]
	v_mfma_f32_16x16x32_bf16 v[70:73], v[226:229], v[212:215], v[70:73]
	v_mfma_f32_16x16x32_bf16 v[66:69], v[234:237], v[212:215], v[66:69]
	s_setprio 0
	s_mov_b32 m0, s55
	s_barrier
	ds_read_b128 v[168:171], v152 offset:49152
	ds_read_b128 v[172:175], v152 offset:50176
	ds_read_b128 v[176:179], v152 offset:51200
	ds_read_b128 v[180:183], v152 offset:52224
	ds_read_b128 v[184:187], v152 offset:53248
	ds_read_b128 v[204:207], v152 offset:54272
	ds_read_b128 v[208:211], v152 offset:55296
	ds_read_b128 v[212:215], v152 offset:56320
	global_load_lds_dwordx4 v134, vcc
	s_mov_b32 m0, s83
	s_nop 0
	global_load_lds_dwordx4 v132, vcc
	s_barrier
	s_waitcnt lgkmcnt(0)
	s_setprio 1
	s_waitcnt lgkmcnt(0)
	v_mfma_f32_16x16x32_bf16 v[62:65], v[140:143], v[168:171], v[62:65]
	v_mfma_f32_16x16x32_bf16 v[58:61], v[154:157], v[168:171], v[58:61]
	v_mfma_f32_16x16x32_bf16 v[50:53], v[140:143], v[176:179], v[50:53]
	v_mfma_f32_16x16x32_bf16 v[42:45], v[154:157], v[176:179], v[42:45]
	v_mfma_f32_16x16x32_bf16 v[34:37], v[140:143], v[184:187], v[34:37]
	v_mfma_f32_16x16x32_bf16 v[26:29], v[154:157], v[184:187], v[26:29]
	v_mfma_f32_16x16x32_bf16 v[18:21], v[140:143], v[208:211], v[18:21]
	v_mfma_f32_16x16x32_bf16 v[10:13], v[154:157], v[208:211], v[10:13]
	v_mfma_f32_16x16x32_bf16 v[62:65], v[144:147], v[172:175], v[62:65]
	v_mfma_f32_16x16x32_bf16 v[58:61], v[158:161], v[172:175], v[58:61]
	v_mfma_f32_16x16x32_bf16 v[50:53], v[144:147], v[180:183], v[50:53]
	v_mfma_f32_16x16x32_bf16 v[42:45], v[158:161], v[180:183], v[42:45]
	v_mfma_f32_16x16x32_bf16 v[34:37], v[144:147], v[204:207], v[34:37]
	v_mfma_f32_16x16x32_bf16 v[26:29], v[158:161], v[204:207], v[26:29]
	v_mfma_f32_16x16x32_bf16 v[18:21], v[144:147], v[212:215], v[18:21]
	v_mfma_f32_16x16x32_bf16 v[10:13], v[158:161], v[212:215], v[10:13]
	s_setprio 0
	s_barrier
	s_add_u32 s6, s6, 0x40080
	s_addc_u32 s7, s7, 0
	s_add_i32 s36, s36, s44
	s_mov_b32 m0, s36
	s_nop 0
	global_load_lds_dwordx4 v0, s[6:7]
	s_add_i32 m0, s36, 0x2000
	s_nop 0
	global_load_lds_dwordx4 v130, s[6:7]
	s_waitcnt vmcnt(6)
	s_barrier
	s_setprio 1
	v_mfma_f32_16x16x32_bf16 v[54:57], v[216:219], v[168:171], v[54:57]
	v_mfma_f32_16x16x32_bf16 v[46:49], v[230:233], v[168:171], v[46:49]
	v_mfma_f32_16x16x32_bf16 v[38:41], v[216:219], v[176:179], v[38:41]
	v_mfma_f32_16x16x32_bf16 v[30:33], v[230:233], v[176:179], v[30:33]
	v_mfma_f32_16x16x32_bf16 v[22:25], v[216:219], v[184:187], v[22:25]
	v_mfma_f32_16x16x32_bf16 v[14:17], v[230:233], v[184:187], v[14:17]
	v_mfma_f32_16x16x32_bf16 v[6:9], v[216:219], v[208:211], v[6:9]
	v_mfma_f32_16x16x32_bf16 v[2:5], v[230:233], v[208:211], v[2:5]
	v_mfma_f32_16x16x32_bf16 v[54:57], v[226:229], v[172:175], v[54:57]
	v_mfma_f32_16x16x32_bf16 v[46:49], v[234:237], v[172:175], v[46:49]
	v_mfma_f32_16x16x32_bf16 v[38:41], v[226:229], v[180:183], v[38:41]
	v_mfma_f32_16x16x32_bf16 v[30:33], v[234:237], v[180:183], v[30:33]
	v_mfma_f32_16x16x32_bf16 v[22:25], v[226:229], v[204:207], v[22:25]
	v_mfma_f32_16x16x32_bf16 v[14:17], v[234:237], v[204:207], v[14:17]
	v_mfma_f32_16x16x32_bf16 v[6:9], v[226:229], v[212:215], v[6:9]
	v_mfma_f32_16x16x32_bf16 v[2:5], v[234:237], v[212:215], v[2:5]
	s_setprio 0
	s_add_i32 s91, s91, 2
	s_add_u32 s24, s24, 0x100
	s_addc_u32 s25, s25, 0
	s_add_u32 s89, s89, 0x100
	s_addc_u32 s90, s90, 0
	s_cmp_gt_u32 s91, 13
	s_barrier
; __device__ __forceinline__ unsigned pk2(float lo, float hi) { unsigned r; asm("v_cvt_pk_bf16_f32 %0, %1, %2" : "=v"(r) : "v"(lo), "v"(hi)); return r; }
; #define PG8_LDA(dst, b, h) do { _Pragma("unroll") for (int m = 0; m < 4; ++m) _Pragma("unroll") for (int k = 0; k < 2; ++k) dst[m][k] = *(const LAS bf16x8*)(lds + PG8_SA(b, h) + aoff + m * 2048 + k * 1024); } while (0)
;     __device__ __forceinline__ void operator()(const f32x4 (&acc)[2][2][4][2], const Unit& u, int ui, int wr, int wc, int fr, int fq) const {
;     ...
;                     u32x4 w; w.x = pk2(v0[0], v0[1]); w.y = pk2(v0[2], v0[3]); w.z = pk2(v1[0], v1[1]); w.w = pk2(v1[2], v1[3]);
;                     *(u32x4*)(rowp + bj * HALF) = w;
; template <class Epi>
; __device__ __forceinline__ void gemm_phase(LAS unsigned char* lds, const Gemm g, const StaticOrder& S, const Epi& E) {
;     ...
;             const char* a1 = cA + (size_t)(t + 1) * kstep;
;             const char* a2 = last ? nA : cA + (size_t)(t + 2) * kstep; const char* b2 = last ? nB : cB + (size_t)(t + 2) * kstep;
;             const char* a3 = a2 + kstep; const char* b3 = b2 + kstep;
;             PG8_LDB(B0, 0, 0); PG8_SCHED; PG8_LDA(At, 0, 0); PG8_STAGE(PG8_SA(1, 1), a1 + hstep, voffA);
;             PG8_WAIT_L(8); PG8_BAR; PG8_WAIT_L(0); PG8_MMA(0, 0, At, B0); PG8_BAR; PG8_SCHED;
;             PG8_LDB(B1, 0, 1); PG8_STAGE(PG8_SB(0, 0), b2, voffB);
;             PG8_BAR; PG8_WAIT_L(0); PG8_MMA(0, 1, At, B1); PG8_BAR;
;             PG8_LDA(At, 0, 1); PG8_STAGE(PG8_SA(0, 0), a2, voffA);
;             PG8_BAR; PG8_WAIT_L(0); PG8_MMA(1, 0, At, B0); PG8_BAR; PG8_SCHED;
;             PG8_STAGE(PG8_SB(0, 1), b2 + hstep, voffB);
;             PG8_WAIT_V(6); PG8_BAR; PG8_MMA(1, 1, At, B1); PG8_BAR;
;             PG8_LDB(B0, 1, 0); PG8_SCHED; PG8_LDA(At, 1, 0); PG8_STAGE(PG8_SA(0, 1), a2 + hstep, voffA);
;             PG8_WAIT_L(8); PG8_BAR; PG8_WAIT_L(0); PG8_MMA(0, 0, At, B0); PG8_BAR; PG8_SCHED;
;             PG8_LDB(B1, 1, 1); PG8_STAGE(PG8_SB(1, 0), b3, voffB);
;             PG8_BAR; PG8_WAIT_L(0); PG8_MMA(0, 1, At, B1); PG8_BAR;
;             PG8_LDA(At, 1, 1); PG8_STAGE(PG8_SA(1, 0), a3, voffA);
;             PG8_BAR; PG8_WAIT_L(0); PG8_MMA(1, 0, At, B0); PG8_BAR; PG8_SCHED;
;             PG8_STAGE(PG8_SB(1, 1), b3 + hstep, voffB);
;             PG8_WAIT_V(6); PG8_BAR; PG8_MMA(1, 1, At, B1); PG8_BAR;
	s_add_u32 s6, s24, 0xfffc0080
	s_addc_u32 s7, s25, -1
	s_add_i32 s58, 0, 0x10000
	v_add_u32_e32 v153, s58, v149
	ds_read_b128 v[140:143], v153
	ds_read_b128 v[144:147], v153 offset:1024
	ds_read_b128 v[154:157], v153 offset:2048
	ds_read_b128 v[158:161], v153 offset:3072
	s_cmp_eq_u32 s91, 12
	s_cselect_b32 s37, s11, s7
	s_cselect_b32 s36, s71, s6
	s_cselect_b32 s7, s9, s90
	s_cselect_b32 s6, s88, s89
	s_add_i32 m0, s47, 0xc000
	ds_read_b128 v[168:171], v152
	ds_read_b128 v[172:175], v152 offset:1024
	ds_read_b128 v[176:179], v152 offset:2048
	ds_read_b128 v[180:183], v152 offset:3072
	ds_read_b128 v[184:187], v152 offset:4096
	ds_read_b128 v[204:207], v152 offset:5120
	ds_read_b128 v[208:211], v152 offset:6144
	ds_read_b128 v[212:215], v152 offset:7168
	global_load_lds_dwordx4 v136, s[24:25]
	s_add_i32 m0, s47, 0xe000
	s_nop 0
	global_load_lds_dwordx4 v138, s[24:25]
	s_waitcnt lgkmcnt(8)
	s_barrier
	s_waitcnt lgkmcnt(0)
	s_setprio 1
	s_waitcnt lgkmcnt(0)
	v_mfma_f32_16x16x32_bf16 v[126:129], v[140:143], v[168:171], v[126:129]
	v_mfma_f32_16x16x32_bf16 v[122:125], v[154:157], v[168:171], v[122:125]
	v_mfma_f32_16x16x32_bf16 v[114:117], v[140:143], v[176:179], v[114:117]
	v_mfma_f32_16x16x32_bf16 v[106:109], v[154:157], v[176:179], v[106:109]
	v_mfma_f32_16x16x32_bf16 v[98:101], v[140:143], v[184:187], v[98:101]
	v_mfma_f32_16x16x32_bf16 v[90:93], v[154:157], v[184:187], v[90:93]
	v_mfma_f32_16x16x32_bf16 v[82:85], v[140:143], v[208:211], v[82:85]
	v_mfma_f32_16x16x32_bf16 v[74:77], v[154:157], v[208:211], v[74:77]
	v_mfma_f32_16x16x32_bf16 v[126:129], v[144:147], v[172:175], v[126:129]
	v_mfma_f32_16x16x32_bf16 v[122:125], v[158:161], v[172:175], v[122:125]
	v_mfma_f32_16x16x32_bf16 v[114:117], v[144:147], v[180:183], v[114:117]
	v_mfma_f32_16x16x32_bf16 v[106:109], v[158:161], v[180:183], v[106:109]
	v_mfma_f32_16x16x32_bf16 v[98:101], v[144:147], v[204:207], v[98:101]
	v_mfma_f32_16x16x32_bf16 v[90:93], v[158:161], v[204:207], v[90:93]
	v_mfma_f32_16x16x32_bf16 v[82:85], v[144:147], v[212:215], v[82:85]
	v_mfma_f32_16x16x32_bf16 v[74:77], v[158:161], v[212:215], v[74:77]
	s_setprio 0
	s_barrier
	s_add_i32 s70, 0, 0x14000
	s_add_i32 s58, s58, s44
	v_add_u32_e32 v153, s70, v149
	s_mov_b32 m0, s58
	ds_read_b128 v[216:219], v153
	ds_read_b128 v[226:229], v153 offset:1024
	ds_read_b128 v[230:233], v153 offset:2048
	ds_read_b128 v[234:237], v153 offset:3072
	global_load_lds_dwordx4 v0, s[6:7]
	s_add_i32 m0, s58, 0x2000
	s_nop 0
	global_load_lds_dwordx4 v130, s[6:7]
	s_barrier
	s_waitcnt lgkmcnt(0)
	s_setprio 1
	s_waitcnt lgkmcnt(0)
	v_mfma_f32_16x16x32_bf16 v[118:121], v[216:219], v[168:171], v[118:121]
	v_mfma_f32_16x16x32_bf16 v[110:113], v[230:233], v[168:171], v[110:113]
	v_mfma_f32_16x16x32_bf16 v[102:105], v[216:219], v[176:179], v[102:105]
	v_mfma_f32_16x16x32_bf16 v[94:97], v[230:233], v[176:179], v[94:97]
	v_mfma_f32_16x16x32_bf16 v[86:89], v[216:219], v[184:187], v[86:89]
	v_mfma_f32_16x16x32_bf16 v[78:81], v[230:233], v[184:187], v[78:81]
	v_mfma_f32_16x16x32_bf16 v[70:73], v[216:219], v[208:211], v[70:73]
	v_mfma_f32_16x16x32_bf16 v[66:69], v[230:233], v[208:211], v[66:69]
	v_mfma_f32_16x16x32_bf16 v[118:121], v[226:229], v[172:175], v[118:121]
	v_mfma_f32_16x16x32_bf16 v[110:113], v[234:237], v[172:175], v[110:113]
	v_mfma_f32_16x16x32_bf16 v[102:105], v[226:229], v[180:183], v[102:105]
	v_mfma_f32_16x16x32_bf16 v[94:97], v[234:237], v[180:183], v[94:97]
	v_mfma_f32_16x16x32_bf16 v[86:89], v[226:229], v[204:207], v[86:89]
	v_mfma_f32_16x16x32_bf16 v[78:81], v[234:237], v[204:207], v[78:81]
	v_mfma_f32_16x16x32_bf16 v[70:73], v[226:229], v[212:215], v[70:73]
	v_mfma_f32_16x16x32_bf16 v[66:69], v[234:237], v[212:215], v[66:69]
	s_setprio 0
	s_mov_b32 m0, s47
	s_add_u32 vcc_lo, s36, 0x80
	s_addc_u32 vcc_hi, s37, 0
	s_barrier
	ds_read_b128 v[168:171], v152 offset:16384
	ds_read_b128 v[172:175], v152 offset:17408
	ds_read_b128 v[176:179], v152 offset:18432
	ds_read_b128 v[180:183], v152 offset:19456
	ds_read_b128 v[184:187], v152 offset:20480
	ds_read_b128 v[204:207], v152 offset:21504
	ds_read_b128 v[208:211], v152 offset:22528
	ds_read_b128 v[212:215], v152 offset:23552
	global_load_lds_dwordx4 v134, s[36:37]
	s_mov_b32 m0, s48
	s_nop 0
	global_load_lds_dwordx4 v132, s[36:37]
	s_barrier
	s_waitcnt lgkmcnt(0)
	s_setprio 1
	s_waitcnt lgkmcnt(0)
	v_mfma_f32_16x16x32_bf16 v[62:65], v[140:143], v[168:171], v[62:65]
	v_mfma_f32_16x16x32_bf16 v[58:61], v[154:157], v[168:171], v[58:61]
	v_mfma_f32_16x16x32_bf16 v[50:53], v[140:143], v[176:179], v[50:53]
	v_mfma_f32_16x16x32_bf16 v[42:45], v[154:157], v[176:179], v[42:45]
	v_mfma_f32_16x16x32_bf16 v[34:37], v[140:143], v[184:187], v[34:37]
	v_mfma_f32_16x16x32_bf16 v[26:29], v[154:157], v[184:187], v[26:29]
	v_mfma_f32_16x16x32_bf16 v[18:21], v[140:143], v[208:211], v[18:21]
	v_mfma_f32_16x16x32_bf16 v[10:13], v[154:157], v[208:211], v[10:13]
	v_mfma_f32_16x16x32_bf16 v[62:65], v[144:147], v[172:175], v[62:65]
	v_mfma_f32_16x16x32_bf16 v[58:61], v[158:161], v[172:175], v[58:61]
	v_mfma_f32_16x16x32_bf16 v[50:53], v[144:147], v[180:183], v[50:53]
	v_mfma_f32_16x16x32_bf16 v[42:45], v[158:161], v[180:183], v[42:45]
	v_mfma_f32_16x16x32_bf16 v[34:37], v[144:147], v[204:207], v[34:37]
	v_mfma_f32_16x16x32_bf16 v[26:29], v[158:161], v[204:207], v[26:29]
	v_mfma_f32_16x16x32_bf16 v[18:21], v[144:147], v[212:215], v[18:21]
	v_mfma_f32_16x16x32_bf16 v[10:13], v[158:161], v[212:215], v[10:13]
	s_setprio 0
	s_barrier
	s_add_u32 s60, s6, 0x40000
	s_addc_u32 s61, s7, 0
	s_add_i32 s58, s70, s44
	s_mov_b32 m0, s58
	s_nop 0
	global_load_lds_dwordx4 v0, s[60:61]
	s_add_i32 m0, s58, 0x2000
	s_nop 0
	global_load_lds_dwordx4 v130, s[60:61]
	s_waitcnt vmcnt(6)
	s_barrier
	s_setprio 1
	v_mfma_f32_16x16x32_bf16 v[54:57], v[216:219], v[168:171], v[54:57]
	v_mfma_f32_16x16x32_bf16 v[46:49], v[230:233], v[168:171], v[46:49]
	s_cmp_eq_u32 s87, 0
	s_cbranch_scc1 .LdsA_skip_6
	global_store_dwordx4 v166, v[244:247], s[4:5]
; #define PG8_STAGE(bufoff, gbase, voff) do { _Pragma("unroll") for (int _i = 0; _i < 2; ++_i) \
;         __builtin_amdgcn_global_load_lds((const unsigned*)((const char*)(gbase) + (voff)[_i]), (LAS unsigned*)(lds + (bufoff) + ldsw + _i * 8192), 16, 0, 0); } while (0)
; #define PG8_LDA(dst, b, h) do { _Pragma("unroll") for (int m = 0; m < 4; ++m) _Pragma("unroll") for (int k = 0; k < 2; ++k) dst[m][k] = *(const LAS bf16x8*)(lds + PG8_SA(b, h) + aoff + m * 2048 + k * 1024); } while (0)
; #define PG8_LDB(dst, b, h) do { _Pragma("unroll") for (int n = 0; n < 2; ++n) _Pragma("unroll") for (int k = 0; k < 2; ++k) dst[n][k] = *(const LAS bf16x8*)(lds + PG8_SB(b, h) + boff + n * 2048 + k * 1024); } while (0)
; #define PG8_WAIT_V(n) asm volatile("s_waitcnt vmcnt(" #n ")" ::: "memory")
; #define PG8_WAIT_L(n) asm volatile("s_waitcnt lgkmcnt(" #n ")" ::: "memory")
; #define PG8_BAR __builtin_amdgcn_s_barrier()
; #define PG8_SCHED __builtin_amdgcn_sched_barrier(0)
; template <class Epi>
; __device__ __forceinline__ void gemm_phase(LAS unsigned char* lds, const Gemm g, const StaticOrder& S, const Epi& E) {
;     ...
;             PG8_LDB(B0, 0, 0); PG8_SCHED; PG8_LDA(At, 0, 0); PG8_STAGE(PG8_SA(1, 1), a1 + hstep, voffA);
;             PG8_WAIT_L(8); PG8_BAR; PG8_WAIT_L(0); PG8_MMA(0, 0, At, B0); PG8_BAR; PG8_SCHED;
;             PG8_LDB(B1, 0, 1); PG8_STAGE(PG8_SB(0, 0), b2, voffB);
;             PG8_BAR; PG8_WAIT_L(0); PG8_MMA(0, 1, At, B1); PG8_BAR;
;             PG8_LDA(At, 0, 1); PG8_STAGE(PG8_SA(0, 0), a2, voffA);
;             PG8_BAR; PG8_WAIT_L(0); PG8_MMA(1, 0, At, B0); PG8_BAR; PG8_SCHED;
;             PG8_STAGE(PG8_SB(0, 1), b2 + hstep, voffB);
;             PG8_WAIT_V(6); PG8_BAR; PG8_MMA(1, 1, At, B1); PG8_BAR;
;             PG8_LDB(B0, 1, 0); PG8_SCHED; PG8_LDA(At, 1, 0); PG8_STAGE(PG8_SA(0, 1), a2 + hstep, voffA);
;             PG8_WAIT_L(8); PG8_BAR; PG8_WAIT_L(0); PG8_MMA(0, 0, At, B0); PG8_BAR; PG8_SCHED;
;             PG8_LDB(B1, 1, 1); PG8_STAGE(PG8_SB(1, 0), b3, voffB);
;             PG8_BAR; PG8_WAIT_L(0); PG8_MMA(0, 1, At, B1); PG8_BAR;
;             PG8_LDA(At, 1, 1); PG8_STAGE(PG8_SA(1, 0), a3, voffA);
;             PG8_BAR; PG8_WAIT_L(0); PG8_MMA(1, 0, At, B0); PG8_BAR; PG8_SCHED;
;             PG8_STAGE(PG8_SB(1, 1), b3 + hstep, voffB);
;             PG8_WAIT_V(6); PG8_BAR; PG8_MMA(1, 1, At, B1); PG8_BAR;
.LdsA_skip_6:
	v_mfma_f32_16x16x32_bf16 v[38:41], v[216:219], v[176:179], v[38:41]
	v_mfma_f32_16x16x32_bf16 v[30:33], v[230:233], v[176:179], v[30:33]
	v_mfma_f32_16x16x32_bf16 v[22:25], v[216:219], v[184:187], v[22:25]
	v_mfma_f32_16x16x32_bf16 v[14:17], v[230:233], v[184:187], v[14:17]
	v_mfma_f32_16x16x32_bf16 v[6:9], v[216:219], v[208:211], v[6:9]
	v_mfma_f32_16x16x32_bf16 v[2:5], v[230:233], v[208:211], v[2:5]
	v_mfma_f32_16x16x32_bf16 v[54:57], v[226:229], v[172:175], v[54:57]
	v_mfma_f32_16x16x32_bf16 v[46:49], v[234:237], v[172:175], v[46:49]
	v_mfma_f32_16x16x32_bf16 v[38:41], v[226:229], v[180:183], v[38:41]
	v_mfma_f32_16x16x32_bf16 v[30:33], v[234:237], v[180:183], v[30:33]
	v_mfma_f32_16x16x32_bf16 v[22:25], v[226:229], v[204:207], v[22:25]
	v_mfma_f32_16x16x32_bf16 v[14:17], v[234:237], v[204:207], v[14:17]
	v_mfma_f32_16x16x32_bf16 v[6:9], v[226:229], v[212:215], v[6:9]
	v_mfma_f32_16x16x32_bf16 v[2:5], v[234:237], v[212:215], v[2:5]
	s_setprio 0
	s_add_i32 s58, 0, 0x18000
	v_add_u32_e32 v153, s58, v149
	s_barrier
	ds_read_b128 v[140:143], v153
	ds_read_b128 v[144:147], v153 offset:1024
	ds_read_b128 v[154:157], v153 offset:2048
	ds_read_b128 v[158:161], v153 offset:3072
	s_add_u32 s36, s36, 0x40000
	s_addc_u32 s37, s37, 0
	s_mov_b32 m0, s49
	ds_read_b128 v[168:171], v152 offset:32768
	ds_read_b128 v[172:175], v152 offset:33792
	ds_read_b128 v[176:179], v152 offset:34816
	ds_read_b128 v[180:183], v152 offset:35840
	ds_read_b128 v[184:187], v152 offset:36864
	ds_read_b128 v[204:207], v152 offset:37888
	ds_read_b128 v[208:211], v152 offset:38912
	ds_read_b128 v[212:215], v152 offset:39936
	global_load_lds_dwordx4 v134, s[36:37]
	s_mov_b32 m0, s54
	s_nop 0
	global_load_lds_dwordx4 v132, s[36:37]
	s_waitcnt lgkmcnt(8)
	s_barrier
	s_waitcnt lgkmcnt(0)
	s_setprio 1
	s_waitcnt lgkmcnt(0)
	v_mfma_f32_16x16x32_bf16 v[126:129], v[140:143], v[168:171], v[126:129]
	v_mfma_f32_16x16x32_bf16 v[122:125], v[154:157], v[168:171], v[122:125]
	v_mfma_f32_16x16x32_bf16 v[114:117], v[140:143], v[176:179], v[114:117]
	v_mfma_f32_16x16x32_bf16 v[106:109], v[154:157], v[176:179], v[106:109]
	v_mfma_f32_16x16x32_bf16 v[98:101], v[140:143], v[184:187], v[98:101]
	v_mfma_f32_16x16x32_bf16 v[90:93], v[154:157], v[184:187], v[90:93]
	v_mfma_f32_16x16x32_bf16 v[82:85], v[140:143], v[208:211], v[82:85]
	v_mfma_f32_16x16x32_bf16 v[74:77], v[154:157], v[208:211], v[74:77]
	v_mfma_f32_16x16x32_bf16 v[126:129], v[144:147], v[172:175], v[126:129]
	v_mfma_f32_16x16x32_bf16 v[122:125], v[158:161], v[172:175], v[122:125]
	v_mfma_f32_16x16x32_bf16 v[114:117], v[144:147], v[180:183], v[114:117]
	v_mfma_f32_16x16x32_bf16 v[106:109], v[158:161], v[180:183], v[106:109]
	v_mfma_f32_16x16x32_bf16 v[98:101], v[144:147], v[204:207], v[98:101]
	v_mfma_f32_16x16x32_bf16 v[90:93], v[158:161], v[204:207], v[90:93]
	v_mfma_f32_16x16x32_bf16 v[82:85], v[144:147], v[212:215], v[82:85]
	v_mfma_f32_16x16x32_bf16 v[74:77], v[158:161], v[212:215], v[74:77]
	s_setprio 0
	s_barrier
	s_add_i32 s36, 0, 0x1c000
	s_add_i32 s37, s58, s44
	v_add_u32_e32 v153, s36, v149
	s_add_u32 s60, s6, 0x80
	s_addc_u32 s61, s7, 0
	s_mov_b32 m0, s37
	ds_read_b128 v[216:219], v153
	ds_read_b128 v[226:229], v153 offset:1024
	ds_read_b128 v[230:233], v153 offset:2048
	ds_read_b128 v[234:237], v153 offset:3072
	global_load_lds_dwordx4 v0, s[60:61]
	s_add_i32 m0, s37, 0x2000
	s_nop 0
	global_load_lds_dwordx4 v130, s[60:61]
	s_barrier
	s_waitcnt lgkmcnt(0)
	s_setprio 1
	s_waitcnt lgkmcnt(0)
	v_mfma_f32_16x16x32_bf16 v[118:121], v[216:219], v[168:171], v[118:121]
	v_mfma_f32_16x16x32_bf16 v[110:113], v[230:233], v[168:171], v[110:113]
	v_mfma_f32_16x16x32_bf16 v[102:105], v[216:219], v[176:179], v[102:105]
	v_mfma_f32_16x16x32_bf16 v[94:97], v[230:233], v[176:179], v[94:97]
	v_mfma_f32_16x16x32_bf16 v[86:89], v[216:219], v[184:187], v[86:89]
	v_mfma_f32_16x16x32_bf16 v[78:81], v[230:233], v[184:187], v[78:81]
	v_mfma_f32_16x16x32_bf16 v[70:73], v[216:219], v[208:211], v[70:73]
	v_mfma_f32_16x16x32_bf16 v[66:69], v[230:233], v[208:211], v[66:69]
	v_mfma_f32_16x16x32_bf16 v[118:121], v[226:229], v[172:175], v[118:121]
	v_mfma_f32_16x16x32_bf16 v[110:113], v[234:237], v[172:175], v[110:113]
	v_mfma_f32_16x16x32_bf16 v[102:105], v[226:229], v[180:183], v[102:105]
	v_mfma_f32_16x16x32_bf16 v[94:97], v[234:237], v[180:183], v[94:97]
	v_mfma_f32_16x16x32_bf16 v[86:89], v[226:229], v[204:207], v[86:89]
	v_mfma_f32_16x16x32_bf16 v[78:81], v[234:237], v[204:207], v[78:81]
	v_mfma_f32_16x16x32_bf16 v[70:73], v[226:229], v[212:215], v[70:73]
	v_mfma_f32_16x16x32_bf16 v[66:69], v[234:237], v[212:215], v[66:69]
	s_setprio 0
	s_mov_b32 m0, s55
	s_barrier
	ds_read_b128 v[168:171], v152 offset:49152
	ds_read_b128 v[172:175], v152 offset:50176
	ds_read_b128 v[176:179], v152 offset:51200
	ds_read_b128 v[180:183], v152 offset:52224
	ds_read_b128 v[184:187], v152 offset:53248
	ds_read_b128 v[204:207], v152 offset:54272
	ds_read_b128 v[208:211], v152 offset:55296
	ds_read_b128 v[212:215], v152 offset:56320
	global_load_lds_dwordx4 v134, vcc
	s_mov_b32 m0, s83
	s_nop 0
	global_load_lds_dwordx4 v132, vcc
	s_barrier
; #define PG8_STAGE(bufoff, gbase, voff) do { _Pragma("unroll") for (int _i = 0; _i < 2; ++_i) \
;         __builtin_amdgcn_global_load_lds((const unsigned*)((const char*)(gbase) + (voff)[_i]), (LAS unsigned*)(lds + (bufoff) + ldsw + _i * 8192), 16, 0, 0); } while (0)
; #define PG8_LDA(dst, b, h) do { _Pragma("unroll") for (int m = 0; m < 4; ++m) _Pragma("unroll") for (int k = 0; k < 2; ++k) dst[m][k] = *(const LAS bf16x8*)(lds + PG8_SA(b, h) + aoff + m * 2048 + k * 1024); } while (0)
; #define PG8_LDB(dst, b, h) do { _Pragma("unroll") for (int n = 0; n < 2; ++n) _Pragma("unroll") for (int k = 0; k < 2; ++k) dst[n][k] = *(const LAS bf16x8*)(lds + PG8_SB(b, h) + boff + n * 2048 + k * 1024); } while (0)
; #define PG8_WAIT_V(n) asm volatile("s_waitcnt vmcnt(" #n ")" ::: "memory")
; #define PG8_WAIT_L(n) asm volatile("s_waitcnt lgkmcnt(" #n ")" ::: "memory")
; #define PG8_BAR __builtin_amdgcn_s_barrier()
; #define PG8_SCHED __builtin_amdgcn_sched_barrier(0)
; template <class Epi>
; __device__ __forceinline__ void gemm_phase(LAS unsigned char* lds, const Gemm g, const StaticOrder& S, const Epi& E) {
;     ...
;             PG8_LDB(B0, 0, 0); PG8_SCHED; PG8_LDA(At, 0, 0); PG8_STAGE(PG8_SA(1, 1), a1 + hstep, voffA);
;             PG8_WAIT_L(8); PG8_BAR; PG8_WAIT_L(0); PG8_MMA(0, 0, At, B0); PG8_BAR; PG8_SCHED;
;             PG8_LDB(B1, 0, 1); PG8_STAGE(PG8_SB(0, 0), b2, voffB);
;             PG8_BAR; PG8_WAIT_L(0); PG8_MMA(0, 1, At, B1); PG8_BAR;
;             PG8_LDA(At, 0, 1); PG8_STAGE(PG8_SA(0, 0), a2, voffA);
;             PG8_BAR; PG8_WAIT_L(0); PG8_MMA(1, 0, At, B0); PG8_BAR; PG8_SCHED;
;             PG8_STAGE(PG8_SB(0, 1), b2 + hstep, voffB);
;             PG8_WAIT_V(6); PG8_BAR; PG8_MMA(1, 1, At, B1); PG8_BAR;
;             PG8_LDB(B0, 1, 0); PG8_SCHED; PG8_LDA(At, 1, 0); PG8_STAGE(PG8_SA(0, 1), a2 + hstep, voffA);
;             PG8_WAIT_L(8); PG8_BAR; PG8_WAIT_L(0); PG8_MMA(0, 0, At, B0); PG8_BAR; PG8_SCHED;
;             PG8_LDB(B1, 1, 1); PG8_STAGE(PG8_SB(1, 0), b3, voffB);
;             PG8_BAR; PG8_WAIT_L(0); PG8_MMA(0, 1, At, B1); PG8_BAR;
;             PG8_LDA(At, 1, 1); PG8_STAGE(PG8_SA(1, 0), a3, voffA);
;             PG8_BAR; PG8_WAIT_L(0); PG8_MMA(1, 0, At, B0); PG8_BAR; PG8_SCHED;
;             PG8_STAGE(PG8_SB(1, 1), b3 + hstep, voffB);
;             PG8_WAIT_V(6); PG8_BAR; PG8_MMA(1, 1, At, B1); PG8_BAR;
	s_waitcnt lgkmcnt(0)
	s_setprio 1
	s_waitcnt lgkmcnt(0)
	v_mfma_f32_16x16x32_bf16 v[62:65], v[140:143], v[168:171], v[62:65]
	v_mfma_f32_16x16x32_bf16 v[58:61], v[154:157], v[168:171], v[58:61]
	v_mfma_f32_16x16x32_bf16 v[50:53], v[140:143], v[176:179], v[50:53]
	v_mfma_f32_16x16x32_bf16 v[42:45], v[154:157], v[176:179], v[42:45]
	v_mfma_f32_16x16x32_bf16 v[34:37], v[140:143], v[184:187], v[34:37]
	v_mfma_f32_16x16x32_bf16 v[26:29], v[154:157], v[184:187], v[26:29]
	v_mfma_f32_16x16x32_bf16 v[18:21], v[140:143], v[208:211], v[18:21]
	v_mfma_f32_16x16x32_bf16 v[10:13], v[154:157], v[208:211], v[10:13]
	v_mfma_f32_16x16x32_bf16 v[62:65], v[144:147], v[172:175], v[62:65]
	v_mfma_f32_16x16x32_bf16 v[58:61], v[158:161], v[172:175], v[58:61]
	v_mfma_f32_16x16x32_bf16 v[50:53], v[144:147], v[180:183], v[50:53]
	v_mfma_f32_16x16x32_bf16 v[42:45], v[158:161], v[180:183], v[42:45]
	v_mfma_f32_16x16x32_bf16 v[34:37], v[144:147], v[204:207], v[34:37]
	v_mfma_f32_16x16x32_bf16 v[26:29], v[158:161], v[204:207], v[26:29]
	v_mfma_f32_16x16x32_bf16 v[18:21], v[144:147], v[212:215], v[18:21]
	v_mfma_f32_16x16x32_bf16 v[10:13], v[158:161], v[212:215], v[10:13]
	s_setprio 0
	s_barrier
	s_add_u32 s6, s6, 0x40080
	s_addc_u32 s7, s7, 0
	s_add_i32 s36, s36, s44
	s_mov_b32 m0, s36
	s_nop 0
	global_load_lds_dwordx4 v0, s[6:7]
	s_add_i32 m0, s36, 0x2000
	s_nop 0
	global_load_lds_dwordx4 v130, s[6:7]
	s_waitcnt vmcnt(6)
	s_barrier
	s_setprio 1
	v_mfma_f32_16x16x32_bf16 v[54:57], v[216:219], v[168:171], v[54:57]
	v_mfma_f32_16x16x32_bf16 v[46:49], v[230:233], v[168:171], v[46:49]
	v_mfma_f32_16x16x32_bf16 v[38:41], v[216:219], v[176:179], v[38:41]
	v_mfma_f32_16x16x32_bf16 v[30:33], v[230:233], v[176:179], v[30:33]
	v_mfma_f32_16x16x32_bf16 v[22:25], v[216:219], v[184:187], v[22:25]
	v_mfma_f32_16x16x32_bf16 v[14:17], v[230:233], v[184:187], v[14:17]
	v_mfma_f32_16x16x32_bf16 v[6:9], v[216:219], v[208:211], v[6:9]
	v_mfma_f32_16x16x32_bf16 v[2:5], v[230:233], v[208:211], v[2:5]
	v_mfma_f32_16x16x32_bf16 v[54:57], v[226:229], v[172:175], v[54:57]
	v_mfma_f32_16x16x32_bf16 v[46:49], v[234:237], v[172:175], v[46:49]
	v_mfma_f32_16x16x32_bf16 v[38:41], v[226:229], v[180:183], v[38:41]
	v_mfma_f32_16x16x32_bf16 v[30:33], v[234:237], v[180:183], v[30:33]
	v_mfma_f32_16x16x32_bf16 v[22:25], v[226:229], v[204:207], v[22:25]
	v_mfma_f32_16x16x32_bf16 v[14:17], v[234:237], v[204:207], v[14:17]
	v_mfma_f32_16x16x32_bf16 v[6:9], v[226:229], v[212:215], v[6:9]
	v_mfma_f32_16x16x32_bf16 v[2:5], v[234:237], v[212:215], v[2:5]
	s_setprio 0
	s_add_i32 s91, s91, 2
	s_add_u32 s24, s24, 0x100
	s_addc_u32 s25, s25, 0
	s_add_u32 s89, s89, 0x100
	s_addc_u32 s90, s90, 0
	s_cmp_gt_u32 s91, 13
	s_barrier
	s_add_u32 s6, s24, 0xfffc0080
	s_addc_u32 s7, s25, -1
	s_add_i32 s58, 0, 0x10000
	v_add_u32_e32 v153, s58, v149
	ds_read_b128 v[140:143], v153
	ds_read_b128 v[144:147], v153 offset:1024
	ds_read_b128 v[154:157], v153 offset:2048
	ds_read_b128 v[158:161], v153 offset:3072
	s_cmp_eq_u32 s91, 12
	s_cselect_b32 s37, s11, s7
	s_cselect_b32 s36, s71, s6
	s_cselect_b32 s7, s9, s90
	s_cselect_b32 s6, s88, s89
	s_add_i32 m0, s47, 0xc000
	ds_read_b128 v[168:171], v152
	ds_read_b128 v[172:175], v152 offset:1024
	ds_read_b128 v[176:179], v152 offset:2048
	ds_read_b128 v[180:183], v152 offset:3072
	ds_read_b128 v[184:187], v152 offset:4096
	ds_read_b128 v[204:207], v152 offset:5120
	ds_read_b128 v[208:211], v152 offset:6144
	ds_read_b128 v[212:215], v152 offset:7168
	global_load_lds_dwordx4 v136, s[24:25]
	s_add_i32 m0, s47, 0xe000
	s_nop 0
	global_load_lds_dwordx4 v138, s[24:25]
	s_waitcnt lgkmcnt(8)
	s_barrier
	s_waitcnt lgkmcnt(0)
	s_setprio 1
	s_waitcnt lgkmcnt(0)
	v_mfma_f32_16x16x32_bf16 v[126:129], v[140:143], v[168:171], v[126:129]
	v_mfma_f32_16x16x32_bf16 v[122:125], v[154:157], v[168:171], v[122:125]
	v_mfma_f32_16x16x32_bf16 v[114:117], v[140:143], v[176:179], v[114:117]
	v_mfma_f32_16x16x32_bf16 v[106:109], v[154:157], v[176:179], v[106:109]
	v_mfma_f32_16x16x32_bf16 v[98:101], v[140:143], v[184:187], v[98:101]
	v_mfma_f32_16x16x32_bf16 v[90:93], v[154:157], v[184:187], v[90:93]
	v_mfma_f32_16x16x32_bf16 v[82:85], v[140:143], v[208:211], v[82:85]
	v_mfma_f32_16x16x32_bf16 v[74:77], v[154:157], v[208:211], v[74:77]
	v_mfma_f32_16x16x32_bf16 v[126:129], v[144:147], v[172:175], v[126:129]
	v_mfma_f32_16x16x32_bf16 v[122:125], v[158:161], v[172:175], v[122:125]
	v_mfma_f32_16x16x32_bf16 v[114:117], v[144:147], v[180:183], v[114:117]
	v_mfma_f32_16x16x32_bf16 v[106:109], v[158:161], v[180:183], v[106:109]
	v_mfma_f32_16x16x32_bf16 v[98:101], v[144:147], v[204:207], v[98:101]
	v_mfma_f32_16x16x32_bf16 v[90:93], v[158:161], v[204:207], v[90:93]
	v_mfma_f32_16x16x32_bf16 v[82:85], v[144:147], v[212:215], v[82:85]
	v_mfma_f32_16x16x32_bf16 v[74:77], v[158:161], v[212:215], v[74:77]
	s_setprio 0
	s_barrier
	s_add_i32 s70, 0, 0x14000
	s_add_i32 s58, s58, s44
	v_add_u32_e32 v153, s70, v149
	s_mov_b32 m0, s58
	ds_read_b128 v[216:219], v153
	ds_read_b128 v[226:229], v153 offset:1024
	ds_read_b128 v[230:233], v153 offset:2048
	ds_read_b128 v[234:237], v153 offset:3072
	global_load_lds_dwordx4 v0, s[6:7]
	s_add_i32 m0, s58, 0x2000
	s_nop 0
	global_load_lds_dwordx4 v130, s[6:7]
	s_barrier
; __device__ __forceinline__ unsigned pk2(float lo, float hi) { unsigned r; asm("v_cvt_pk_bf16_f32 %0, %1, %2" : "=v"(r) : "v"(lo), "v"(hi)); return r; }
; #define PG8_STAGE(bufoff, gbase, voff) do { _Pragma("unroll") for (int _i = 0; _i < 2; ++_i) \
;         __builtin_amdgcn_global_load_lds((const unsigned*)((const char*)(gbase) + (voff)[_i]), (LAS unsigned*)(lds + (bufoff) + ldsw + _i * 8192), 16, 0, 0); } while (0)
; #define PG8_LDA(dst, b, h) do { _Pragma("unroll") for (int m = 0; m < 4; ++m) _Pragma("unroll") for (int k = 0; k < 2; ++k) dst[m][k] = *(const LAS bf16x8*)(lds + PG8_SA(b, h) + aoff + m * 2048 + k * 1024); } while (0)
;     __device__ __forceinline__ void operator()(const f32x4 (&acc)[2][2][4][2], const Unit& u, int ui, int wr, int wc, int fr, int fq) const {
;     ...
;                     u32x4 w; w.x = pk2(v0[0], v0[1]); w.y = pk2(v0[2], v0[3]); w.z = pk2(v1[0], v1[1]); w.w = pk2(v1[2], v1[3]);
;                     *(u32x4*)(rowp + bj * HALF) = w;
; template <class Epi>
; __device__ __forceinline__ void gemm_phase(LAS unsigned char* lds, const Gemm g, const StaticOrder& S, const Epi& E) {
;     ...
;             PG8_LDB(B0, 0, 0); PG8_SCHED; PG8_LDA(At, 0, 0); PG8_STAGE(PG8_SA(1, 1), a1 + hstep, voffA);
;             PG8_WAIT_L(8); PG8_BAR; PG8_WAIT_L(0); PG8_MMA(0, 0, At, B0); PG8_BAR; PG8_SCHED;
;             PG8_LDB(B1, 0, 1); PG8_STAGE(PG8_SB(0, 0), b2, voffB);
;             PG8_BAR; PG8_WAIT_L(0); PG8_MMA(0, 1, At, B1); PG8_BAR;
;             PG8_LDA(At, 0, 1); PG8_STAGE(PG8_SA(0, 0), a2, voffA);
;             PG8_BAR; PG8_WAIT_L(0); PG8_MMA(1, 0, At, B0); PG8_BAR; PG8_SCHED;
;             PG8_STAGE(PG8_SB(0, 1), b2 + hstep, voffB);
;             PG8_WAIT_V(6); PG8_BAR; PG8_MMA(1, 1, At, B1); PG8_BAR;
;             PG8_LDB(B0, 1, 0); PG8_SCHED; PG8_LDA(At, 1, 0); PG8_STAGE(PG8_SA(0, 1), a2 + hstep, voffA);
;             PG8_WAIT_L(8); PG8_BAR; PG8_WAIT_L(0); PG8_MMA(0, 0, At, B0); PG8_BAR; PG8_SCHED;
;             PG8_LDB(B1, 1, 1); PG8_STAGE(PG8_SB(1, 0), b3, voffB);
;             PG8_BAR; PG8_WAIT_L(0); PG8_MMA(0, 1, At, B1); PG8_BAR;
;             PG8_LDA(At, 1, 1); PG8_STAGE(PG8_SA(1, 0), a3, voffA);
;             PG8_BAR; PG8_WAIT_L(0); PG8_MMA(1, 0, At, B0); PG8_BAR; PG8_SCHED;
;             PG8_STAGE(PG8_SB(1, 1), b3 + hstep, voffB);
;             PG8_WAIT_V(6); PG8_BAR; PG8_MMA(1, 1, At, B1); PG8_BAR;
	s_waitcnt lgkmcnt(0)
	s_setprio 1
	s_waitcnt lgkmcnt(0)
	v_mfma_f32_16x16x32_bf16 v[118:121], v[216:219], v[168:171], v[118:121]
	v_mfma_f32_16x16x32_bf16 v[110:113], v[230:233], v[168:171], v[110:113]
	v_mfma_f32_16x16x32_bf16 v[102:105], v[216:219], v[176:179], v[102:105]
	v_mfma_f32_16x16x32_bf16 v[94:97], v[230:233], v[176:179], v[94:97]
	v_mfma_f32_16x16x32_bf16 v[86:89], v[216:219], v[184:187], v[86:89]
	v_mfma_f32_16x16x32_bf16 v[78:81], v[230:233], v[184:187], v[78:81]
	v_mfma_f32_16x16x32_bf16 v[70:73], v[216:219], v[208:211], v[70:73]
	v_mfma_f32_16x16x32_bf16 v[66:69], v[230:233], v[208:211], v[66:69]
	v_mfma_f32_16x16x32_bf16 v[118:121], v[226:229], v[172:175], v[118:121]
	v_mfma_f32_16x16x32_bf16 v[110:113], v[234:237], v[172:175], v[110:113]
	v_mfma_f32_16x16x32_bf16 v[102:105], v[226:229], v[180:183], v[102:105]
	v_mfma_f32_16x16x32_bf16 v[94:97], v[234:237], v[180:183], v[94:97]
	v_mfma_f32_16x16x32_bf16 v[86:89], v[226:229], v[204:207], v[86:89]
	v_mfma_f32_16x16x32_bf16 v[78:81], v[234:237], v[204:207], v[78:81]
	v_mfma_f32_16x16x32_bf16 v[70:73], v[226:229], v[212:215], v[70:73]
	v_mfma_f32_16x16x32_bf16 v[66:69], v[234:237], v[212:215], v[66:69]
	s_setprio 0
	s_mov_b32 m0, s47
	s_add_u32 vcc_lo, s36, 0x80
	s_addc_u32 vcc_hi, s37, 0
	s_barrier
	ds_read_b128 v[168:171], v152 offset:16384
	ds_read_b128 v[172:175], v152 offset:17408
	ds_read_b128 v[176:179], v152 offset:18432
	ds_read_b128 v[180:183], v152 offset:19456
	ds_read_b128 v[184:187], v152 offset:20480
	ds_read_b128 v[204:207], v152 offset:21504
	ds_read_b128 v[208:211], v152 offset:22528
	ds_read_b128 v[212:215], v152 offset:23552
	global_load_lds_dwordx4 v134, s[36:37]
	s_mov_b32 m0, s48
	s_nop 0
	global_load_lds_dwordx4 v132, s[36:37]
	s_barrier
	s_waitcnt lgkmcnt(0)
	s_setprio 1
	s_waitcnt lgkmcnt(0)
	v_mfma_f32_16x16x32_bf16 v[62:65], v[140:143], v[168:171], v[62:65]
	v_mfma_f32_16x16x32_bf16 v[58:61], v[154:157], v[168:171], v[58:61]
	v_mfma_f32_16x16x32_bf16 v[50:53], v[140:143], v[176:179], v[50:53]
	v_mfma_f32_16x16x32_bf16 v[42:45], v[154:157], v[176:179], v[42:45]
	v_mfma_f32_16x16x32_bf16 v[34:37], v[140:143], v[184:187], v[34:37]
	v_mfma_f32_16x16x32_bf16 v[26:29], v[154:157], v[184:187], v[26:29]
	v_mfma_f32_16x16x32_bf16 v[18:21], v[140:143], v[208:211], v[18:21]
	v_mfma_f32_16x16x32_bf16 v[10:13], v[154:157], v[208:211], v[10:13]
	v_mfma_f32_16x16x32_bf16 v[62:65], v[144:147], v[172:175], v[62:65]
	v_mfma_f32_16x16x32_bf16 v[58:61], v[158:161], v[172:175], v[58:61]
	v_mfma_f32_16x16x32_bf16 v[50:53], v[144:147], v[180:183], v[50:53]
	v_mfma_f32_16x16x32_bf16 v[42:45], v[158:161], v[180:183], v[42:45]
	v_mfma_f32_16x16x32_bf16 v[34:37], v[144:147], v[204:207], v[34:37]
	v_mfma_f32_16x16x32_bf16 v[26:29], v[158:161], v[204:207], v[26:29]
	v_mfma_f32_16x16x32_bf16 v[18:21], v[144:147], v[212:215], v[18:21]
	v_mfma_f32_16x16x32_bf16 v[10:13], v[158:161], v[212:215], v[10:13]
	s_setprio 0
	s_barrier
	s_add_u32 s60, s6, 0x40000
	s_addc_u32 s61, s7, 0
	s_add_i32 s58, s70, s44
	s_mov_b32 m0, s58
	s_nop 0
	global_load_lds_dwordx4 v0, s[60:61]
	s_add_i32 m0, s58, 0x2000
	s_nop 0
	global_load_lds_dwordx4 v130, s[60:61]
	s_waitcnt vmcnt(6)
	s_barrier
	s_setprio 1
	v_mfma_f32_16x16x32_bf16 v[54:57], v[216:219], v[168:171], v[54:57]
	v_mfma_f32_16x16x32_bf16 v[46:49], v[230:233], v[168:171], v[46:49]
	s_cmp_eq_u32 s87, 0
	s_cbranch_scc1 .LdsA_skip_7
	global_store_dwordx4 v166, v[248:251], s[4:5] offset:256
.LdsA_skip_7:
	v_mfma_f32_16x16x32_bf16 v[38:41], v[216:219], v[176:179], v[38:41]
	v_mfma_f32_16x16x32_bf16 v[30:33], v[230:233], v[176:179], v[30:33]
	v_mfma_f32_16x16x32_bf16 v[22:25], v[216:219], v[184:187], v[22:25]
	v_mfma_f32_16x16x32_bf16 v[14:17], v[230:233], v[184:187], v[14:17]
	v_mfma_f32_16x16x32_bf16 v[6:9], v[216:219], v[208:211], v[6:9]
	v_mfma_f32_16x16x32_bf16 v[2:5], v[230:233], v[208:211], v[2:5]
	v_mfma_f32_16x16x32_bf16 v[54:57], v[226:229], v[172:175], v[54:57]
	v_mfma_f32_16x16x32_bf16 v[46:49], v[234:237], v[172:175], v[46:49]
	v_mfma_f32_16x16x32_bf16 v[38:41], v[226:229], v[180:183], v[38:41]
	v_mfma_f32_16x16x32_bf16 v[30:33], v[234:237], v[180:183], v[30:33]
	v_mfma_f32_16x16x32_bf16 v[22:25], v[226:229], v[204:207], v[22:25]
	v_mfma_f32_16x16x32_bf16 v[14:17], v[234:237], v[204:207], v[14:17]
	v_mfma_f32_16x16x32_bf16 v[6:9], v[226:229], v[212:215], v[6:9]
	v_mfma_f32_16x16x32_bf16 v[2:5], v[234:237], v[212:215], v[2:5]
	s_setprio 0
	s_add_i32 s58, 0, 0x18000
	v_add_u32_e32 v153, s58, v149
	s_barrier
	ds_read_b128 v[140:143], v153
	ds_read_b128 v[144:147], v153 offset:1024
	ds_read_b128 v[154:157], v153 offset:2048
	ds_read_b128 v[158:161], v153 offset:3072
	s_add_u32 s36, s36, 0x40000
	s_addc_u32 s37, s37, 0
	s_mov_b32 m0, s49
	ds_read_b128 v[168:171], v152 offset:32768
	ds_read_b128 v[172:175], v152 offset:33792
	ds_read_b128 v[176:179], v152 offset:34816
	ds_read_b128 v[180:183], v152 offset:35840
	ds_read_b128 v[184:187], v152 offset:36864
	ds_read_b128 v[204:207], v152 offset:37888
	ds_read_b128 v[208:211], v152 offset:38912
	ds_read_b128 v[212:215], v152 offset:39936
	global_load_lds_dwordx4 v134, s[36:37]
	s_mov_b32 m0, s54
	s_nop 0
	global_load_lds_dwordx4 v132, s[36:37]
	s_waitcnt lgkmcnt(8)
	s_barrier
; #define PG8_STAGE(bufoff, gbase, voff) do { _Pragma("unroll") for (int _i = 0; _i < 2; ++_i) \
;         __builtin_amdgcn_global_load_lds((const unsigned*)((const char*)(gbase) + (voff)[_i]), (LAS unsigned*)(lds + (bufoff) + ldsw + _i * 8192), 16, 0, 0); } while (0)
; #define PG8_LDA(dst, b, h) do { _Pragma("unroll") for (int m = 0; m < 4; ++m) _Pragma("unroll") for (int k = 0; k < 2; ++k) dst[m][k] = *(const LAS bf16x8*)(lds + PG8_SA(b, h) + aoff + m * 2048 + k * 1024); } while (0)
; #define PG8_LDB(dst, b, h) do { _Pragma("unroll") for (int n = 0; n < 2; ++n) _Pragma("unroll") for (int k = 0; k < 2; ++k) dst[n][k] = *(const LAS bf16x8*)(lds + PG8_SB(b, h) + boff + n * 2048 + k * 1024); } while (0)
; #define PG8_WAIT_V(n) asm volatile("s_waitcnt vmcnt(" #n ")" ::: "memory")
; #define PG8_WAIT_L(n) asm volatile("s_waitcnt lgkmcnt(" #n ")" ::: "memory")
; #define PG8_BAR __builtin_amdgcn_s_barrier()
; #define PG8_SCHED __builtin_amdgcn_sched_barrier(0)
; template <class Epi>
; __device__ __forceinline__ void gemm_phase(LAS unsigned char* lds, const Gemm g, const StaticOrder& S, const Epi& E) {
;     ...
;             PG8_LDB(B0, 0, 0); PG8_SCHED; PG8_LDA(At, 0, 0); PG8_STAGE(PG8_SA(1, 1), a1 + hstep, voffA);
;             PG8_WAIT_L(8); PG8_BAR; PG8_WAIT_L(0); PG8_MMA(0, 0, At, B0); PG8_BAR; PG8_SCHED;
;             PG8_LDB(B1, 0, 1); PG8_STAGE(PG8_SB(0, 0), b2, voffB);
;             PG8_BAR; PG8_WAIT_L(0); PG8_MMA(0, 1, At, B1); PG8_BAR;
;             PG8_LDA(At, 0, 1); PG8_STAGE(PG8_SA(0, 0), a2, voffA);
;             PG8_BAR; PG8_WAIT_L(0); PG8_MMA(1, 0, At, B0); PG8_BAR; PG8_SCHED;
;             PG8_STAGE(PG8_SB(0, 1), b2 + hstep, voffB);
;             PG8_WAIT_V(6); PG8_BAR; PG8_MMA(1, 1, At, B1); PG8_BAR;
;             PG8_LDB(B0, 1, 0); PG8_SCHED; PG8_LDA(At, 1, 0); PG8_STAGE(PG8_SA(0, 1), a2 + hstep, voffA);
;             PG8_WAIT_L(8); PG8_BAR; PG8_WAIT_L(0); PG8_MMA(0, 0, At, B0); PG8_BAR; PG8_SCHED;
;             PG8_LDB(B1, 1, 1); PG8_STAGE(PG8_SB(1, 0), b3, voffB);
;             PG8_BAR; PG8_WAIT_L(0); PG8_MMA(0, 1, At, B1); PG8_BAR;
;             PG8_LDA(At, 1, 1); PG8_STAGE(PG8_SA(1, 0), a3, voffA);
;             PG8_BAR; PG8_WAIT_L(0); PG8_MMA(1, 0, At, B0); PG8_BAR; PG8_SCHED;
;             PG8_STAGE(PG8_SB(1, 1), b3 + hstep, voffB);
;             PG8_WAIT_V(6); PG8_BAR; PG8_MMA(1, 1, At, B1); PG8_BAR;
	s_waitcnt lgkmcnt(0)
	s_setprio 1
	s_waitcnt lgkmcnt(0)
	v_mfma_f32_16x16x32_bf16 v[126:129], v[140:143], v[168:171], v[126:129]
	v_mfma_f32_16x16x32_bf16 v[122:125], v[154:157], v[168:171], v[122:125]
	v_mfma_f32_16x16x32_bf16 v[114:117], v[140:143], v[176:179], v[114:117]
	v_mfma_f32_16x16x32_bf16 v[106:109], v[154:157], v[176:179], v[106:109]
	v_mfma_f32_16x16x32_bf16 v[98:101], v[140:143], v[184:187], v[98:101]
	v_mfma_f32_16x16x32_bf16 v[90:93], v[154:157], v[184:187], v[90:93]
	v_mfma_f32_16x16x32_bf16 v[82:85], v[140:143], v[208:211], v[82:85]
	v_mfma_f32_16x16x32_bf16 v[74:77], v[154:157], v[208:211], v[74:77]
	v_mfma_f32_16x16x32_bf16 v[126:129], v[144:147], v[172:175], v[126:129]
	v_mfma_f32_16x16x32_bf16 v[122:125], v[158:161], v[172:175], v[122:125]
	v_mfma_f32_16x16x32_bf16 v[114:117], v[144:147], v[180:183], v[114:117]
	v_mfma_f32_16x16x32_bf16 v[106:109], v[158:161], v[180:183], v[106:109]
	v_mfma_f32_16x16x32_bf16 v[98:101], v[144:147], v[204:207], v[98:101]
	v_mfma_f32_16x16x32_bf16 v[90:93], v[158:161], v[204:207], v[90:93]
	v_mfma_f32_16x16x32_bf16 v[82:85], v[144:147], v[212:215], v[82:85]
	v_mfma_f32_16x16x32_bf16 v[74:77], v[158:161], v[212:215], v[74:77]
	s_setprio 0
	s_barrier
	s_add_i32 s36, 0, 0x1c000
	s_add_i32 s37, s58, s44
	v_add_u32_e32 v153, s36, v149
	s_add_u32 s60, s6, 0x80
	s_addc_u32 s61, s7, 0
	s_mov_b32 m0, s37
	ds_read_b128 v[216:219], v153
	ds_read_b128 v[226:229], v153 offset:1024
	ds_read_b128 v[230:233], v153 offset:2048
	ds_read_b128 v[234:237], v153 offset:3072
	global_load_lds_dwordx4 v0, s[60:61]
	s_add_i32 m0, s37, 0x2000
	s_nop 0
	global_load_lds_dwordx4 v130, s[60:61]
	s_barrier
	s_waitcnt lgkmcnt(0)
	s_setprio 1
	s_waitcnt lgkmcnt(0)
	v_mfma_f32_16x16x32_bf16 v[118:121], v[216:219], v[168:171], v[118:121]
	v_mfma_f32_16x16x32_bf16 v[110:113], v[230:233], v[168:171], v[110:113]
	v_mfma_f32_16x16x32_bf16 v[102:105], v[216:219], v[176:179], v[102:105]
	v_mfma_f32_16x16x32_bf16 v[94:97], v[230:233], v[176:179], v[94:97]
	v_mfma_f32_16x16x32_bf16 v[86:89], v[216:219], v[184:187], v[86:89]
	v_mfma_f32_16x16x32_bf16 v[78:81], v[230:233], v[184:187], v[78:81]
	v_mfma_f32_16x16x32_bf16 v[70:73], v[216:219], v[208:211], v[70:73]
	v_mfma_f32_16x16x32_bf16 v[66:69], v[230:233], v[208:211], v[66:69]
	v_mfma_f32_16x16x32_bf16 v[118:121], v[226:229], v[172:175], v[118:121]
	v_mfma_f32_16x16x32_bf16 v[110:113], v[234:237], v[172:175], v[110:113]
	v_mfma_f32_16x16x32_bf16 v[102:105], v[226:229], v[180:183], v[102:105]
	v_mfma_f32_16x16x32_bf16 v[94:97], v[234:237], v[180:183], v[94:97]
	v_mfma_f32_16x16x32_bf16 v[86:89], v[226:229], v[204:207], v[86:89]
	v_mfma_f32_16x16x32_bf16 v[78:81], v[234:237], v[204:207], v[78:81]
	v_mfma_f32_16x16x32_bf16 v[70:73], v[226:229], v[212:215], v[70:73]
	v_mfma_f32_16x16x32_bf16 v[66:69], v[234:237], v[212:215], v[66:69]
	s_setprio 0
	s_mov_b32 m0, s55
	s_barrier
	ds_read_b128 v[168:171], v152 offset:49152
	ds_read_b128 v[172:175], v152 offset:50176
	ds_read_b128 v[176:179], v152 offset:51200
	ds_read_b128 v[180:183], v152 offset:52224
	ds_read_b128 v[184:187], v152 offset:53248
	ds_read_b128 v[204:207], v152 offset:54272
	ds_read_b128 v[208:211], v152 offset:55296
	ds_read_b128 v[212:215], v152 offset:56320
	global_load_lds_dwordx4 v134, vcc
	s_mov_b32 m0, s83
	s_nop 0
	global_load_lds_dwordx4 v132, vcc
	s_barrier
	s_waitcnt lgkmcnt(0)
	s_setprio 1
	s_waitcnt lgkmcnt(0)
	v_mfma_f32_16x16x32_bf16 v[62:65], v[140:143], v[168:171], v[62:65]
	v_mfma_f32_16x16x32_bf16 v[58:61], v[154:157], v[168:171], v[58:61]
	v_mfma_f32_16x16x32_bf16 v[50:53], v[140:143], v[176:179], v[50:53]
	v_mfma_f32_16x16x32_bf16 v[42:45], v[154:157], v[176:179], v[42:45]
	v_mfma_f32_16x16x32_bf16 v[34:37], v[140:143], v[184:187], v[34:37]
	v_mfma_f32_16x16x32_bf16 v[26:29], v[154:157], v[184:187], v[26:29]
	v_mfma_f32_16x16x32_bf16 v[18:21], v[140:143], v[208:211], v[18:21]
	v_mfma_f32_16x16x32_bf16 v[10:13], v[154:157], v[208:211], v[10:13]
	v_mfma_f32_16x16x32_bf16 v[62:65], v[144:147], v[172:175], v[62:65]
	v_mfma_f32_16x16x32_bf16 v[58:61], v[158:161], v[172:175], v[58:61]
	v_mfma_f32_16x16x32_bf16 v[50:53], v[144:147], v[180:183], v[50:53]
	v_mfma_f32_16x16x32_bf16 v[42:45], v[158:161], v[180:183], v[42:45]
	v_mfma_f32_16x16x32_bf16 v[34:37], v[144:147], v[204:207], v[34:37]
	v_mfma_f32_16x16x32_bf16 v[26:29], v[158:161], v[204:207], v[26:29]
	v_mfma_f32_16x16x32_bf16 v[18:21], v[144:147], v[212:215], v[18:21]
	v_mfma_f32_16x16x32_bf16 v[10:13], v[158:161], v[212:215], v[10:13]
	s_setprio 0
	s_barrier
	s_add_u32 s6, s6, 0x40080
	s_addc_u32 s7, s7, 0
	s_add_i32 s36, s36, s44
	s_mov_b32 m0, s36
	s_nop 0
	global_load_lds_dwordx4 v0, s[6:7]
	s_add_i32 m0, s36, 0x2000
	s_nop 0
	global_load_lds_dwordx4 v130, s[6:7]
	s_waitcnt vmcnt(6)
	s_barrier
	s_setprio 1
	v_mfma_f32_16x16x32_bf16 v[54:57], v[216:219], v[168:171], v[54:57]
	v_mfma_f32_16x16x32_bf16 v[46:49], v[230:233], v[168:171], v[46:49]
	v_mfma_f32_16x16x32_bf16 v[38:41], v[216:219], v[176:179], v[38:41]
	v_mfma_f32_16x16x32_bf16 v[30:33], v[230:233], v[176:179], v[30:33]
	v_mfma_f32_16x16x32_bf16 v[22:25], v[216:219], v[184:187], v[22:25]
	v_mfma_f32_16x16x32_bf16 v[14:17], v[230:233], v[184:187], v[14:17]
	v_mfma_f32_16x16x32_bf16 v[6:9], v[216:219], v[208:211], v[6:9]
	v_mfma_f32_16x16x32_bf16 v[2:5], v[230:233], v[208:211], v[2:5]
	v_mfma_f32_16x16x32_bf16 v[54:57], v[226:229], v[172:175], v[54:57]
	v_mfma_f32_16x16x32_bf16 v[46:49], v[234:237], v[172:175], v[46:49]
	v_mfma_f32_16x16x32_bf16 v[38:41], v[226:229], v[180:183], v[38:41]
	v_mfma_f32_16x16x32_bf16 v[30:33], v[234:237], v[180:183], v[30:33]
	v_mfma_f32_16x16x32_bf16 v[22:25], v[226:229], v[204:207], v[22:25]
	v_mfma_f32_16x16x32_bf16 v[14:17], v[234:237], v[204:207], v[14:17]
	v_mfma_f32_16x16x32_bf16 v[6:9], v[226:229], v[212:215], v[6:9]
	v_mfma_f32_16x16x32_bf16 v[2:5], v[234:237], v[212:215], v[2:5]
	s_setprio 0
	s_add_i32 s91, s91, 2
	s_add_u32 s24, s24, 0x100
	s_addc_u32 s25, s25, 0
	s_add_u32 s89, s89, 0x100
	s_addc_u32 s90, s90, 0
	s_cmp_gt_u32 s91, 13
	s_barrier
; __device__ __forceinline__ unsigned pk2(float lo, float hi) { unsigned r; asm("v_cvt_pk_bf16_f32 %0, %1, %2" : "=v"(r) : "v"(lo), "v"(hi)); return r; }
;     __device__ __forceinline__ void operator()(const f32x4 (&acc)[2][2][4][2], const Unit& u, int ui, int wr, int wc, int fr, int fq) const {
;         const int lrow0 = wr * 64 + fr, row0 = u.pm * BM + lrow0, col0 = u.pn * BM + wc * 32 + 8 * fq;
;         float rsv[2][4];
; #pragma unroll
;         for (int ai = 0; ai < 2; ++ai)
; #pragma unroll
;             for (int m = 0; m < 4; ++m) rsv[ai][m] = rstab[ui * 256 + lrow0 + ai * HALF + m * 16];
; #pragma unroll
;         for (int ai = 0; ai < 2; ++ai)
; #pragma unroll
;             for (int m = 0; m < 4; ++m) {
;                 const int row = row0 + ai * HALF + m * 16; const float rs = rsv[ai][m];
;                 bf16_t* rowp = O + (size_t)row * ldc + col0;
; #pragma unroll
;                 for (int bj = 0; bj < 2; ++bj) {
;                     f32x4 v0 = acc[ai][bj][m][0] * rs, v1 = acc[ai][bj][m][1] * rs;
;                     if (ACT == 1) {
; #pragma unroll
;                         for (int j = 0; j < 4; ++j) { const float a = fmaxf(v0[j], 0.f), b = fmaxf(v1[j], 0.f); v0[j] = a * a; v1[j] = b * b; }
;                     }
;                     u32x4 w; w.x = pk2(v0[0], v0[1]); w.y = pk2(v0[2], v0[3]); w.z = pk2(v1[0], v1[1]); w.w = pk2(v1[2], v1[3]);
;                     *(u32x4*)(rowp + bj * HALF) = w;
;                 }
; template <class Epi>
; __device__ __forceinline__ void gemm_phase(LAS unsigned char* lds, const Gemm g, const StaticOrder& S, const Epi& E) {
;     ...
;         cur = nxt; cA = nA; cB = nB; ++ui;
	v_lshl_add_u32 v140, s87, 10, v150
	v_lshl_or_b32 v144, s85, 8, v151
	v_lshl_add_u32 v153, s86, 8, v148
	v_mul_u32_u24_e32 v166, 0xe00, v153
	v_lshl_add_u32 v166, v144, 1, v166
	v_add_u32_e32 v166, 0x70000, v166
	ds_read2_b32 v[154:155], v140 offset1:16
	ds_read2_b32 v[156:157], v140 offset0:32 offset1:48
	ds_read2_b32 v[146:147], v140 offset0:128 offset1:144
	ds_read2_b32 v[140:141], v140 offset0:160 offset1:176
	v_ashrrev_i32_e32 v145, 31, v144
	v_mov_b64_e32 v[142:143], s[4:5]
	v_mad_i64_i32 v[158:159], s[6:7], v153, s65, v[142:143]
	v_lshlrev_b64 v[144:145], 1, v[144:145]
	v_lshl_add_u64 v[158:159], v[158:159], 0, v[144:145]
	s_waitcnt lgkmcnt(0)
	v_pk_mul_f32 v[128:129], v[128:129], v[154:155] op_sel_hi:[1,0]
	v_pk_mul_f32 v[126:127], v[126:127], v[154:155] op_sel_hi:[1,0]
	v_pk_mul_f32 v[160:161], v[124:125], v[154:155] op_sel_hi:[1,0]
	v_pk_mul_f32 v[124:125], v[122:123], v[154:155] op_sel_hi:[1,0]
	v_cvt_pk_bf16_f32 v122, v126, v127
	v_cvt_pk_bf16_f32 v123, v128, v129
	v_pk_mul_f32 v[118:119], v[118:119], v[154:155] op_sel_hi:[1,0]
	v_cvt_pk_bf16_f32 v124, v124, v125
	v_cvt_pk_bf16_f32 v125, v160, v161
	global_store_dwordx4 v[158:159], v[122:125], off
	v_pk_mul_f32 v[120:121], v[120:121], v[154:155] op_sel_hi:[1,0]
	v_pk_mul_f32 v[98:99], v[98:99], v[156:157] op_sel_hi:[1,0]
	v_pk_mul_f32 v[122:123], v[112:113], v[154:155] op_sel_hi:[1,0]
	v_pk_mul_f32 v[112:113], v[110:111], v[154:155] op_sel_hi:[1,0]
	v_cvt_pk_bf16_f32 v110, v118, v119
	v_cvt_pk_bf16_f32 v111, v120, v121
	v_pk_mul_f32 v[86:87], v[86:87], v[156:157] op_sel_hi:[1,0]
	v_cvt_pk_bf16_f32 v112, v112, v113
	v_cvt_pk_bf16_f32 v113, v122, v123
	global_store_dwordx4 v[158:159], v[110:113], off offset:256
	v_pk_mul_f32 v[88:89], v[88:89], v[156:157] op_sel_hi:[1,0]
	v_pk_mul_f32 v[64:65], v[64:65], v[146:147] op_sel_hi:[1,0]
	v_or_b32_e32 v110, 16, v153
	v_mad_i64_i32 v[110:111], s[6:7], v110, s65, v[142:143]
	v_mov_b32_e32 v112, v155
	v_lshl_add_u64 v[110:111], v[110:111], 0, v[144:145]
	v_pk_mul_f32 v[116:117], v[116:117], v[112:113] op_sel_hi:[1,0]
	v_pk_mul_f32 v[114:115], v[114:115], v[112:113] op_sel_hi:[1,0]
	v_pk_mul_f32 v[118:119], v[108:109], v[112:113] op_sel_hi:[1,0]
	v_pk_mul_f32 v[108:109], v[106:107], v[112:113] op_sel_hi:[1,0]
	v_cvt_pk_bf16_f32 v106, v114, v115
	v_cvt_pk_bf16_f32 v107, v116, v117
	v_pk_mul_f32 v[102:103], v[102:103], v[112:113] op_sel_hi:[1,0]
	v_cvt_pk_bf16_f32 v108, v108, v109
	v_cvt_pk_bf16_f32 v109, v118, v119
	global_store_dwordx4 v[110:111], v[106:109], off
	v_pk_mul_f32 v[104:105], v[104:105], v[112:113] op_sel_hi:[1,0]
	v_pk_mul_f32 v[62:63], v[62:63], v[146:147] op_sel_hi:[1,0]
	v_pk_mul_f32 v[106:107], v[96:97], v[112:113] op_sel_hi:[1,0]
	v_pk_mul_f32 v[96:97], v[94:95], v[112:113] op_sel_hi:[1,0]
	v_cvt_pk_bf16_f32 v94, v102, v103
	v_cvt_pk_bf16_f32 v95, v104, v105
	v_pk_mul_f32 v[54:55], v[54:55], v[146:147] op_sel_hi:[1,0]
	v_cvt_pk_bf16_f32 v96, v96, v97
	v_cvt_pk_bf16_f32 v97, v106, v107
	global_store_dwordx4 v[110:111], v[94:97], off offset:256
	v_pk_mul_f32 v[56:57], v[56:57], v[146:147] op_sel_hi:[1,0]
	v_pk_mul_f32 v[34:35], v[34:35], v[140:141] op_sel_hi:[1,0]
	v_or_b32_e32 v94, 32, v153
	v_mad_i64_i32 v[94:95], s[6:7], v94, s65, v[142:143]
	v_lshl_add_u64 v[94:95], v[94:95], 0, v[144:145]
	v_pk_mul_f32 v[96:97], v[100:101], v[156:157] op_sel_hi:[1,0]
	v_pk_mul_f32 v[100:101], v[92:93], v[156:157] op_sel_hi:[1,0]
	v_pk_mul_f32 v[92:93], v[90:91], v[156:157] op_sel_hi:[1,0]
	v_cvt_pk_bf16_f32 v90, v98, v99
	v_cvt_pk_bf16_f32 v91, v96, v97
	v_pk_mul_f32 v[22:23], v[22:23], v[140:141] op_sel_hi:[1,0]
	v_cvt_pk_bf16_f32 v92, v92, v93
	v_cvt_pk_bf16_f32 v93, v100, v101
	global_store_dwordx4 v[94:95], v[90:93], off
	v_pk_mul_f32 v[24:25], v[24:25], v[140:141] op_sel_hi:[1,0]
	s_and_b64 vcc, exec, s[40:41]
	v_pk_mul_f32 v[90:91], v[80:81], v[156:157] op_sel_hi:[1,0]
	v_pk_mul_f32 v[80:81], v[78:79], v[156:157] op_sel_hi:[1,0]
	v_cvt_pk_bf16_f32 v78, v86, v87
	v_cvt_pk_bf16_f32 v79, v88, v89
	s_mov_b32 s85, s8
	v_cvt_pk_bf16_f32 v80, v80, v81
	v_cvt_pk_bf16_f32 v81, v90, v91
	global_store_dwordx4 v[94:95], v[78:81], off offset:256
	s_mov_b32 s86, s10
	s_mov_b64 s[24:25], s[12:13]
	v_or_b32_e32 v78, 48, v153
	v_mad_i64_i32 v[78:79], s[6:7], v78, s65, v[142:143]
	v_mov_b32_e32 v80, v157
	v_lshl_add_u64 v[78:79], v[78:79], 0, v[144:145]
	v_pk_mul_f32 v[84:85], v[84:85], v[80:81] op_sel_hi:[1,0]
	v_pk_mul_f32 v[82:83], v[82:83], v[80:81] op_sel_hi:[1,0]
	v_pk_mul_f32 v[86:87], v[76:77], v[80:81] op_sel_hi:[1,0]
	v_pk_mul_f32 v[76:77], v[74:75], v[80:81] op_sel_hi:[1,0]
	v_cvt_pk_bf16_f32 v74, v82, v83
	v_cvt_pk_bf16_f32 v75, v84, v85
	v_pk_mul_f32 v[70:71], v[70:71], v[80:81] op_sel_hi:[1,0]
	v_cvt_pk_bf16_f32 v76, v76, v77
	v_cvt_pk_bf16_f32 v77, v86, v87
	global_store_dwordx4 v[78:79], v[74:77], off
	v_pk_mul_f32 v[72:73], v[72:73], v[80:81] op_sel_hi:[1,0]
	s_mov_b32 s87, s84
	v_pk_mul_f32 v[74:75], v[68:69], v[80:81] op_sel_hi:[1,0]
	v_pk_mul_f32 v[68:69], v[66:67], v[80:81] op_sel_hi:[1,0]
	v_cvt_pk_bf16_f32 v66, v70, v71
	v_cvt_pk_bf16_f32 v67, v72, v73
	s_nop 0
	v_cvt_pk_bf16_f32 v68, v68, v69
	v_cvt_pk_bf16_f32 v69, v74, v75
	global_store_dwordx4 v[78:79], v[66:69], off offset:256
	s_nop 1
	v_add_u32_e32 v66, 0x80, v153
	v_mad_i64_i32 v[66:67], s[6:7], v66, s65, v[142:143]
	v_lshl_add_u64 v[66:67], v[66:67], 0, v[144:145]
; __device__ __forceinline__ unsigned pk2(float lo, float hi) { unsigned r; asm("v_cvt_pk_bf16_f32 %0, %1, %2" : "=v"(r) : "v"(lo), "v"(hi)); return r; }
; #define PG8_WAIT_V(n) asm volatile("s_waitcnt vmcnt(" #n ")" ::: "memory")
; #define PG8_BAR __builtin_amdgcn_s_barrier()
;     __device__ __forceinline__ void operator()(const f32x4 (&acc)[2][2][4][2], const Unit& u, int ui, int wr, int wc, int fr, int fq) const {
;     ...
;                 const int row = row0 + ai * HALF + m * 16; const float rs = rsv[ai][m];
;                 bf16_t* rowp = O + (size_t)row * ldc + col0;
; #pragma unroll
;                 for (int bj = 0; bj < 2; ++bj) {
;                     f32x4 v0 = acc[ai][bj][m][0] * rs, v1 = acc[ai][bj][m][1] * rs;
;                     if (ACT == 1) {
; #pragma unroll
;                         for (int j = 0; j < 4; ++j) { const float a = fmaxf(v0[j], 0.f), b = fmaxf(v1[j], 0.f); v0[j] = a * a; v1[j] = b * b; }
;                     }
;                     u32x4 w; w.x = pk2(v0[0], v0[1]); w.y = pk2(v0[2], v0[3]); w.z = pk2(v1[0], v1[1]); w.w = pk2(v1[2], v1[3]);
;                     *(u32x4*)(rowp + bj * HALF) = w;
;                 }
; template <class Epi>
; __device__ __forceinline__ void gemm_phase(LAS unsigned char* lds, const Gemm g, const StaticOrder& S, const Epi& E) {
;     ...
;         if (!has_next) break;
; #pragma unroll
;         for (int a = 0; a < 2; ++a)
; #pragma unroll
;             for (int b = 0; b < 2; ++b)
; #pragma unroll
;                 for (int m = 0; m < 4; ++m)
; #pragma unroll
;                     for (int n = 0; n < 2; ++n) acc[a][b][m][n] = (f32x4){0.f, 0.f, 0.f, 0.f};
;         cur = nxt; cA = nA; cB = nB; ++ui;
;     }
;     PG8_WAIT_V(0);
;     if (wr == 0) PG8_BAR;
;     PG8_BAR;
	v_pk_mul_f32 v[68:69], v[60:61], v[146:147] op_sel_hi:[1,0]
	v_pk_mul_f32 v[60:61], v[58:59], v[146:147] op_sel_hi:[1,0]
	v_cvt_pk_bf16_f32 v58, v62, v63
	v_cvt_pk_bf16_f32 v59, v64, v65
	s_nop 0
	v_cvt_pk_bf16_f32 v60, v60, v61
	v_cvt_pk_bf16_f32 v61, v68, v69
	v_mov_b32_e32 v162, v58
	v_mov_b32_e32 v163, v59
	v_mov_b32_e32 v164, v60
	v_mov_b32_e32 v165, v61
	s_nop 1
	v_pk_mul_f32 v[58:59], v[48:49], v[146:147] op_sel_hi:[1,0]
	v_pk_mul_f32 v[48:49], v[46:47], v[146:147] op_sel_hi:[1,0]
	v_cvt_pk_bf16_f32 v46, v54, v55
	v_cvt_pk_bf16_f32 v47, v56, v57
	s_nop 0
	v_cvt_pk_bf16_f32 v48, v48, v49
	v_cvt_pk_bf16_f32 v49, v58, v59
	v_mov_b32_e32 v188, v46
	v_mov_b32_e32 v189, v47
	v_mov_b32_e32 v190, v48
	v_mov_b32_e32 v191, v49
	s_nop 1
	v_add_u32_e32 v46, 0x90, v153
	v_mad_i64_i32 v[46:47], s[6:7], v46, s65, v[142:143]
	v_mov_b32_e32 v48, v147
	v_lshl_add_u64 v[46:47], v[46:47], 0, v[144:145]
	v_pk_mul_f32 v[52:53], v[52:53], v[48:49] op_sel_hi:[1,0]
	v_pk_mul_f32 v[50:51], v[50:51], v[48:49] op_sel_hi:[1,0]
	v_pk_mul_f32 v[54:55], v[44:45], v[48:49] op_sel_hi:[1,0]
	v_pk_mul_f32 v[44:45], v[42:43], v[48:49] op_sel_hi:[1,0]
	v_cvt_pk_bf16_f32 v42, v50, v51
	v_cvt_pk_bf16_f32 v43, v52, v53
	v_pk_mul_f32 v[38:39], v[38:39], v[48:49] op_sel_hi:[1,0]
	v_cvt_pk_bf16_f32 v44, v44, v45
	v_cvt_pk_bf16_f32 v45, v54, v55
	v_mov_b32_e32 v192, v42
	v_mov_b32_e32 v193, v43
	v_mov_b32_e32 v194, v44
	v_mov_b32_e32 v195, v45
	v_pk_mul_f32 v[40:41], v[40:41], v[48:49] op_sel_hi:[1,0]
	s_nop 0
	v_pk_mul_f32 v[42:43], v[32:33], v[48:49] op_sel_hi:[1,0]
	v_pk_mul_f32 v[32:33], v[30:31], v[48:49] op_sel_hi:[1,0]
	v_cvt_pk_bf16_f32 v30, v38, v39
	v_cvt_pk_bf16_f32 v31, v40, v41
	s_nop 0
	v_cvt_pk_bf16_f32 v32, v32, v33
	v_cvt_pk_bf16_f32 v33, v42, v43
	v_mov_b32_e32 v196, v30
	v_mov_b32_e32 v197, v31
	v_mov_b32_e32 v198, v32
	v_mov_b32_e32 v199, v33
	s_nop 1
	v_add_u32_e32 v30, 0xa0, v153
	v_mad_i64_i32 v[30:31], s[6:7], v30, s65, v[142:143]
	v_lshl_add_u64 v[30:31], v[30:31], 0, v[144:145]
	v_pk_mul_f32 v[32:33], v[36:37], v[140:141] op_sel_hi:[1,0]
	v_pk_mul_f32 v[36:37], v[28:29], v[140:141] op_sel_hi:[1,0]
	v_pk_mul_f32 v[28:29], v[26:27], v[140:141] op_sel_hi:[1,0]
	v_cvt_pk_bf16_f32 v26, v34, v35
	v_cvt_pk_bf16_f32 v27, v32, v33
	s_nop 0
	v_cvt_pk_bf16_f32 v28, v28, v29
	v_cvt_pk_bf16_f32 v29, v36, v37
	v_mov_b32_e32 v200, v26
	v_mov_b32_e32 v201, v27
	v_mov_b32_e32 v202, v28
	v_mov_b32_e32 v203, v29
	s_nop 1
	v_pk_mul_f32 v[26:27], v[16:17], v[140:141] op_sel_hi:[1,0]
	v_pk_mul_f32 v[16:17], v[14:15], v[140:141] op_sel_hi:[1,0]
	v_cvt_pk_bf16_f32 v14, v22, v23
	v_cvt_pk_bf16_f32 v15, v24, v25
	s_nop 0
	v_cvt_pk_bf16_f32 v16, v16, v17
	v_cvt_pk_bf16_f32 v17, v26, v27
	v_mov_b32_e32 v222, v14
	v_mov_b32_e32 v223, v15
	v_mov_b32_e32 v224, v16
	v_mov_b32_e32 v225, v17
	s_nop 1
	v_add_u32_e32 v14, 0xb0, v153
	v_mad_i64_i32 v[14:15], s[6:7], v14, s65, v[142:143]
	v_mov_b32_e32 v16, v141
	v_lshl_add_u64 v[14:15], v[14:15], 0, v[144:145]
	v_pk_mul_f32 v[20:21], v[20:21], v[16:17] op_sel_hi:[1,0]
	v_pk_mul_f32 v[18:19], v[18:19], v[16:17] op_sel_hi:[1,0]
	v_pk_mul_f32 v[22:23], v[12:13], v[16:17] op_sel_hi:[1,0]
	v_pk_mul_f32 v[12:13], v[10:11], v[16:17] op_sel_hi:[1,0]
	v_cvt_pk_bf16_f32 v10, v18, v19
	v_cvt_pk_bf16_f32 v11, v20, v21
	s_mov_b64 s[6:7], s[22:23]
	v_cvt_pk_bf16_f32 v12, v12, v13
	v_cvt_pk_bf16_f32 v13, v22, v23
	v_mov_b32_e32 v244, v10
	v_mov_b32_e32 v245, v11
	v_mov_b32_e32 v246, v12
	v_mov_b32_e32 v247, v13
	v_pk_mul_f32 v[8:9], v[8:9], v[16:17] op_sel_hi:[1,0]
	v_pk_mul_f32 v[6:7], v[6:7], v[16:17] op_sel_hi:[1,0]
	v_pk_mul_f32 v[10:11], v[4:5], v[16:17] op_sel_hi:[1,0]
	v_pk_mul_f32 v[4:5], v[2:3], v[16:17] op_sel_hi:[1,0]
	v_cvt_pk_bf16_f32 v2, v6, v7
	v_cvt_pk_bf16_f32 v3, v8, v9
	s_nop 0
	v_cvt_pk_bf16_f32 v4, v4, v5
	v_cvt_pk_bf16_f32 v5, v10, v11
	v_mov_b32_e32 v248, v2
	v_mov_b32_e32 v249, v3
	v_mov_b32_e32 v250, v4
	v_mov_b32_e32 v251, v5
	s_cbranch_vccz .LBB0_460
	global_store_dwordx4 v166, v[162:165], s[4:5]
	global_store_dwordx4 v166, v[188:191], s[4:5] offset:256
	v_add_u32_e32 v166, 0xe000, v166
	global_store_dwordx4 v166, v[192:195], s[4:5]
	global_store_dwordx4 v166, v[196:199], s[4:5] offset:256
	v_add_u32_e32 v166, 0xe000, v166
	global_store_dwordx4 v166, v[200:203], s[4:5]
	global_store_dwordx4 v166, v[222:225], s[4:5] offset:256
	v_add_u32_e32 v166, 0xe000, v166
	global_store_dwordx4 v166, v[244:247], s[4:5]
	global_store_dwordx4 v166, v[248:251], s[4:5] offset:256
	s_nop 1
	v_mov_b64_e32 v[164:165], 0x200
	v_mbcnt_lo_u32_b32 v193, -1, 0
	v_mbcnt_hi_u32_b32 v193, -1, v193
	v_mov_b32_e32 v188, 1
	v_mov_b32_e32 v189, 0x358637bd
	v_mov_b32_e32 v190, 0x260
	v_mov_b32_e32 v191, 0x3c0881c4
	v_mov_b32_e32 v192, 0xbab64f3b
	v_mov_b32_e32 v194, 0xf149f2ca
	v_mov_b32_e32 v195, 0xc0
	v_mov_b32_e32 v196, 0x70
	v_mov_b32_e32 v197, 0x71
	v_mov_b32_e32 v198, 5
	v_mov_b32_e32 v199, 2
	v_mov_b32_e32 v200, 3
	v_not_b32_e32 v201, 63
	v_not_b32_e32 v202, 31
	v_mov_b32_e32 v203, 0x7fc00000
	v_mov_b32_e32 v222, 0
	v_mov_b32_e32 v223, 0
	v_mov_b32_e32 v224, 0
	v_mov_b32_e32 v225, 0
	s_waitcnt vmcnt(0)
	v_readlane_b32 s70, v254, 40
	v_readlane_b32 s84, v254, 42
	s_cmpk_gt_u32 s18, 0xff
	v_readlane_b32 s71, v254, 41
	v_readlane_b32 s86, v254, 44
	v_readlane_b32 s87, v254, 45
	v_readlane_b32 s85, v254, 43
	s_cbranch_scc1 .LBB0_467
	s_barrier
